# W_in log-forget epilogue: also the |log2|<inf select of the second logf (argument >= la > 0 wherever the value is used) deleted
# baseline (speedup 1.0000x reference)
; __device__ __forceinline__ float silu_f(float x) { return x * __builtin_amdgcn_rcpf(1.f + __expf(-x)); }
; __device__ __forceinline__ v4u pack8(const f32x4 a, const f32x4 b) { v4u w; w.x = cvt_pk_bf16(a[0], a[1]); w.y = cvt_pk_bf16(a[2], a[3]); w.z = cvt_pk_bf16(b[0], b[1]); w.w = cvt_pk_bf16(b[2], b[3]); return w; }
;     __device__ __forceinline__ void operator()(const f32x4 (&acc)[2][2][4][2], const pg8::Unit& u, int wr, int wc, int fr, int fq) const {
;     ...
;         if (grp == 0) { WIN_LOOP( _Pragma("unroll") for (int i = 0; i < 4; ++i) { a[i] = silu_f(a[i]); b[i] = silu_f(b[i]); } *(v4u*)(QO + (size_t)row * DM + c) = pack8(a, b); ) }
;         else if (grp == 3) { WIN_LOOP( _Pragma("unroll") for (int i = 0; i < 4; ++i) { a[i] = silu_f(a[i]); b[i] = silu_f(b[i]); } *(v4u*)(GH + (size_t)row * 512 + c) = pack8(a, b); ) }
;         else if (grp == 1) {
;             f32x4 l0[2], l1[2];
; #pragma unroll
;             for (int bj = 0; bj < 2; ++bj) { l0[bj] = *(const f32x4*)(lb + cb + bj * 128); l1[bj] = *(const f32x4*)(lb + cb + bj * 128 + 4); }
;             WIN_LOOP( _Pragma("unroll") for (int i = 0; i < 4; ++i) { const float s0 = fminf(a[i], 0.f) - __logf(1.f + __expf(-fabsf(a[i]))), s1 = fminf(b[i], 0.f) - __logf(1.f + __expf(-fabsf(b[i]))); const float la = l0[bj][i], lbv = l1[bj][i];
;                     a[i] = la > 0.f ? __logf(la + (1.f - la) * __expf(s0)) : s0; b[i] = lbv > 0.f ? __logf(lbv + (1.f - lbv) * __expf(s1)) : s1; }
;                 *(f32x4*)(LF + (size_t)row * 512 + c) = a; *(f32x4*)(LF + (size_t)row * 512 + c + 4) = b; __builtin_amdgcn_sched_barrier(0); ) }
.LBB0_414:
	s_andn2_b64 vcc, exec, s[8:9]
	s_cbranch_vccnz .LBB0_416
	v_ashrrev_i32_e32 v167, 31, v166
	v_lshlrev_b64 v[128:129], 6, v[166:167]
	v_lshl_add_u64 v[128:129], v[160:161], 0, v[128:129]
	s_nop 0
	v_readlane_b32 s8, v255, 35
	v_lshlrev_b32_e32 v192, 2, v176
	v_readlane_b32 s9, v255, 36
	v_and_b32_e32 v133, 64, v215
	v_xor_b32_e32 v132, 16, v215
	v_lshl_add_u64 v[144:145], s[8:9], 0, v[192:193]
	flat_load_dwordx4 v[140:143], v[144:145]
	flat_load_dwordx4 v[136:139], v[144:145] offset:16
	v_add_u32_e32 v134, 64, v133
	v_cmp_lt_i32_e32 vcc, v132, v134
	v_lshlrev_b64 v[146:147], 11, v[166:167]
	v_readlane_b32 s50, v255, 45
	v_cndmask_b32_e32 v132, v215, v132, vcc
	v_lshlrev_b32_e32 v169, 2, v132
	v_readlane_b32 s51, v255, 46
	s_mov_b32 s95, s28
	s_mov_b32 s91, s29
	v_lshl_add_u64 v[170:171], s[50:51], 0, v[146:147]
	v_lshl_add_u64 v[170:171], v[170:171], 0, v[192:193]
	s_waitcnt vmcnt(0) lgkmcnt(0)
	s_nop 3
	v_xor_b32_e32 v130, 32, v215
	s_nop 1
	v_cmp_lt_i32_e32 vcc, v130, v134
	v_sub_f32_e32 v190, 1.0, v140
	v_sub_f32_e32 v191, 1.0, v136
	v_cndmask_b32_e32 v130, v215, v130, vcc
	v_lshlrev_b32_e32 v202, 2, v130
	s_waitcnt lgkmcnt(0)
	s_nop 1
	flat_load_dwordx4 v[132:135], v[144:145] offset:512
	flat_load_dwordx4 v[128:131], v[144:145] offset:528
	v_sub_f32_e32 v188, 1.0, v141
	v_cmp_lt_f32_e64 s[38:39], 0, v140
	v_cmp_lt_f32_e64 s[36:37], 0, v136
	s_waitcnt lgkmcnt(0)
	s_nop 1
	v_mov_b32_e32 v168, v250
	v_sub_f32_e32 v189, 1.0, v137
	v_cmp_lt_f32_e64 s[34:35], 0, v141
	v_cmp_lt_f32_e64 s[30:31], 0, v137
	v_pk_mul_f32 v[144:145], v[60:61], v[168:169] op_sel_hi:[1,0]
	v_pk_mul_f32 v[148:149], v[56:57], v[168:169] op_sel_hi:[1,0]
	v_min_f32_e32 v167, 0, v144
	v_mul_f32_e64 v144, |v144|, s57
	v_min_f32_e32 v177, 0, v148
	v_mul_f32_e64 v148, |v148|, s57
	v_exp_f32_e32 v144, v144
	v_exp_f32_e32 v148, v148
	v_min_f32_e32 v179, 0, v149
	v_mul_f32_e64 v149, |v149|, s57
	v_add_f32_e32 v144, 1.0, v144
	v_exp_f32_e32 v149, v149
	v_add_f32_e32 v148, 1.0, v148
	v_min_f32_e32 v178, 0, v145
	v_mul_f32_e64 v145, |v145|, s57
	v_exp_f32_e32 v145, v145
	v_log_f32_e32 v144, v144
	v_add_f32_e32 v149, 1.0, v149
	v_log_f32_e32 v148, v148
	v_add_f32_e32 v145, 1.0, v145
	v_mul_f32_e32 v183, 0x3f317217, v144
	v_mul_f32_e32 v184, 0x3f317217, v148
	v_fma_f32 v183, v144, s52, -v183
	v_fma_f32 v184, v148, s52, -v184
	v_fmac_f32_e32 v183, 0x3377d1cf, v144
	v_fmac_f32_e32 v184, 0x3377d1cf, v148
	v_fmac_f32_e32 v183, 0x3f317217, v144
	v_log_f32_e32 v145, v145
	v_fmac_f32_e32 v184, 0x3f317217, v148
	v_mov_b32_e32 v144, v183
	v_log_f32_e32 v149, v149
	v_mov_b32_e32 v148, v184
	v_sub_f32_e32 v144, v167, v144
	v_sub_f32_e32 v167, v177, v148
	v_mul_f32_e32 v148, 0x3fb8aa3b, v144
	v_mul_f32_e32 v185, 0x3f317217, v145
	v_mul_f32_e32 v177, 0x3fb8aa3b, v167
	v_exp_f32_e32 v148, v148
	v_mul_f32_e32 v186, 0x3f317217, v149
	v_fma_f32 v185, v145, s52, -v185
	v_exp_f32_e32 v177, v177
	v_fma_f32 v186, v149, s52, -v186
	v_fmac_f32_e32 v185, 0x3377d1cf, v145
	v_fmac_f32_e32 v186, 0x3377d1cf, v149
	v_fmac_f32_e32 v185, 0x3f317217, v145
	v_fmac_f32_e32 v186, 0x3f317217, v149
	v_fma_f32 v148, v190, v148, v140
	v_mov_b32_e32 v145, v185
	v_fma_f32 v177, v191, v177, v136
	v_cmp_gt_f32_e64 s[10:11], s97, v177
	v_mov_b32_e32 v149, v186
	v_cmp_gt_f32_e64 s[8:9], s97, v148
	v_cndmask_b32_e64 v181, 0, 32, s[10:11]
	v_ldexp_f32 v177, v177, v181
	v_cndmask_b32_e64 v180, 0, 32, s[8:9]
	v_ldexp_f32 v148, v148, v180
	v_log_f32_e32 v148, v148
	v_log_f32_e32 v177, v177
	v_sub_f32_e32 v145, v178, v145
	v_mul_f32_e32 v178, 0x3fb8aa3b, v145
	v_mul_f32_e32 v182, 0x3f317217, v148
	v_exp_f32_e32 v178, v178
	v_mul_f32_e32 v183, 0x3f317217, v177
	v_fma_f32 v182, v148, s52, -v182
	v_fma_f32 v183, v177, s52, -v183
	v_fmac_f32_e32 v182, 0x3377d1cf, v148
	v_cndmask_b32_e64 v180, 0, v216, s[8:9]
	v_fmac_f32_e32 v183, 0x3377d1cf, v177
	v_fmac_f32_e32 v182, 0x3f317217, v148
	v_fmac_f32_e32 v183, 0x3f317217, v177
	v_fma_f32 v178, v188, v178, v141
	v_mov_b32_e32 v148, v182
	v_cndmask_b32_e64 v181, 0, v216, s[10:11]
	v_sub_f32_e32 v148, v148, v180
	v_mov_b32_e32 v177, v183
	v_sub_f32_e32 v177, v177, v181
	v_cmp_gt_f32_e64 s[8:9], s97, v178
	v_cndmask_b32_e64 v148, v144, v148, s[38:39]
	v_cndmask_b32_e64 v144, v167, v177, s[36:37]
	v_cndmask_b32_e64 v167, 0, 32, s[8:9]
	v_ldexp_f32 v167, v178, v167
	v_log_f32_e32 v167, v167
	v_sub_f32_e32 v177, v179, v149
	v_mul_f32_e32 v178, 0x3fb8aa3b, v177
	v_exp_f32_e32 v178, v178
	v_mul_f32_e32 v149, 0x3f317217, v167
	v_fma_f32 v149, v167, s52, -v149
	v_fmac_f32_e32 v149, 0x3377d1cf, v167
	v_fmac_f32_e32 v149, 0x3f317217, v167
	v_fma_f32 v178, v189, v178, v137
	v_pk_mul_f32 v[150:151], v[62:63], v[168:169] op_sel_hi:[1,0]
	v_cmp_gt_f32_e32 vcc, s97, v178
	v_cndmask_b32_e64 v167, 0, v216, s[8:9]
	v_sub_f32_e32 v149, v149, v167
	v_cndmask_b32_e64 v179, 0, 32, vcc
	v_ldexp_f32 v178, v178, v179
	v_log_f32_e32 v178, v178
	v_mul_f32_e64 v167, |v150|, s57
	v_exp_f32_e32 v167, v167
	v_cndmask_b32_e64 v149, v145, v149, s[34:35]
	v_mul_f32_e32 v145, 0x3f317217, v178
	v_fma_f32 v145, v178, s52, -v145
	v_fmac_f32_e32 v145, 0x3377d1cf, v178
	v_fmac_f32_e32 v145, 0x3f317217, v178
	v_add_f32_e32 v167, 1.0, v167
	v_pk_mul_f32 v[146:147], v[58:59], v[168:169] op_sel_hi:[1,0]
	v_cndmask_b32_e32 v178, 0, v216, vcc
	v_sub_f32_e32 v145, v145, v178
	v_cndmask_b32_e64 v145, v177, v145, s[30:31]
	v_log_f32_e32 v167, v167
	v_mul_f32_e64 v178, |v146|, s57
	v_exp_f32_e32 v178, v178
	v_min_f32_e32 v150, 0, v150
	v_mul_f32_e32 v177, 0x3f317217, v167
	v_fma_f32 v177, v167, s52, -v177
	v_fmac_f32_e32 v177, 0x3377d1cf, v167
	v_fmac_f32_e32 v177, 0x3f317217, v167
	v_add_f32_e32 v178, 1.0, v178
;     __device__ __forceinline__ void operator()(const f32x4 (&acc)[2][2][4][2], const pg8::Unit& u, int wr, int wc, int fr, int fq) const {
;     ...
;             WIN_LOOP( _Pragma("unroll") for (int i = 0; i < 4; ++i) { const float s0 = fminf(a[i], 0.f) - __logf(1.f + __expf(-fabsf(a[i]))), s1 = fminf(b[i], 0.f) - __logf(1.f + __expf(-fabsf(b[i]))); const float la = l0[bj][i], lbv = l1[bj][i];
;                     a[i] = la > 0.f ? __logf(la + (1.f - la) * __expf(s0)) : s0; b[i] = lbv > 0.f ? __logf(lbv + (1.f - lbv) * __expf(s1)) : s1; }
	v_sub_f32_e32 v187, 1.0, v142
	v_mov_b32_e32 v167, v177
	v_sub_f32_e32 v150, v150, v167
	v_log_f32_e32 v178, v178
	v_mul_f32_e32 v177, 0x3fb8aa3b, v150
	v_exp_f32_e32 v177, v177
	v_min_f32_e32 v146, 0, v146
	v_mul_f32_e32 v167, 0x3f317217, v178
	v_fma_f32 v167, v178, s52, -v167
	v_fmac_f32_e32 v167, 0x3377d1cf, v178
	v_fmac_f32_e32 v167, 0x3f317217, v178
	v_fma_f32 v177, v187, v177, v142
	v_sub_f32_e32 v186, 1.0, v138
	v_mov_b32_e32 v167, v167
	v_cmp_gt_f32_e64 s[8:9], s97, v177
	v_cmp_lt_f32_e64 s[28:29], 0, v142
	v_cmp_lt_f32_e64 s[26:27], 0, v138
	v_cndmask_b32_e64 v178, 0, 32, s[8:9]
	v_ldexp_f32 v177, v177, v178
	v_log_f32_e32 v177, v177
	v_sub_f32_e32 v146, v146, v167
	v_mul_f32_e32 v178, 0x3fb8aa3b, v146
	v_exp_f32_e32 v178, v178
	v_mul_f32_e32 v167, 0x3f317217, v177
	v_fma_f32 v167, v177, s52, -v167
	v_fmac_f32_e32 v167, 0x3377d1cf, v177
	v_fmac_f32_e32 v167, 0x3f317217, v177
	v_fma_f32 v178, v186, v178, v138
	v_sub_f32_e32 v185, 1.0, v143
	v_cmp_gt_f32_e32 vcc, s97, v178
	v_cndmask_b32_e64 v177, 0, v216, s[8:9]
	v_sub_f32_e32 v167, v167, v177
	v_cndmask_b32_e64 v179, 0, 32, vcc
	v_ldexp_f32 v178, v178, v179
	v_log_f32_e32 v178, v178
	v_mul_f32_e64 v177, |v151|, s57
	v_exp_f32_e32 v177, v177
	v_cndmask_b32_e64 v150, v150, v167, s[28:29]
	v_mul_f32_e32 v167, 0x3f317217, v178
	v_fma_f32 v167, v178, s52, -v167
	v_fmac_f32_e32 v167, 0x3377d1cf, v178
	v_fmac_f32_e32 v167, 0x3f317217, v178
	v_add_f32_e32 v177, 1.0, v177
	v_min_f32_e32 v151, 0, v151
	v_cndmask_b32_e32 v178, 0, v216, vcc
	v_sub_f32_e32 v167, v167, v178
	v_cndmask_b32_e64 v146, v146, v167, s[26:27]
	v_log_f32_e32 v177, v177
	v_mul_f32_e64 v178, |v147|, s57
	v_exp_f32_e32 v178, v178
	v_min_f32_e32 v147, 0, v147
	v_mul_f32_e32 v167, 0x3f317217, v177
	v_fma_f32 v167, v177, s52, -v167
	v_fmac_f32_e32 v167, 0x3377d1cf, v177
	v_fmac_f32_e32 v167, 0x3f317217, v177
	v_add_f32_e32 v178, 1.0, v178
	v_sub_f32_e32 v184, 1.0, v139
	v_mov_b32_e32 v167, v167
	v_sub_f32_e32 v151, v151, v167
	v_log_f32_e32 v178, v178
	v_mul_f32_e32 v177, 0x3fb8aa3b, v151
	v_exp_f32_e32 v177, v177
	v_cmp_lt_f32_e64 s[24:25], 0, v143
	v_mul_f32_e32 v167, 0x3f317217, v178
	v_fma_f32 v167, v178, s52, -v167
	v_fmac_f32_e32 v167, 0x3377d1cf, v178
	v_fmac_f32_e32 v167, 0x3f317217, v178
	v_fma_f32 v177, v185, v177, v143
	v_cmp_lt_f32_e64 s[22:23], 0, v139
	v_mov_b32_e32 v167, v167
	v_cmp_gt_f32_e64 s[8:9], s97, v177
	s_nop 1
	v_cndmask_b32_e64 v178, 0, 32, s[8:9]
	v_ldexp_f32 v177, v177, v178
	v_log_f32_e32 v177, v177
	v_sub_f32_e32 v147, v147, v167
	v_mul_f32_e32 v178, 0x3fb8aa3b, v147
	v_exp_f32_e32 v178, v178
	v_mul_f32_e32 v167, 0x3f317217, v177
	v_fma_f32 v167, v177, s52, -v167
	v_fmac_f32_e32 v167, 0x3377d1cf, v177
	v_fmac_f32_e32 v167, 0x3f317217, v177
	v_fma_f32 v178, v184, v178, v139
	s_nop 0
	v_cmp_gt_f32_e32 vcc, s97, v178
	v_cndmask_b32_e64 v177, 0, v216, s[8:9]
	v_sub_f32_e32 v167, v167, v177
	v_cndmask_b32_e64 v179, 0, 32, vcc
	v_ldexp_f32 v178, v178, v179
	v_log_f32_e32 v178, v178
	v_cndmask_b32_e64 v151, v151, v167, s[24:25]
	v_cndmask_b32_e32 v177, 0, v216, vcc
	v_mul_f32_e32 v167, 0x3f317217, v178
	v_fma_f32 v167, v178, s52, -v167
	v_fmac_f32_e32 v167, 0x3377d1cf, v178
	v_fmac_f32_e32 v167, 0x3f317217, v178
	v_sub_f32_e32 v167, v167, v177
	v_cndmask_b32_e64 v147, v147, v167, s[22:23]
	global_store_dwordx4 v[170:171], v[148:151], off
	global_store_dwordx4 v[170:171], v[144:147], off offset:16
	s_nop 1
	v_pk_mul_f32 v[144:145], v[124:125], v[168:169] op_sel_hi:[1,0]
	v_pk_mul_f32 v[150:151], v[126:127], v[168:169] op_sel_hi:[1,0]
	v_mul_f32_e64 v146, |v144|, s57
	v_exp_f32_e32 v148, v146
	v_pk_mul_f32 v[146:147], v[122:123], v[168:169] op_sel_hi:[1,0]
	v_min_f32_e32 v144, 0, v144
	s_waitcnt vmcnt(0)
	v_sub_f32_e32 v183, 1.0, v132
	v_add_f32_e32 v148, 1.0, v148
	v_sub_f32_e32 v182, 1.0, v128
	v_cmp_lt_f32_e64 s[20:21], 0, v132
	v_log_f32_e32 v167, v148
	v_pk_mul_f32 v[148:149], v[120:121], v[168:169] op_sel_hi:[1,0]
	v_cmp_lt_f32_e64 s[18:19], 0, v128
	v_mul_f32_e64 v168, |v148|, s57
	v_exp_f32_e32 v168, v168
	v_mul_f32_e32 v177, 0x3f317217, v167
	v_fma_f32 v177, v167, s52, -v177
	v_fmac_f32_e32 v177, 0x3377d1cf, v167
	v_fmac_f32_e32 v177, 0x3f317217, v167
	v_add_f32_e32 v168, 1.0, v168
	v_min_f32_e32 v148, 0, v148
	v_mov_b32_e32 v167, v177
	v_sub_f32_e32 v144, v144, v167
	v_log_f32_e32 v168, v168
	v_mul_f32_e32 v177, 0x3fb8aa3b, v144
	v_exp_f32_e32 v177, v177
	v_sub_f32_e32 v181, 1.0, v133
	v_mul_f32_e32 v167, 0x3f317217, v168
	v_fma_f32 v167, v168, s52, -v167
	v_fmac_f32_e32 v167, 0x3377d1cf, v168
	v_fmac_f32_e32 v167, 0x3f317217, v168
	v_sub_f32_e32 v180, 1.0, v129
	v_cmp_lt_f32_e64 s[16:17], 0, v133
	v_mov_b32_e32 v167, v167
	v_fma_f32 v168, v183, v177, v132
	v_cmp_gt_f32_e64 s[8:9], s97, v168
	v_cmp_lt_f32_e64 s[14:15], 0, v129
	v_sub_f32_e32 v179, 1.0, v134
	v_cndmask_b32_e64 v177, 0, 32, s[8:9]
	v_ldexp_f32 v168, v168, v177
	v_log_f32_e32 v168, v168
	v_sub_f32_e32 v148, v148, v167
	v_mul_f32_e32 v177, 0x3fb8aa3b, v148
	v_exp_f32_e32 v177, v177
	v_mul_f32_e32 v167, 0x3f317217, v168
	v_fma_f32 v167, v168, s52, -v167
	v_fmac_f32_e32 v167, 0x3377d1cf, v168
	v_fmac_f32_e32 v167, 0x3f317217, v168
	v_fma_f32 v177, v182, v177, v128
	v_cmp_lt_f32_e64 s[12:13], 0, v134
	v_cmp_gt_f32_e32 vcc, s97, v177
	v_cndmask_b32_e64 v168, 0, v216, s[8:9]
	v_sub_f32_e32 v167, v167, v168
	v_cndmask_b32_e64 v178, 0, 32, vcc
	v_ldexp_f32 v177, v177, v178
	v_log_f32_e32 v177, v177
	v_mul_f32_e64 v168, |v145|, s57
	v_exp_f32_e32 v168, v168
	v_cndmask_b32_e64 v144, v144, v167, s[20:21]
	v_mul_f32_e32 v167, 0x3f317217, v177
	v_fma_f32 v167, v177, s52, -v167
	v_fmac_f32_e32 v167, 0x3377d1cf, v177
	v_fmac_f32_e32 v167, 0x3f317217, v177
;     __device__ __forceinline__ void operator()(const f32x4 (&acc)[2][2][4][2], const pg8::Unit& u, int wr, int wc, int fr, int fq) const {
;     ...
;             WIN_LOOP( _Pragma("unroll") for (int i = 0; i < 4; ++i) { const float s0 = fminf(a[i], 0.f) - __logf(1.f + __expf(-fabsf(a[i]))), s1 = fminf(b[i], 0.f) - __logf(1.f + __expf(-fabsf(b[i]))); const float la = l0[bj][i], lbv = l1[bj][i];
;                     a[i] = la > 0.f ? __logf(la + (1.f - la) * __expf(s0)) : s0; b[i] = lbv > 0.f ? __logf(lbv + (1.f - lbv) * __expf(s1)) : s1; }
	v_add_f32_e32 v168, 1.0, v168
	v_min_f32_e32 v145, 0, v145
	v_cndmask_b32_e32 v177, 0, v216, vcc
	v_sub_f32_e32 v167, v167, v177
	v_cndmask_b32_e64 v148, v148, v167, s[18:19]
	v_log_f32_e32 v168, v168
	v_mul_f32_e64 v177, |v149|, s57
	v_exp_f32_e32 v177, v177
	v_min_f32_e32 v149, 0, v149
	v_mul_f32_e32 v167, 0x3f317217, v168
	v_fma_f32 v167, v168, s52, -v167
	v_fmac_f32_e32 v167, 0x3377d1cf, v168
	v_fmac_f32_e32 v167, 0x3f317217, v168
	v_add_f32_e32 v177, 1.0, v177
	v_cmp_lt_f32_e64 s[10:11], 0, v130
	v_mov_b32_e32 v167, v167
	v_sub_f32_e32 v145, v145, v167
	v_log_f32_e32 v177, v177
	v_mul_f32_e32 v168, 0x3fb8aa3b, v145
	v_exp_f32_e32 v168, v168
	s_mov_b32 s2, s40
	v_mul_f32_e32 v167, 0x3f317217, v177
	v_fma_f32 v167, v177, s52, -v167
	v_fmac_f32_e32 v167, 0x3377d1cf, v177
	v_fmac_f32_e32 v167, 0x3f317217, v177
	v_fma_f32 v168, v181, v168, v133
	s_nop 0
	v_mov_b32_e32 v167, v167
	v_cmp_gt_f32_e64 s[8:9], s97, v168
	s_nop 1
	v_cndmask_b32_e64 v177, 0, 32, s[8:9]
	v_ldexp_f32 v168, v168, v177
	v_log_f32_e32 v168, v168
	v_sub_f32_e32 v149, v149, v167
	v_mul_f32_e32 v177, 0x3fb8aa3b, v149
	v_exp_f32_e32 v177, v177
	v_mul_f32_e32 v167, 0x3f317217, v168
	v_fma_f32 v167, v168, s52, -v167
	v_fmac_f32_e32 v167, 0x3377d1cf, v168
	v_fmac_f32_e32 v167, 0x3f317217, v168
	v_fma_f32 v177, v180, v177, v129
	s_nop 0
	v_cmp_gt_f32_e32 vcc, s97, v177
	v_cndmask_b32_e64 v168, 0, v216, s[8:9]
	v_sub_f32_e32 v167, v167, v168
	v_cndmask_b32_e64 v178, 0, 32, vcc
	v_ldexp_f32 v177, v177, v178
	v_log_f32_e32 v177, v177
	v_mul_f32_e64 v168, |v150|, s57
	v_exp_f32_e32 v168, v168
	v_cndmask_b32_e64 v145, v145, v167, s[16:17]
	v_mul_f32_e32 v167, 0x3f317217, v177
	v_fma_f32 v167, v177, s52, -v167
	v_fmac_f32_e32 v167, 0x3377d1cf, v177
	v_fmac_f32_e32 v167, 0x3f317217, v177
	v_add_f32_e32 v168, 1.0, v168
	v_min_f32_e32 v150, 0, v150
	v_cndmask_b32_e32 v177, 0, v216, vcc
	v_sub_f32_e32 v167, v167, v177
	v_cndmask_b32_e64 v149, v149, v167, s[14:15]
	v_log_f32_e32 v168, v168
	v_mul_f32_e64 v177, |v146|, s57
	v_exp_f32_e32 v177, v177
	v_min_f32_e32 v146, 0, v146
	v_mul_f32_e32 v167, 0x3f317217, v168
	v_fma_f32 v167, v168, s52, -v167
	v_fmac_f32_e32 v167, 0x3377d1cf, v168
	v_fmac_f32_e32 v167, 0x3f317217, v168
	v_add_f32_e32 v177, 1.0, v177
	s_nop 0
	v_mov_b32_e32 v167, v167
	v_sub_f32_e32 v150, v150, v167
	v_log_f32_e32 v177, v177
	v_mul_f32_e32 v168, 0x3fb8aa3b, v150
	v_exp_f32_e32 v168, v168
	v_sub_f32_e32 v178, 1.0, v130
	v_mul_f32_e32 v167, 0x3f317217, v177
	v_fma_f32 v167, v177, s52, -v167
	v_fmac_f32_e32 v167, 0x3377d1cf, v177
	v_fmac_f32_e32 v167, 0x3f317217, v177
	v_fma_f32 v168, v179, v168, v134
	s_nop 0
	v_mov_b32_e32 v167, v167
	v_cmp_gt_f32_e64 s[8:9], s97, v168
	s_nop 1
	v_cndmask_b32_e64 v177, 0, 32, s[8:9]
	v_ldexp_f32 v168, v168, v177
	v_log_f32_e32 v168, v168
	v_sub_f32_e32 v167, v146, v167
	v_mul_f32_e32 v177, 0x3fb8aa3b, v167
	v_exp_f32_e32 v177, v177
	v_mul_f32_e32 v146, 0x3f317217, v168
	v_fma_f32 v146, v168, s52, -v146
	v_fmac_f32_e32 v146, 0x3377d1cf, v168
	v_fmac_f32_e32 v146, 0x3f317217, v168
	v_fma_f32 v177, v178, v177, v130
	s_nop 0
	v_cmp_gt_f32_e32 vcc, s97, v177
	v_cndmask_b32_e64 v168, 0, v216, s[8:9]
	v_sub_f32_e32 v146, v146, v168
	v_cndmask_b32_e64 v194, 0, 32, vcc
	v_ldexp_f32 v177, v177, v194
	v_log_f32_e32 v177, v177
	v_mul_f32_e64 v168, |v151|, s57
	v_exp_f32_e32 v168, v168
	v_cndmask_b32_e64 v146, v150, v146, s[12:13]
	v_mul_f32_e32 v150, 0x3f317217, v177
	v_fma_f32 v150, v177, s52, -v150
	v_fmac_f32_e32 v150, 0x3377d1cf, v177
	v_fmac_f32_e32 v150, 0x3f317217, v177
	v_add_f32_e32 v168, 1.0, v168
	v_min_f32_e32 v151, 0, v151
	v_cndmask_b32_e32 v177, 0, v216, vcc
	v_sub_f32_e32 v150, v150, v177
	v_cndmask_b32_e64 v150, v167, v150, s[10:11]
	v_log_f32_e32 v168, v168
	v_mul_f32_e64 v177, |v147|, s57
	v_exp_f32_e32 v177, v177
	v_min_f32_e32 v147, 0, v147
	v_mul_f32_e32 v167, 0x3f317217, v168
	v_fma_f32 v167, v168, s52, -v167
	v_fmac_f32_e32 v167, 0x3377d1cf, v168
	v_fmac_f32_e32 v167, 0x3f317217, v168
	v_add_f32_e32 v177, 1.0, v177
	s_nop 0
	v_mov_b32_e32 v167, v167
	v_sub_f32_e32 v151, v151, v167
	v_log_f32_e32 v177, v177
	v_mul_f32_e32 v168, 0x3fb8aa3b, v151
	v_exp_f32_e32 v168, v168
	v_mul_f32_e32 v167, 0x3f317217, v177
	v_fma_f32 v167, v177, s52, -v167
	v_fmac_f32_e32 v167, 0x3377d1cf, v177
	v_fmac_f32_e32 v167, 0x3f317217, v177
	v_mov_b32_e32 v167, v167
	v_sub_f32_e32 v177, 1.0, v135
	v_fma_f32 v168, v177, v168, v135
	v_cmp_gt_f32_e64 s[8:9], s97, v168
	s_nop 1
	v_cndmask_b32_e64 v194, 0, 32, s[8:9]
	v_ldexp_f32 v168, v168, v194
	v_log_f32_e32 v168, v168
	v_sub_f32_e32 v194, v147, v167
	v_mul_f32_e32 v167, 0x3fb8aa3b, v194
	v_exp_f32_e32 v195, v167
	v_mul_f32_e32 v147, 0x3f317217, v168
	v_fma_f32 v147, v168, s52, -v147
	v_fmac_f32_e32 v147, 0x3377d1cf, v168
	v_sub_f32_e32 v167, 1.0, v131
	v_fmac_f32_e32 v147, 0x3f317217, v168
	v_fma_f32 v195, v167, v195, v131
	s_nop 0
	v_cmp_gt_f32_e32 vcc, s97, v195
	v_cndmask_b32_e64 v168, 0, v216, s[8:9]
	v_sub_f32_e32 v147, v147, v168
	v_cndmask_b32_e64 v204, 0, 32, vcc
	v_ldexp_f32 v195, v195, v204
	v_log_f32_e32 v195, v195
	v_cmp_lt_f32_e64 s[8:9], 0, v135
	v_cndmask_b32_e32 v168, 0, v216, vcc
	v_cmp_lt_f32_e32 vcc, 0, v131
	v_cndmask_b32_e64 v147, v151, v147, s[8:9]
	v_mul_f32_e32 v151, 0x3f317217, v195
	v_fma_f32 v151, v195, s52, -v151
	v_fmac_f32_e32 v151, 0x3377d1cf, v195
	v_fmac_f32_e32 v151, 0x3f317217, v195
	v_sub_f32_e32 v151, v151, v168
	v_cndmask_b32_e32 v151, v194, v151, vcc
	global_store_dwordx4 v[170:171], v[144:147], off offset:512
	global_store_dwordx4 v[170:171], v[148:151], off offset:528
	s_nop 1
	v_or_b32_e32 v148, 16, v166
	v_ashrrev_i32_e32 v149, 31, v148
	v_lshlrev_b64 v[144:145], 6, v[148:149]
	v_lshl_add_u64 v[144:145], v[160:161], 0, v[144:145]
	s_nop 0
	s_waitcnt lgkmcnt(0)
; __device__ __forceinline__ float silu_f(float x) { return x * __builtin_amdgcn_rcpf(1.f + __expf(-x)); }
; __device__ __forceinline__ v4u pack8(const f32x4 a, const f32x4 b) { v4u w; w.x = cvt_pk_bf16(a[0], a[1]); w.y = cvt_pk_bf16(a[2], a[3]); w.z = cvt_pk_bf16(b[0], b[1]); w.w = cvt_pk_bf16(b[2], b[3]); return w; }
;     __device__ __forceinline__ void operator()(const f32x4 (&acc)[2][2][4][2], const pg8::Unit& u, int wr, int wc, int fr, int fq) const {
;     ...
;         if (grp == 0) { WIN_LOOP( _Pragma("unroll") for (int i = 0; i < 4; ++i) { a[i] = silu_f(a[i]); b[i] = silu_f(b[i]); } *(v4u*)(QO + (size_t)row * DM + c) = pack8(a, b); ) }
;         else if (grp == 3) { WIN_LOOP( _Pragma("unroll") for (int i = 0; i < 4; ++i) { a[i] = silu_f(a[i]); b[i] = silu_f(b[i]); } *(v4u*)(GH + (size_t)row * 512 + c) = pack8(a, b); ) }
;         else if (grp == 1) {
;             f32x4 l0[2], l1[2];
; #pragma unroll
;             for (int bj = 0; bj < 2; ++bj) { l0[bj] = *(const f32x4*)(lb + cb + bj * 128); l1[bj] = *(const f32x4*)(lb + cb + bj * 128 + 4); }
;             WIN_LOOP( _Pragma("unroll") for (int i = 0; i < 4; ++i) { const float s0 = fminf(a[i], 0.f) - __logf(1.f + __expf(-fabsf(a[i]))), s1 = fminf(b[i], 0.f) - __logf(1.f + __expf(-fabsf(b[i]))); const float la = l0[bj][i], lbv = l1[bj][i];
;                     a[i] = la > 0.f ? __logf(la + (1.f - la) * __expf(s0)) : s0; b[i] = lbv > 0.f ? __logf(lbv + (1.f - lbv) * __expf(s1)) : s1; }
;                 *(f32x4*)(LF + (size_t)row * 512 + c) = a; *(f32x4*)(LF + (size_t)row * 512 + c + 4) = b; __builtin_amdgcn_sched_barrier(0); ) }
	s_nop 3
	s_nop 0
	s_nop 1
	s_waitcnt lgkmcnt(0)
	s_nop 1
	s_waitcnt lgkmcnt(0)
	s_nop 1
	v_mov_b32_e32 v168, v251
	v_lshlrev_b64 v[144:145], 11, v[148:149]
	v_lshl_add_u64 v[170:171], s[50:51], 0, v[144:145]
	v_lshl_add_u64 v[170:171], v[170:171], 0, v[192:193]
	v_pk_mul_f32 v[148:149], v[52:53], v[168:169] op_sel_hi:[1,0]
	v_pk_mul_f32 v[144:145], v[48:49], v[168:169] op_sel_hi:[1,0]
	v_min_f32_e32 v194, 0, v148
	v_mul_f32_e64 v148, |v148|, s57
	v_exp_f32_e32 v148, v148
	v_pk_mul_f32 v[150:151], v[54:55], v[168:169] op_sel_hi:[1,0]
	v_pk_mul_f32 v[146:147], v[50:51], v[168:169] op_sel_hi:[1,0]
	v_add_f32_e32 v148, 1.0, v148
	v_log_f32_e32 v148, v148
	s_nop 0
	v_mul_f32_e32 v195, 0x3f317217, v148
	v_fma_f32 v195, v148, s52, -v195
	v_fmac_f32_e32 v195, 0x3377d1cf, v148
	v_fmac_f32_e32 v195, 0x3f317217, v148
	v_mov_b32_e32 v148, v195
	v_sub_f32_e32 v148, v194, v148
	v_min_f32_e32 v194, 0, v144
	v_mul_f32_e64 v144, |v144|, s57
	v_exp_f32_e32 v144, v144
	s_nop 0
	v_add_f32_e32 v144, 1.0, v144
	v_log_f32_e32 v144, v144
	s_nop 0
	v_mul_f32_e32 v195, 0x3f317217, v144
	v_fma_f32 v195, v144, s52, -v195
	v_fmac_f32_e32 v195, 0x3377d1cf, v144
	v_fmac_f32_e32 v195, 0x3f317217, v144
	v_mov_b32_e32 v144, v195
	v_sub_f32_e32 v194, v194, v144
	v_mul_f32_e32 v144, 0x3fb8aa3b, v148
	v_exp_f32_e32 v144, v144
	s_nop 0
	v_fma_f32 v144, v190, v144, v140
	v_cmp_gt_f32_e64 s[40:41], s97, v144
	s_nop 1
	v_cndmask_b32_e64 v195, 0, 32, s[40:41]
	v_ldexp_f32 v144, v144, v195
	v_log_f32_e32 v144, v144
	s_nop 0
	v_mul_f32_e32 v195, 0x3f317217, v144
	v_fma_f32 v195, v144, s52, -v195
	v_fmac_f32_e32 v195, 0x3377d1cf, v144
	v_fmac_f32_e32 v195, 0x3f317217, v144
	v_mov_b32_e32 v144, v195
	v_cndmask_b32_e64 v195, 0, v216, s[40:41]
	v_sub_f32_e32 v144, v144, v195
	v_cndmask_b32_e64 v144, v148, v144, s[38:39]
	v_mul_f32_e32 v148, 0x3fb8aa3b, v194
	v_exp_f32_e32 v148, v148
	s_nop 0
	v_fma_f32 v148, v191, v148, v136
	v_cmp_gt_f32_e64 s[40:41], s97, v148
	s_nop 1
	v_cndmask_b32_e64 v195, 0, 32, s[40:41]
	v_ldexp_f32 v148, v148, v195
	v_log_f32_e32 v148, v148
	s_nop 0
	v_mul_f32_e32 v195, 0x3f317217, v148
	v_fma_f32 v195, v148, s52, -v195
	v_fmac_f32_e32 v195, 0x3377d1cf, v148
	v_fmac_f32_e32 v195, 0x3f317217, v148
	v_mov_b32_e32 v148, v195
	v_cndmask_b32_e64 v195, 0, v216, s[40:41]
	v_sub_f32_e32 v148, v148, v195
	v_cndmask_b32_e64 v148, v194, v148, s[36:37]
	v_min_f32_e32 v194, 0, v149
	v_mul_f32_e64 v149, |v149|, s57
	v_exp_f32_e32 v149, v149
	s_nop 0
	v_add_f32_e32 v149, 1.0, v149
	v_log_f32_e32 v149, v149
	s_nop 0
	v_mul_f32_e32 v195, 0x3f317217, v149
	v_fma_f32 v195, v149, s52, -v195
	v_fmac_f32_e32 v195, 0x3377d1cf, v149
	v_fmac_f32_e32 v195, 0x3f317217, v149
	v_mov_b32_e32 v149, v195
	v_sub_f32_e32 v149, v194, v149
	v_min_f32_e32 v194, 0, v145
	v_mul_f32_e64 v145, |v145|, s57
	v_exp_f32_e32 v145, v145
	s_nop 0
	v_add_f32_e32 v145, 1.0, v145
	v_log_f32_e32 v145, v145
	s_nop 0
	v_mul_f32_e32 v195, 0x3f317217, v145
	v_fma_f32 v195, v145, s52, -v195
	v_fmac_f32_e32 v195, 0x3377d1cf, v145
	v_fmac_f32_e32 v195, 0x3f317217, v145
	v_mov_b32_e32 v145, v195
	v_sub_f32_e32 v194, v194, v145
	v_mul_f32_e32 v145, 0x3fb8aa3b, v149
	v_exp_f32_e32 v145, v145
	s_nop 0
	v_fma_f32 v145, v188, v145, v141
	v_cmp_gt_f32_e64 s[40:41], s97, v145
	s_nop 1
	v_cndmask_b32_e64 v195, 0, 32, s[40:41]
	v_ldexp_f32 v145, v145, v195
	v_log_f32_e32 v145, v145
	s_nop 0
	v_mul_f32_e32 v195, 0x3f317217, v145
	v_fma_f32 v195, v145, s52, -v195
	v_fmac_f32_e32 v195, 0x3377d1cf, v145
	v_fmac_f32_e32 v195, 0x3f317217, v145
	v_mov_b32_e32 v145, v195
	v_cndmask_b32_e64 v195, 0, v216, s[40:41]
	v_sub_f32_e32 v145, v145, v195
	v_cndmask_b32_e64 v145, v149, v145, s[34:35]
	v_mul_f32_e32 v149, 0x3fb8aa3b, v194
	v_exp_f32_e32 v149, v149
	s_nop 0
	v_fma_f32 v149, v189, v149, v137
	v_cmp_gt_f32_e64 s[40:41], s97, v149
	s_nop 1
	v_cndmask_b32_e64 v195, 0, 32, s[40:41]
	v_ldexp_f32 v149, v149, v195
	v_log_f32_e32 v149, v149
	s_nop 0
	v_mul_f32_e32 v195, 0x3f317217, v149
	v_fma_f32 v195, v149, s52, -v195
	v_fmac_f32_e32 v195, 0x3377d1cf, v149
	v_fmac_f32_e32 v195, 0x3f317217, v149
	v_mov_b32_e32 v149, v195
	v_cndmask_b32_e64 v195, 0, v216, s[40:41]
	v_sub_f32_e32 v149, v149, v195
	v_cndmask_b32_e64 v149, v194, v149, s[30:31]
	v_min_f32_e32 v194, 0, v150
	v_mul_f32_e64 v150, |v150|, s57
	v_exp_f32_e32 v150, v150
	s_nop 0
	v_add_f32_e32 v150, 1.0, v150
	v_log_f32_e32 v150, v150
	s_nop 0
	v_mul_f32_e32 v195, 0x3f317217, v150
	v_fma_f32 v195, v150, s52, -v195
	v_fmac_f32_e32 v195, 0x3377d1cf, v150
	v_fmac_f32_e32 v195, 0x3f317217, v150
	v_mov_b32_e32 v150, v195
	v_sub_f32_e32 v150, v194, v150
	v_min_f32_e32 v194, 0, v146
	v_mul_f32_e64 v146, |v146|, s57
	v_exp_f32_e32 v146, v146
	s_nop 0
	v_add_f32_e32 v146, 1.0, v146
	v_log_f32_e32 v146, v146
	s_nop 0
	v_mul_f32_e32 v195, 0x3f317217, v146
	v_fma_f32 v195, v146, s52, -v195
	v_fmac_f32_e32 v195, 0x3377d1cf, v146
	v_fmac_f32_e32 v195, 0x3f317217, v146
	v_mov_b32_e32 v146, v195
	v_sub_f32_e32 v194, v194, v146
	v_mul_f32_e32 v146, 0x3fb8aa3b, v150
	v_exp_f32_e32 v146, v146
	s_nop 0
	v_fma_f32 v146, v187, v146, v142
	v_cmp_gt_f32_e64 s[40:41], s97, v146
	s_nop 1
	v_cndmask_b32_e64 v195, 0, 32, s[40:41]
	v_ldexp_f32 v146, v146, v195
	v_log_f32_e32 v146, v146
	s_nop 0
	v_mul_f32_e32 v195, 0x3f317217, v146
	v_fma_f32 v195, v146, s52, -v195
	v_fmac_f32_e32 v195, 0x3377d1cf, v146
	v_fmac_f32_e32 v195, 0x3f317217, v146
	v_mov_b32_e32 v146, v195
	v_cndmask_b32_e64 v195, 0, v216, s[40:41]
	v_sub_f32_e32 v146, v146, v195
	v_cndmask_b32_e64 v146, v150, v146, s[28:29]
	v_mul_f32_e32 v150, 0x3fb8aa3b, v194
	v_exp_f32_e32 v150, v150
	s_nop 0
	v_fma_f32 v150, v186, v150, v138
; __device__ __forceinline__ float silu_f(float x) { return x * __builtin_amdgcn_rcpf(1.f + __expf(-x)); }
; __device__ __forceinline__ v4u pack8(const f32x4 a, const f32x4 b) { v4u w; w.x = cvt_pk_bf16(a[0], a[1]); w.y = cvt_pk_bf16(a[2], a[3]); w.z = cvt_pk_bf16(b[0], b[1]); w.w = cvt_pk_bf16(b[2], b[3]); return w; }
;     __device__ __forceinline__ void operator()(const f32x4 (&acc)[2][2][4][2], const pg8::Unit& u, int wr, int wc, int fr, int fq) const {
;     ...
;         if (grp == 0) { WIN_LOOP( _Pragma("unroll") for (int i = 0; i < 4; ++i) { a[i] = silu_f(a[i]); b[i] = silu_f(b[i]); } *(v4u*)(QO + (size_t)row * DM + c) = pack8(a, b); ) }
;         else if (grp == 3) { WIN_LOOP( _Pragma("unroll") for (int i = 0; i < 4; ++i) { a[i] = silu_f(a[i]); b[i] = silu_f(b[i]); } *(v4u*)(GH + (size_t)row * 512 + c) = pack8(a, b); ) }
;         else if (grp == 1) {
;             f32x4 l0[2], l1[2];
; #pragma unroll
;             for (int bj = 0; bj < 2; ++bj) { l0[bj] = *(const f32x4*)(lb + cb + bj * 128); l1[bj] = *(const f32x4*)(lb + cb + bj * 128 + 4); }
;             WIN_LOOP( _Pragma("unroll") for (int i = 0; i < 4; ++i) { const float s0 = fminf(a[i], 0.f) - __logf(1.f + __expf(-fabsf(a[i]))), s1 = fminf(b[i], 0.f) - __logf(1.f + __expf(-fabsf(b[i]))); const float la = l0[bj][i], lbv = l1[bj][i];
;                     a[i] = la > 0.f ? __logf(la + (1.f - la) * __expf(s0)) : s0; b[i] = lbv > 0.f ? __logf(lbv + (1.f - lbv) * __expf(s1)) : s1; }
;                 *(f32x4*)(LF + (size_t)row * 512 + c) = a; *(f32x4*)(LF + (size_t)row * 512 + c + 4) = b; __builtin_amdgcn_sched_barrier(0); ) }
	v_cmp_gt_f32_e64 s[40:41], s97, v150
	s_nop 1
	v_cndmask_b32_e64 v195, 0, 32, s[40:41]
	v_ldexp_f32 v150, v150, v195
	v_log_f32_e32 v150, v150
	s_nop 0
	v_mul_f32_e32 v195, 0x3f317217, v150
	v_fma_f32 v195, v150, s52, -v195
	v_fmac_f32_e32 v195, 0x3377d1cf, v150
	v_fmac_f32_e32 v195, 0x3f317217, v150
	v_mov_b32_e32 v150, v195
	v_cndmask_b32_e64 v195, 0, v216, s[40:41]
	v_sub_f32_e32 v150, v150, v195
	v_cndmask_b32_e64 v150, v194, v150, s[26:27]
	v_min_f32_e32 v194, 0, v151
	v_mul_f32_e64 v151, |v151|, s57
	v_exp_f32_e32 v151, v151
	s_nop 0
	v_add_f32_e32 v151, 1.0, v151
	v_log_f32_e32 v151, v151
	s_nop 0
	v_mul_f32_e32 v195, 0x3f317217, v151
	v_fma_f32 v195, v151, s52, -v195
	v_fmac_f32_e32 v195, 0x3377d1cf, v151
	v_fmac_f32_e32 v195, 0x3f317217, v151
	v_mov_b32_e32 v151, v195
	v_sub_f32_e32 v151, v194, v151
	v_min_f32_e32 v194, 0, v147
	v_mul_f32_e64 v147, |v147|, s57
	v_exp_f32_e32 v147, v147
	s_nop 0
	v_add_f32_e32 v147, 1.0, v147
	v_log_f32_e32 v147, v147
	s_nop 0
	v_mul_f32_e32 v195, 0x3f317217, v147
	v_fma_f32 v195, v147, s52, -v195
	v_fmac_f32_e32 v195, 0x3377d1cf, v147
	v_fmac_f32_e32 v195, 0x3f317217, v147
	v_mov_b32_e32 v147, v195
	v_sub_f32_e32 v194, v194, v147
	v_mul_f32_e32 v147, 0x3fb8aa3b, v151
	v_exp_f32_e32 v147, v147
	s_nop 0
	v_fma_f32 v147, v185, v147, v143
	v_cmp_gt_f32_e64 s[40:41], s97, v147
	s_nop 1
	v_cndmask_b32_e64 v195, 0, 32, s[40:41]
	v_ldexp_f32 v147, v147, v195
	v_log_f32_e32 v147, v147
	s_nop 0
	v_mul_f32_e32 v195, 0x3f317217, v147
	v_fma_f32 v195, v147, s52, -v195
	v_fmac_f32_e32 v195, 0x3377d1cf, v147
	v_fmac_f32_e32 v195, 0x3f317217, v147
	v_mov_b32_e32 v147, v195
	v_cndmask_b32_e64 v195, 0, v216, s[40:41]
	v_sub_f32_e32 v147, v147, v195
	v_cndmask_b32_e64 v147, v151, v147, s[24:25]
	v_mul_f32_e32 v151, 0x3fb8aa3b, v194
	v_exp_f32_e32 v151, v151
	s_nop 0
	v_fma_f32 v151, v184, v151, v139
	v_cmp_gt_f32_e64 s[40:41], s97, v151
	s_nop 1
	v_cndmask_b32_e64 v195, 0, 32, s[40:41]
	v_ldexp_f32 v151, v151, v195
	v_log_f32_e32 v151, v151
	s_nop 0
	v_mul_f32_e32 v195, 0x3f317217, v151
	v_fma_f32 v195, v151, s52, -v195
	v_fmac_f32_e32 v195, 0x3377d1cf, v151
	v_fmac_f32_e32 v195, 0x3f317217, v151
	v_mov_b32_e32 v151, v195
	v_cndmask_b32_e64 v195, 0, v216, s[40:41]
	v_sub_f32_e32 v151, v151, v195
	v_cndmask_b32_e64 v151, v194, v151, s[22:23]
	global_store_dwordx4 v[170:171], v[144:147], off
	global_store_dwordx4 v[170:171], v[148:151], off offset:16
	s_nop 1
	v_pk_mul_f32 v[148:149], v[116:117], v[168:169] op_sel_hi:[1,0]
	v_pk_mul_f32 v[150:151], v[118:119], v[168:169] op_sel_hi:[1,0]
	v_pk_mul_f32 v[146:147], v[114:115], v[168:169] op_sel_hi:[1,0]
	v_pk_mul_f32 v[144:145], v[112:113], v[168:169] op_sel_hi:[1,0]
	v_min_f32_e32 v168, 0, v148
	v_mul_f32_e64 v148, |v148|, s57
	v_exp_f32_e32 v148, v148
	s_nop 0
	v_add_f32_e32 v148, 1.0, v148
	v_log_f32_e32 v148, v148
	s_nop 0
	v_mul_f32_e32 v194, 0x3f317217, v148
	v_fma_f32 v194, v148, s52, -v194
	v_fmac_f32_e32 v194, 0x3377d1cf, v148
	v_fmac_f32_e32 v194, 0x3f317217, v148
	v_mov_b32_e32 v148, v194
	v_sub_f32_e32 v148, v168, v148
	v_min_f32_e32 v168, 0, v144
	v_mul_f32_e64 v144, |v144|, s57
	v_exp_f32_e32 v144, v144
	s_nop 0
	v_add_f32_e32 v144, 1.0, v144
	v_log_f32_e32 v144, v144
	s_nop 0
	v_mul_f32_e32 v194, 0x3f317217, v144
	v_fma_f32 v194, v144, s52, -v194
	v_fmac_f32_e32 v194, 0x3377d1cf, v144
	v_fmac_f32_e32 v194, 0x3f317217, v144
	v_mov_b32_e32 v144, v194
	v_sub_f32_e32 v168, v168, v144
	v_mul_f32_e32 v144, 0x3fb8aa3b, v148
	v_exp_f32_e32 v144, v144
	s_nop 0
	v_fma_f32 v144, v183, v144, v132
	v_cmp_gt_f32_e64 s[40:41], s97, v144
	s_nop 1
	v_cndmask_b32_e64 v194, 0, 32, s[40:41]
	v_ldexp_f32 v144, v144, v194
	v_log_f32_e32 v144, v144
	s_nop 0
	v_mul_f32_e32 v194, 0x3f317217, v144
	v_fma_f32 v194, v144, s52, -v194
	v_fmac_f32_e32 v194, 0x3377d1cf, v144
	v_fmac_f32_e32 v194, 0x3f317217, v144
	v_mov_b32_e32 v144, v194
	v_cndmask_b32_e64 v194, 0, v216, s[40:41]
	v_sub_f32_e32 v144, v144, v194
	v_cndmask_b32_e64 v144, v148, v144, s[20:21]
	v_mul_f32_e32 v148, 0x3fb8aa3b, v168
	v_exp_f32_e32 v148, v148
	s_nop 0
	v_fma_f32 v148, v182, v148, v128
	v_cmp_gt_f32_e64 s[40:41], s97, v148
	s_nop 1
	v_cndmask_b32_e64 v194, 0, 32, s[40:41]
	v_ldexp_f32 v148, v148, v194
	v_log_f32_e32 v148, v148
	s_nop 0
	v_mul_f32_e32 v194, 0x3f317217, v148
	v_fma_f32 v194, v148, s52, -v194
	v_fmac_f32_e32 v194, 0x3377d1cf, v148
	v_fmac_f32_e32 v194, 0x3f317217, v148
	v_mov_b32_e32 v148, v194
	v_cndmask_b32_e64 v194, 0, v216, s[40:41]
	v_sub_f32_e32 v148, v148, v194
	v_cndmask_b32_e64 v148, v168, v148, s[18:19]
	v_min_f32_e32 v168, 0, v149
	v_mul_f32_e64 v149, |v149|, s57
	v_exp_f32_e32 v149, v149
	s_nop 0
	v_add_f32_e32 v149, 1.0, v149
	v_log_f32_e32 v149, v149
	s_nop 0
	v_mul_f32_e32 v194, 0x3f317217, v149
	v_fma_f32 v194, v149, s52, -v194
	v_fmac_f32_e32 v194, 0x3377d1cf, v149
	v_fmac_f32_e32 v194, 0x3f317217, v149
	v_mov_b32_e32 v149, v194
	v_sub_f32_e32 v149, v168, v149
	v_min_f32_e32 v168, 0, v145
	v_mul_f32_e64 v145, |v145|, s57
	v_exp_f32_e32 v145, v145
	s_nop 0
	v_add_f32_e32 v145, 1.0, v145
	v_log_f32_e32 v145, v145
	s_nop 0
	v_mul_f32_e32 v194, 0x3f317217, v145
	v_fma_f32 v194, v145, s52, -v194
	v_fmac_f32_e32 v194, 0x3377d1cf, v145
	v_fmac_f32_e32 v194, 0x3f317217, v145
	v_mov_b32_e32 v145, v194
	v_sub_f32_e32 v168, v168, v145
	v_mul_f32_e32 v145, 0x3fb8aa3b, v149
	v_exp_f32_e32 v145, v145
	s_nop 0
	v_fma_f32 v145, v181, v145, v133
	v_cmp_gt_f32_e64 s[40:41], s97, v145
	s_nop 1
	v_cndmask_b32_e64 v194, 0, 32, s[40:41]
	v_ldexp_f32 v145, v145, v194
	v_log_f32_e32 v145, v145
	s_nop 0
	v_mul_f32_e32 v194, 0x3f317217, v145
	v_fma_f32 v194, v145, s52, -v194
	v_fmac_f32_e32 v194, 0x3377d1cf, v145
; __device__ __forceinline__ float silu_f(float x) { return x * __builtin_amdgcn_rcpf(1.f + __expf(-x)); }
; __device__ __forceinline__ v4u pack8(const f32x4 a, const f32x4 b) { v4u w; w.x = cvt_pk_bf16(a[0], a[1]); w.y = cvt_pk_bf16(a[2], a[3]); w.z = cvt_pk_bf16(b[0], b[1]); w.w = cvt_pk_bf16(b[2], b[3]); return w; }
;     __device__ __forceinline__ void operator()(const f32x4 (&acc)[2][2][4][2], const pg8::Unit& u, int wr, int wc, int fr, int fq) const {
;     ...
;         if (grp == 0) { WIN_LOOP( _Pragma("unroll") for (int i = 0; i < 4; ++i) { a[i] = silu_f(a[i]); b[i] = silu_f(b[i]); } *(v4u*)(QO + (size_t)row * DM + c) = pack8(a, b); ) }
;         else if (grp == 3) { WIN_LOOP( _Pragma("unroll") for (int i = 0; i < 4; ++i) { a[i] = silu_f(a[i]); b[i] = silu_f(b[i]); } *(v4u*)(GH + (size_t)row * 512 + c) = pack8(a, b); ) }
;         else if (grp == 1) {
;             f32x4 l0[2], l1[2];
; #pragma unroll
;             for (int bj = 0; bj < 2; ++bj) { l0[bj] = *(const f32x4*)(lb + cb + bj * 128); l1[bj] = *(const f32x4*)(lb + cb + bj * 128 + 4); }
;             WIN_LOOP( _Pragma("unroll") for (int i = 0; i < 4; ++i) { const float s0 = fminf(a[i], 0.f) - __logf(1.f + __expf(-fabsf(a[i]))), s1 = fminf(b[i], 0.f) - __logf(1.f + __expf(-fabsf(b[i]))); const float la = l0[bj][i], lbv = l1[bj][i];
;                     a[i] = la > 0.f ? __logf(la + (1.f - la) * __expf(s0)) : s0; b[i] = lbv > 0.f ? __logf(lbv + (1.f - lbv) * __expf(s1)) : s1; }
;                 *(f32x4*)(LF + (size_t)row * 512 + c) = a; *(f32x4*)(LF + (size_t)row * 512 + c + 4) = b; __builtin_amdgcn_sched_barrier(0); ) }
	v_fmac_f32_e32 v194, 0x3f317217, v145
	v_mov_b32_e32 v145, v194
	v_cndmask_b32_e64 v194, 0, v216, s[40:41]
	v_sub_f32_e32 v145, v145, v194
	v_cndmask_b32_e64 v145, v149, v145, s[16:17]
	v_mul_f32_e32 v149, 0x3fb8aa3b, v168
	v_exp_f32_e32 v149, v149
	s_nop 0
	v_fma_f32 v149, v180, v149, v129
	v_cmp_gt_f32_e64 s[40:41], s97, v149
	s_nop 1
	v_cndmask_b32_e64 v194, 0, 32, s[40:41]
	v_ldexp_f32 v149, v149, v194
	v_log_f32_e32 v149, v149
	s_nop 0
	v_mul_f32_e32 v194, 0x3f317217, v149
	v_fma_f32 v194, v149, s52, -v194
	v_fmac_f32_e32 v194, 0x3377d1cf, v149
	v_fmac_f32_e32 v194, 0x3f317217, v149
	v_mov_b32_e32 v149, v194
	v_cndmask_b32_e64 v194, 0, v216, s[40:41]
	v_sub_f32_e32 v149, v149, v194
	v_cndmask_b32_e64 v149, v168, v149, s[14:15]
	v_min_f32_e32 v168, 0, v150
	v_mul_f32_e64 v150, |v150|, s57
	v_exp_f32_e32 v150, v150
	s_nop 0
	v_add_f32_e32 v150, 1.0, v150
	v_log_f32_e32 v150, v150
	s_nop 0
	v_mul_f32_e32 v194, 0x3f317217, v150
	v_fma_f32 v194, v150, s52, -v194
	v_fmac_f32_e32 v194, 0x3377d1cf, v150
	v_fmac_f32_e32 v194, 0x3f317217, v150
	v_mov_b32_e32 v150, v194
	v_sub_f32_e32 v150, v168, v150
	v_min_f32_e32 v168, 0, v146
	v_mul_f32_e64 v146, |v146|, s57
	v_exp_f32_e32 v146, v146
	s_nop 0
	v_add_f32_e32 v146, 1.0, v146
	v_log_f32_e32 v146, v146
	s_nop 0
	v_mul_f32_e32 v194, 0x3f317217, v146
	v_fma_f32 v194, v146, s52, -v194
	v_fmac_f32_e32 v194, 0x3377d1cf, v146
	v_fmac_f32_e32 v194, 0x3f317217, v146
	v_mov_b32_e32 v146, v194
	v_sub_f32_e32 v168, v168, v146
	v_mul_f32_e32 v146, 0x3fb8aa3b, v150
	v_exp_f32_e32 v146, v146
	s_nop 0
	v_fma_f32 v146, v179, v146, v134
	v_cmp_gt_f32_e64 s[40:41], s97, v146
	s_nop 1
	v_cndmask_b32_e64 v194, 0, 32, s[40:41]
	v_ldexp_f32 v146, v146, v194
	v_log_f32_e32 v146, v146
	s_nop 0
	v_mul_f32_e32 v194, 0x3f317217, v146
	v_fma_f32 v194, v146, s52, -v194
	v_fmac_f32_e32 v194, 0x3377d1cf, v146
	v_fmac_f32_e32 v194, 0x3f317217, v146
	v_mov_b32_e32 v146, v194
	v_cndmask_b32_e64 v194, 0, v216, s[40:41]
	v_sub_f32_e32 v146, v146, v194
	v_cndmask_b32_e64 v146, v150, v146, s[12:13]
	v_mul_f32_e32 v150, 0x3fb8aa3b, v168
	v_exp_f32_e32 v150, v150
	s_nop 0
	v_fma_f32 v150, v178, v150, v130
	v_cmp_gt_f32_e64 s[40:41], s97, v150
	s_nop 1
	v_cndmask_b32_e64 v194, 0, 32, s[40:41]
	v_ldexp_f32 v150, v150, v194
	v_log_f32_e32 v150, v150
	s_nop 0
	v_mul_f32_e32 v194, 0x3f317217, v150
	v_fma_f32 v194, v150, s52, -v194
	v_fmac_f32_e32 v194, 0x3377d1cf, v150
	v_fmac_f32_e32 v194, 0x3f317217, v150
	v_mov_b32_e32 v150, v194
	v_cndmask_b32_e64 v194, 0, v216, s[40:41]
	v_sub_f32_e32 v150, v150, v194
	v_cndmask_b32_e64 v150, v168, v150, s[10:11]
	v_min_f32_e32 v168, 0, v151
	v_mul_f32_e64 v151, |v151|, s57
	v_exp_f32_e32 v151, v151
	s_nop 0
	v_add_f32_e32 v151, 1.0, v151
	v_log_f32_e32 v151, v151
	s_nop 0
	v_mul_f32_e32 v194, 0x3f317217, v151
	v_fma_f32 v194, v151, s52, -v194
	v_fmac_f32_e32 v194, 0x3377d1cf, v151
	v_fmac_f32_e32 v194, 0x3f317217, v151
	v_mov_b32_e32 v151, v194
	v_sub_f32_e32 v151, v168, v151
	v_min_f32_e32 v168, 0, v147
	v_mul_f32_e64 v147, |v147|, s57
	v_exp_f32_e32 v147, v147
	s_nop 0
	v_add_f32_e32 v147, 1.0, v147
	v_log_f32_e32 v147, v147
	s_nop 0
	v_mul_f32_e32 v194, 0x3f317217, v147
	v_fma_f32 v194, v147, s52, -v194
	v_fmac_f32_e32 v194, 0x3377d1cf, v147
	v_fmac_f32_e32 v194, 0x3f317217, v147
	v_mov_b32_e32 v147, v194
	v_sub_f32_e32 v168, v168, v147
	v_mul_f32_e32 v147, 0x3fb8aa3b, v151
	v_exp_f32_e32 v147, v147
	s_nop 0
	v_fma_f32 v147, v177, v147, v135
	v_cmp_gt_f32_e64 s[40:41], s97, v147
	s_nop 1
	v_cndmask_b32_e64 v194, 0, 32, s[40:41]
	v_ldexp_f32 v147, v147, v194
	v_log_f32_e32 v147, v147
	s_nop 0
	v_mul_f32_e32 v194, 0x3f317217, v147
	v_fma_f32 v194, v147, s52, -v194
	v_fmac_f32_e32 v194, 0x3377d1cf, v147
	v_fmac_f32_e32 v194, 0x3f317217, v147
	v_mov_b32_e32 v147, v194
	v_cndmask_b32_e64 v194, 0, v216, s[40:41]
	v_sub_f32_e32 v147, v147, v194
	v_cndmask_b32_e64 v147, v151, v147, s[8:9]
	v_mul_f32_e32 v151, 0x3fb8aa3b, v168
	v_exp_f32_e32 v151, v151
	s_nop 0
	v_fma_f32 v151, v167, v151, v131
	v_cmp_gt_f32_e64 s[40:41], s97, v151
	s_nop 1
	v_cndmask_b32_e64 v194, 0, 32, s[40:41]
	v_ldexp_f32 v151, v151, v194
	v_log_f32_e32 v151, v151
	s_nop 0
	v_mul_f32_e32 v194, 0x3f317217, v151
	v_fma_f32 v194, v151, s52, -v194
	v_fmac_f32_e32 v194, 0x3377d1cf, v151
	v_fmac_f32_e32 v194, 0x3f317217, v151
	v_mov_b32_e32 v151, v194
	v_cndmask_b32_e64 v194, 0, v216, s[40:41]
	v_sub_f32_e32 v151, v151, v194
	v_cndmask_b32_e32 v151, v168, v151, vcc
	global_store_dwordx4 v[170:171], v[144:147], off offset:512
	global_store_dwordx4 v[170:171], v[148:151], off offset:528
	s_nop 1
	v_or_b32_e32 v148, 32, v166
	v_ashrrev_i32_e32 v149, 31, v148
	v_lshlrev_b64 v[144:145], 6, v[148:149]
	v_lshl_add_u64 v[144:145], v[160:161], 0, v[144:145]
	s_nop 0
	s_waitcnt lgkmcnt(0)
	s_nop 3
	s_nop 0
	s_nop 1
	s_waitcnt lgkmcnt(0)
	s_nop 1
	s_waitcnt lgkmcnt(0)
; __device__ __forceinline__ float silu_f(float x) { return x * __builtin_amdgcn_rcpf(1.f + __expf(-x)); }
; __device__ __forceinline__ v4u pack8(const f32x4 a, const f32x4 b) { v4u w; w.x = cvt_pk_bf16(a[0], a[1]); w.y = cvt_pk_bf16(a[2], a[3]); w.z = cvt_pk_bf16(b[0], b[1]); w.w = cvt_pk_bf16(b[2], b[3]); return w; }
;     __device__ __forceinline__ void operator()(const f32x4 (&acc)[2][2][4][2], const pg8::Unit& u, int wr, int wc, int fr, int fq) const {
;     ...
;         if (grp == 0) { WIN_LOOP( _Pragma("unroll") for (int i = 0; i < 4; ++i) { a[i] = silu_f(a[i]); b[i] = silu_f(b[i]); } *(v4u*)(QO + (size_t)row * DM + c) = pack8(a, b); ) }
;         else if (grp == 3) { WIN_LOOP( _Pragma("unroll") for (int i = 0; i < 4; ++i) { a[i] = silu_f(a[i]); b[i] = silu_f(b[i]); } *(v4u*)(GH + (size_t)row * 512 + c) = pack8(a, b); ) }
;         else if (grp == 1) {
;             f32x4 l0[2], l1[2];
; #pragma unroll
;             for (int bj = 0; bj < 2; ++bj) { l0[bj] = *(const f32x4*)(lb + cb + bj * 128); l1[bj] = *(const f32x4*)(lb + cb + bj * 128 + 4); }
;             WIN_LOOP( _Pragma("unroll") for (int i = 0; i < 4; ++i) { const float s0 = fminf(a[i], 0.f) - __logf(1.f + __expf(-fabsf(a[i]))), s1 = fminf(b[i], 0.f) - __logf(1.f + __expf(-fabsf(b[i]))); const float la = l0[bj][i], lbv = l1[bj][i];
;                     a[i] = la > 0.f ? __logf(la + (1.f - la) * __expf(s0)) : s0; b[i] = lbv > 0.f ? __logf(lbv + (1.f - lbv) * __expf(s1)) : s1; }
;                 *(f32x4*)(LF + (size_t)row * 512 + c) = a; *(f32x4*)(LF + (size_t)row * 512 + c + 4) = b; __builtin_amdgcn_sched_barrier(0); ) }
	s_nop 1
	v_mov_b32_e32 v168, v252
	v_lshlrev_b64 v[144:145], 11, v[148:149]
	v_lshl_add_u64 v[170:171], s[50:51], 0, v[144:145]
	v_lshl_add_u64 v[170:171], v[170:171], 0, v[192:193]
	v_pk_mul_f32 v[148:149], v[44:45], v[168:169] op_sel_hi:[1,0]
	v_pk_mul_f32 v[144:145], v[40:41], v[168:169] op_sel_hi:[1,0]
	v_min_f32_e32 v194, 0, v148
	v_mul_f32_e64 v148, |v148|, s57
	v_exp_f32_e32 v148, v148
	v_pk_mul_f32 v[150:151], v[46:47], v[168:169] op_sel_hi:[1,0]
	v_pk_mul_f32 v[146:147], v[42:43], v[168:169] op_sel_hi:[1,0]
	v_add_f32_e32 v148, 1.0, v148
	v_log_f32_e32 v148, v148
	s_nop 0
	v_mul_f32_e32 v195, 0x3f317217, v148
	v_fma_f32 v195, v148, s52, -v195
	v_fmac_f32_e32 v195, 0x3377d1cf, v148
	v_fmac_f32_e32 v195, 0x3f317217, v148
	v_mov_b32_e32 v148, v195
	v_sub_f32_e32 v148, v194, v148
	v_min_f32_e32 v194, 0, v144
	v_mul_f32_e64 v144, |v144|, s57
	v_exp_f32_e32 v144, v144
	s_nop 0
	v_add_f32_e32 v144, 1.0, v144
	v_log_f32_e32 v144, v144
	s_nop 0
	v_mul_f32_e32 v195, 0x3f317217, v144
	v_fma_f32 v195, v144, s52, -v195
	v_fmac_f32_e32 v195, 0x3377d1cf, v144
	v_fmac_f32_e32 v195, 0x3f317217, v144
	v_mov_b32_e32 v144, v195
	v_sub_f32_e32 v194, v194, v144
	v_mul_f32_e32 v144, 0x3fb8aa3b, v148
	v_exp_f32_e32 v144, v144
	s_nop 0
	v_fma_f32 v144, v190, v144, v140
	v_cmp_gt_f32_e64 s[40:41], s97, v144
	s_nop 1
	v_cndmask_b32_e64 v195, 0, 32, s[40:41]
	v_ldexp_f32 v144, v144, v195
	v_log_f32_e32 v144, v144
	s_nop 0
	v_mul_f32_e32 v195, 0x3f317217, v144
	v_fma_f32 v195, v144, s52, -v195
	v_fmac_f32_e32 v195, 0x3377d1cf, v144
	v_fmac_f32_e32 v195, 0x3f317217, v144
	v_mov_b32_e32 v144, v195
	v_cndmask_b32_e64 v195, 0, v216, s[40:41]
	v_sub_f32_e32 v144, v144, v195
	v_cndmask_b32_e64 v144, v148, v144, s[38:39]
	v_mul_f32_e32 v148, 0x3fb8aa3b, v194
	v_exp_f32_e32 v148, v148
	s_nop 0
	v_fma_f32 v148, v191, v148, v136
	v_cmp_gt_f32_e64 s[40:41], s97, v148
	s_nop 1
	v_cndmask_b32_e64 v195, 0, 32, s[40:41]
	v_ldexp_f32 v148, v148, v195
	v_log_f32_e32 v148, v148
	s_nop 0
	v_mul_f32_e32 v195, 0x3f317217, v148
	v_fma_f32 v195, v148, s52, -v195
	v_fmac_f32_e32 v195, 0x3377d1cf, v148
	v_fmac_f32_e32 v195, 0x3f317217, v148
	v_mov_b32_e32 v148, v195
	v_cndmask_b32_e64 v195, 0, v216, s[40:41]
	v_sub_f32_e32 v148, v148, v195
	v_cndmask_b32_e64 v148, v194, v148, s[36:37]
	v_min_f32_e32 v194, 0, v149
	v_mul_f32_e64 v149, |v149|, s57
	v_exp_f32_e32 v149, v149
	s_nop 0
	v_add_f32_e32 v149, 1.0, v149
	v_log_f32_e32 v149, v149
	s_nop 0
	v_mul_f32_e32 v195, 0x3f317217, v149
	v_fma_f32 v195, v149, s52, -v195
	v_fmac_f32_e32 v195, 0x3377d1cf, v149
	v_fmac_f32_e32 v195, 0x3f317217, v149
	v_mov_b32_e32 v149, v195
	v_sub_f32_e32 v149, v194, v149
	v_min_f32_e32 v194, 0, v145
	v_mul_f32_e64 v145, |v145|, s57
	v_exp_f32_e32 v145, v145
	s_nop 0
	v_add_f32_e32 v145, 1.0, v145
	v_log_f32_e32 v145, v145
	s_nop 0
	v_mul_f32_e32 v195, 0x3f317217, v145
	v_fma_f32 v195, v145, s52, -v195
	v_fmac_f32_e32 v195, 0x3377d1cf, v145
	v_fmac_f32_e32 v195, 0x3f317217, v145
	v_mov_b32_e32 v145, v195
	v_sub_f32_e32 v194, v194, v145
	v_mul_f32_e32 v145, 0x3fb8aa3b, v149
	v_exp_f32_e32 v145, v145
	s_nop 0
	v_fma_f32 v145, v188, v145, v141
	v_cmp_gt_f32_e64 s[40:41], s97, v145
	s_nop 1
	v_cndmask_b32_e64 v195, 0, 32, s[40:41]
	v_ldexp_f32 v145, v145, v195
	v_log_f32_e32 v145, v145
	s_nop 0
	v_mul_f32_e32 v195, 0x3f317217, v145
	v_fma_f32 v195, v145, s52, -v195
	v_fmac_f32_e32 v195, 0x3377d1cf, v145
	v_fmac_f32_e32 v195, 0x3f317217, v145
	v_mov_b32_e32 v145, v195
	v_cndmask_b32_e64 v195, 0, v216, s[40:41]
	v_sub_f32_e32 v145, v145, v195
	v_cndmask_b32_e64 v145, v149, v145, s[34:35]
	v_mul_f32_e32 v149, 0x3fb8aa3b, v194
	v_exp_f32_e32 v149, v149
	s_nop 0
	v_fma_f32 v149, v189, v149, v137
	v_cmp_gt_f32_e64 s[40:41], s97, v149
	s_nop 1
	v_cndmask_b32_e64 v195, 0, 32, s[40:41]
	v_ldexp_f32 v149, v149, v195
	v_log_f32_e32 v149, v149
	s_nop 0
	v_mul_f32_e32 v195, 0x3f317217, v149
	v_fma_f32 v195, v149, s52, -v195
	v_fmac_f32_e32 v195, 0x3377d1cf, v149
	v_fmac_f32_e32 v195, 0x3f317217, v149
	v_mov_b32_e32 v149, v195
	v_cndmask_b32_e64 v195, 0, v216, s[40:41]
	v_sub_f32_e32 v149, v149, v195
	v_cndmask_b32_e64 v149, v194, v149, s[30:31]
	v_min_f32_e32 v194, 0, v150
	v_mul_f32_e64 v150, |v150|, s57
	v_exp_f32_e32 v150, v150
	s_nop 0
	v_add_f32_e32 v150, 1.0, v150
	v_log_f32_e32 v150, v150
	s_nop 0
	v_mul_f32_e32 v195, 0x3f317217, v150
	v_fma_f32 v195, v150, s52, -v195
	v_fmac_f32_e32 v195, 0x3377d1cf, v150
	v_fmac_f32_e32 v195, 0x3f317217, v150
	v_mov_b32_e32 v150, v195
	v_sub_f32_e32 v150, v194, v150
	v_min_f32_e32 v194, 0, v146
	v_mul_f32_e64 v146, |v146|, s57
	v_exp_f32_e32 v146, v146
	s_nop 0
	v_add_f32_e32 v146, 1.0, v146
	v_log_f32_e32 v146, v146
	s_nop 0
	v_mul_f32_e32 v195, 0x3f317217, v146
	v_fma_f32 v195, v146, s52, -v195
	v_fmac_f32_e32 v195, 0x3377d1cf, v146
	v_fmac_f32_e32 v195, 0x3f317217, v146
	v_mov_b32_e32 v146, v195
	v_sub_f32_e32 v194, v194, v146
	v_mul_f32_e32 v146, 0x3fb8aa3b, v150
	v_exp_f32_e32 v146, v146
	s_nop 0
	v_fma_f32 v146, v187, v146, v142
	v_cmp_gt_f32_e64 s[40:41], s97, v146
	s_nop 1
	v_cndmask_b32_e64 v195, 0, 32, s[40:41]
	v_ldexp_f32 v146, v146, v195
	v_log_f32_e32 v146, v146
	s_nop 0
	v_mul_f32_e32 v195, 0x3f317217, v146
	v_fma_f32 v195, v146, s52, -v195
	v_fmac_f32_e32 v195, 0x3377d1cf, v146
	v_fmac_f32_e32 v195, 0x3f317217, v146
	v_mov_b32_e32 v146, v195
	v_cndmask_b32_e64 v195, 0, v216, s[40:41]
	v_sub_f32_e32 v146, v146, v195
	v_cndmask_b32_e64 v146, v150, v146, s[28:29]
	v_mul_f32_e32 v150, 0x3fb8aa3b, v194
	v_exp_f32_e32 v150, v150
	s_nop 0
	v_fma_f32 v150, v186, v150, v138
	v_cmp_gt_f32_e64 s[40:41], s97, v150
	s_nop 1
	v_cndmask_b32_e64 v195, 0, 32, s[40:41]
; __device__ __forceinline__ float silu_f(float x) { return x * __builtin_amdgcn_rcpf(1.f + __expf(-x)); }
; __device__ __forceinline__ v4u pack8(const f32x4 a, const f32x4 b) { v4u w; w.x = cvt_pk_bf16(a[0], a[1]); w.y = cvt_pk_bf16(a[2], a[3]); w.z = cvt_pk_bf16(b[0], b[1]); w.w = cvt_pk_bf16(b[2], b[3]); return w; }
;     __device__ __forceinline__ void operator()(const f32x4 (&acc)[2][2][4][2], const pg8::Unit& u, int wr, int wc, int fr, int fq) const {
;     ...
;         if (grp == 0) { WIN_LOOP( _Pragma("unroll") for (int i = 0; i < 4; ++i) { a[i] = silu_f(a[i]); b[i] = silu_f(b[i]); } *(v4u*)(QO + (size_t)row * DM + c) = pack8(a, b); ) }
;         else if (grp == 3) { WIN_LOOP( _Pragma("unroll") for (int i = 0; i < 4; ++i) { a[i] = silu_f(a[i]); b[i] = silu_f(b[i]); } *(v4u*)(GH + (size_t)row * 512 + c) = pack8(a, b); ) }
;         else if (grp == 1) {
;             f32x4 l0[2], l1[2];
; #pragma unroll
;             for (int bj = 0; bj < 2; ++bj) { l0[bj] = *(const f32x4*)(lb + cb + bj * 128); l1[bj] = *(const f32x4*)(lb + cb + bj * 128 + 4); }
;             WIN_LOOP( _Pragma("unroll") for (int i = 0; i < 4; ++i) { const float s0 = fminf(a[i], 0.f) - __logf(1.f + __expf(-fabsf(a[i]))), s1 = fminf(b[i], 0.f) - __logf(1.f + __expf(-fabsf(b[i]))); const float la = l0[bj][i], lbv = l1[bj][i];
;                     a[i] = la > 0.f ? __logf(la + (1.f - la) * __expf(s0)) : s0; b[i] = lbv > 0.f ? __logf(lbv + (1.f - lbv) * __expf(s1)) : s1; }
;                 *(f32x4*)(LF + (size_t)row * 512 + c) = a; *(f32x4*)(LF + (size_t)row * 512 + c + 4) = b; __builtin_amdgcn_sched_barrier(0); ) }
	v_ldexp_f32 v150, v150, v195
	v_log_f32_e32 v150, v150
	s_nop 0
	v_mul_f32_e32 v195, 0x3f317217, v150
	v_fma_f32 v195, v150, s52, -v195
	v_fmac_f32_e32 v195, 0x3377d1cf, v150
	v_fmac_f32_e32 v195, 0x3f317217, v150
	v_mov_b32_e32 v150, v195
	v_cndmask_b32_e64 v195, 0, v216, s[40:41]
	v_sub_f32_e32 v150, v150, v195
	v_cndmask_b32_e64 v150, v194, v150, s[26:27]
	v_min_f32_e32 v194, 0, v151
	v_mul_f32_e64 v151, |v151|, s57
	v_exp_f32_e32 v151, v151
	s_nop 0
	v_add_f32_e32 v151, 1.0, v151
	v_log_f32_e32 v151, v151
	s_nop 0
	v_mul_f32_e32 v195, 0x3f317217, v151
	v_fma_f32 v195, v151, s52, -v195
	v_fmac_f32_e32 v195, 0x3377d1cf, v151
	v_fmac_f32_e32 v195, 0x3f317217, v151
	v_mov_b32_e32 v151, v195
	v_sub_f32_e32 v151, v194, v151
	v_min_f32_e32 v194, 0, v147
	v_mul_f32_e64 v147, |v147|, s57
	v_exp_f32_e32 v147, v147
	s_nop 0
	v_add_f32_e32 v147, 1.0, v147
	v_log_f32_e32 v147, v147
	s_nop 0
	v_mul_f32_e32 v195, 0x3f317217, v147
	v_fma_f32 v195, v147, s52, -v195
	v_fmac_f32_e32 v195, 0x3377d1cf, v147
	v_fmac_f32_e32 v195, 0x3f317217, v147
	v_mov_b32_e32 v147, v195
	v_sub_f32_e32 v194, v194, v147
	v_mul_f32_e32 v147, 0x3fb8aa3b, v151
	v_exp_f32_e32 v147, v147
	s_nop 0
	v_fma_f32 v147, v185, v147, v143
	v_cmp_gt_f32_e64 s[40:41], s97, v147
	s_nop 1
	v_cndmask_b32_e64 v195, 0, 32, s[40:41]
	v_ldexp_f32 v147, v147, v195
	v_log_f32_e32 v147, v147
	s_nop 0
	v_mul_f32_e32 v195, 0x3f317217, v147
	v_fma_f32 v195, v147, s52, -v195
	v_fmac_f32_e32 v195, 0x3377d1cf, v147
	v_fmac_f32_e32 v195, 0x3f317217, v147
	v_mov_b32_e32 v147, v195
	v_cndmask_b32_e64 v195, 0, v216, s[40:41]
	v_sub_f32_e32 v147, v147, v195
	v_cndmask_b32_e64 v147, v151, v147, s[24:25]
	v_mul_f32_e32 v151, 0x3fb8aa3b, v194
	v_exp_f32_e32 v151, v151
	s_nop 0
	v_fma_f32 v151, v184, v151, v139
	v_cmp_gt_f32_e64 s[40:41], s97, v151
	s_nop 1
	v_cndmask_b32_e64 v195, 0, 32, s[40:41]
	v_ldexp_f32 v151, v151, v195
	v_log_f32_e32 v151, v151
	s_nop 0
	v_mul_f32_e32 v195, 0x3f317217, v151
	v_fma_f32 v195, v151, s52, -v195
	v_fmac_f32_e32 v195, 0x3377d1cf, v151
	v_fmac_f32_e32 v195, 0x3f317217, v151
	v_mov_b32_e32 v151, v195
	v_cndmask_b32_e64 v195, 0, v216, s[40:41]
	v_sub_f32_e32 v151, v151, v195
	v_cndmask_b32_e64 v151, v194, v151, s[22:23]
	global_store_dwordx4 v[170:171], v[144:147], off
	global_store_dwordx4 v[170:171], v[148:151], off offset:16
	s_nop 1
	v_pk_mul_f32 v[148:149], v[108:109], v[168:169] op_sel_hi:[1,0]
	v_pk_mul_f32 v[150:151], v[110:111], v[168:169] op_sel_hi:[1,0]
	v_pk_mul_f32 v[146:147], v[106:107], v[168:169] op_sel_hi:[1,0]
	v_pk_mul_f32 v[144:145], v[104:105], v[168:169] op_sel_hi:[1,0]
	v_min_f32_e32 v168, 0, v148
	v_mul_f32_e64 v148, |v148|, s57
	v_exp_f32_e32 v148, v148
	s_nop 0
	v_add_f32_e32 v148, 1.0, v148
	v_log_f32_e32 v148, v148
	s_nop 0
	v_mul_f32_e32 v194, 0x3f317217, v148
	v_fma_f32 v194, v148, s52, -v194
	v_fmac_f32_e32 v194, 0x3377d1cf, v148
	v_fmac_f32_e32 v194, 0x3f317217, v148
	v_mov_b32_e32 v148, v194
	v_sub_f32_e32 v148, v168, v148
	v_min_f32_e32 v168, 0, v144
	v_mul_f32_e64 v144, |v144|, s57
	v_exp_f32_e32 v144, v144
	s_nop 0
	v_add_f32_e32 v144, 1.0, v144
	v_log_f32_e32 v144, v144
	s_nop 0
	v_mul_f32_e32 v194, 0x3f317217, v144
	v_fma_f32 v194, v144, s52, -v194
	v_fmac_f32_e32 v194, 0x3377d1cf, v144
	v_fmac_f32_e32 v194, 0x3f317217, v144
	v_mov_b32_e32 v144, v194
	v_sub_f32_e32 v168, v168, v144
	v_mul_f32_e32 v144, 0x3fb8aa3b, v148
	v_exp_f32_e32 v144, v144
	s_nop 0
	v_fma_f32 v144, v183, v144, v132
	v_cmp_gt_f32_e64 s[40:41], s97, v144
	s_nop 1
	v_cndmask_b32_e64 v194, 0, 32, s[40:41]
	v_ldexp_f32 v144, v144, v194
	v_log_f32_e32 v144, v144
	s_nop 0
	v_mul_f32_e32 v194, 0x3f317217, v144
	v_fma_f32 v194, v144, s52, -v194
	v_fmac_f32_e32 v194, 0x3377d1cf, v144
	v_fmac_f32_e32 v194, 0x3f317217, v144
	v_mov_b32_e32 v144, v194
	v_cndmask_b32_e64 v194, 0, v216, s[40:41]
	v_sub_f32_e32 v144, v144, v194
	v_cndmask_b32_e64 v144, v148, v144, s[20:21]
	v_mul_f32_e32 v148, 0x3fb8aa3b, v168
	v_exp_f32_e32 v148, v148
	s_nop 0
	v_fma_f32 v148, v182, v148, v128
	v_cmp_gt_f32_e64 s[40:41], s97, v148
	s_nop 1
	v_cndmask_b32_e64 v194, 0, 32, s[40:41]
	v_ldexp_f32 v148, v148, v194
	v_log_f32_e32 v148, v148
	s_nop 0
	v_mul_f32_e32 v194, 0x3f317217, v148
	v_fma_f32 v194, v148, s52, -v194
	v_fmac_f32_e32 v194, 0x3377d1cf, v148
	v_fmac_f32_e32 v194, 0x3f317217, v148
	v_mov_b32_e32 v148, v194
	v_cndmask_b32_e64 v194, 0, v216, s[40:41]
	v_sub_f32_e32 v148, v148, v194
	v_cndmask_b32_e64 v148, v168, v148, s[18:19]
	v_min_f32_e32 v168, 0, v149
	v_mul_f32_e64 v149, |v149|, s57
	v_exp_f32_e32 v149, v149
	s_nop 0
	v_add_f32_e32 v149, 1.0, v149
	v_log_f32_e32 v149, v149
	s_nop 0
	v_mul_f32_e32 v194, 0x3f317217, v149
	v_fma_f32 v194, v149, s52, -v194
	v_fmac_f32_e32 v194, 0x3377d1cf, v149
	v_fmac_f32_e32 v194, 0x3f317217, v149
	v_mov_b32_e32 v149, v194
	v_sub_f32_e32 v149, v168, v149
	v_min_f32_e32 v168, 0, v145
	v_mul_f32_e64 v145, |v145|, s57
	v_exp_f32_e32 v145, v145
	s_nop 0
	v_add_f32_e32 v145, 1.0, v145
	v_log_f32_e32 v145, v145
	s_nop 0
	v_mul_f32_e32 v194, 0x3f317217, v145
	v_fma_f32 v194, v145, s52, -v194
	v_fmac_f32_e32 v194, 0x3377d1cf, v145
	v_fmac_f32_e32 v194, 0x3f317217, v145
	v_mov_b32_e32 v145, v194
	v_sub_f32_e32 v168, v168, v145
	v_mul_f32_e32 v145, 0x3fb8aa3b, v149
	v_exp_f32_e32 v145, v145
	s_nop 0
	v_fma_f32 v145, v181, v145, v133
	v_cmp_gt_f32_e64 s[40:41], s97, v145
	s_nop 1
	v_cndmask_b32_e64 v194, 0, 32, s[40:41]
	v_ldexp_f32 v145, v145, v194
	v_log_f32_e32 v145, v145
	s_nop 0
	v_mul_f32_e32 v194, 0x3f317217, v145
	v_fma_f32 v194, v145, s52, -v194
	v_fmac_f32_e32 v194, 0x3377d1cf, v145
	v_fmac_f32_e32 v194, 0x3f317217, v145
	v_mov_b32_e32 v145, v194
;     __device__ __forceinline__ void operator()(const f32x4 (&acc)[2][2][4][2], const pg8::Unit& u, int wr, int wc, int fr, int fq) const {
;     ...
;             WIN_LOOP( _Pragma("unroll") for (int i = 0; i < 4; ++i) { const float s0 = fminf(a[i], 0.f) - __logf(1.f + __expf(-fabsf(a[i]))), s1 = fminf(b[i], 0.f) - __logf(1.f + __expf(-fabsf(b[i]))); const float la = l0[bj][i], lbv = l1[bj][i];
;                     a[i] = la > 0.f ? __logf(la + (1.f - la) * __expf(s0)) : s0; b[i] = lbv > 0.f ? __logf(lbv + (1.f - lbv) * __expf(s1)) : s1; }
;                 *(f32x4*)(LF + (size_t)row * 512 + c) = a; *(f32x4*)(LF + (size_t)row * 512 + c + 4) = b; __builtin_amdgcn_sched_barrier(0); ) }
	v_cndmask_b32_e64 v194, 0, v216, s[40:41]
	v_sub_f32_e32 v145, v145, v194
	v_cndmask_b32_e64 v145, v149, v145, s[16:17]
	v_mul_f32_e32 v149, 0x3fb8aa3b, v168
	v_exp_f32_e32 v149, v149
	s_nop 0
	v_fma_f32 v149, v180, v149, v129
	v_cmp_gt_f32_e64 s[40:41], s97, v149
	s_nop 1
	v_cndmask_b32_e64 v194, 0, 32, s[40:41]
	v_ldexp_f32 v149, v149, v194
	v_log_f32_e32 v149, v149
	s_nop 0
	v_mul_f32_e32 v194, 0x3f317217, v149
	v_fma_f32 v194, v149, s52, -v194
	v_fmac_f32_e32 v194, 0x3377d1cf, v149
	v_fmac_f32_e32 v194, 0x3f317217, v149
	v_mov_b32_e32 v149, v194
	v_cndmask_b32_e64 v194, 0, v216, s[40:41]
	v_sub_f32_e32 v149, v149, v194
	v_cndmask_b32_e64 v149, v168, v149, s[14:15]
	v_min_f32_e32 v168, 0, v150
	v_mul_f32_e64 v150, |v150|, s57
	v_exp_f32_e32 v150, v150
	s_nop 0
	v_add_f32_e32 v150, 1.0, v150
	v_log_f32_e32 v150, v150
	s_nop 0
	v_mul_f32_e32 v194, 0x3f317217, v150
	v_fma_f32 v194, v150, s52, -v194
	v_fmac_f32_e32 v194, 0x3377d1cf, v150
	v_fmac_f32_e32 v194, 0x3f317217, v150
	v_mov_b32_e32 v150, v194
	v_sub_f32_e32 v150, v168, v150
	v_min_f32_e32 v168, 0, v146
	v_mul_f32_e64 v146, |v146|, s57
	v_exp_f32_e32 v146, v146
	s_nop 0
	v_add_f32_e32 v146, 1.0, v146
	v_log_f32_e32 v146, v146
	s_nop 0
	v_mul_f32_e32 v194, 0x3f317217, v146
	v_fma_f32 v194, v146, s52, -v194
	v_fmac_f32_e32 v194, 0x3377d1cf, v146
	v_fmac_f32_e32 v194, 0x3f317217, v146
	v_mov_b32_e32 v146, v194
	v_sub_f32_e32 v168, v168, v146
	v_mul_f32_e32 v146, 0x3fb8aa3b, v150
	v_exp_f32_e32 v146, v146
	s_nop 0
	v_fma_f32 v146, v179, v146, v134
	v_cmp_gt_f32_e64 s[40:41], s97, v146
	s_nop 1
	v_cndmask_b32_e64 v194, 0, 32, s[40:41]
	v_ldexp_f32 v146, v146, v194
	v_log_f32_e32 v146, v146
	s_nop 0
	v_mul_f32_e32 v194, 0x3f317217, v146
	v_fma_f32 v194, v146, s52, -v194
	v_fmac_f32_e32 v194, 0x3377d1cf, v146
	v_fmac_f32_e32 v194, 0x3f317217, v146
	v_mov_b32_e32 v146, v194
	v_cndmask_b32_e64 v194, 0, v216, s[40:41]
	v_sub_f32_e32 v146, v146, v194
	v_cndmask_b32_e64 v146, v150, v146, s[12:13]
	v_mul_f32_e32 v150, 0x3fb8aa3b, v168
	v_exp_f32_e32 v150, v150
	s_nop 0
	v_fma_f32 v150, v178, v150, v130
	v_cmp_gt_f32_e64 s[40:41], s97, v150
	s_nop 1
	v_cndmask_b32_e64 v194, 0, 32, s[40:41]
	v_ldexp_f32 v150, v150, v194
	v_log_f32_e32 v150, v150
	s_nop 0
	v_mul_f32_e32 v194, 0x3f317217, v150
	v_fma_f32 v194, v150, s52, -v194
	v_fmac_f32_e32 v194, 0x3377d1cf, v150
	v_fmac_f32_e32 v194, 0x3f317217, v150
	v_mov_b32_e32 v150, v194
	v_cndmask_b32_e64 v194, 0, v216, s[40:41]
	v_sub_f32_e32 v150, v150, v194
	v_cndmask_b32_e64 v150, v168, v150, s[10:11]
	v_min_f32_e32 v168, 0, v151
	v_mul_f32_e64 v151, |v151|, s57
	v_exp_f32_e32 v151, v151
	s_nop 0
	v_add_f32_e32 v151, 1.0, v151
	v_log_f32_e32 v151, v151
	s_nop 0
	v_mul_f32_e32 v194, 0x3f317217, v151
	v_fma_f32 v194, v151, s52, -v194
	v_fmac_f32_e32 v194, 0x3377d1cf, v151
	v_fmac_f32_e32 v194, 0x3f317217, v151
	v_mov_b32_e32 v151, v194
	v_sub_f32_e32 v151, v168, v151
	v_min_f32_e32 v168, 0, v147
	v_mul_f32_e64 v147, |v147|, s57
	v_exp_f32_e32 v147, v147
	s_nop 0
	v_add_f32_e32 v147, 1.0, v147
	v_log_f32_e32 v147, v147
	s_nop 0
	v_mul_f32_e32 v194, 0x3f317217, v147
	v_fma_f32 v194, v147, s52, -v194
	v_fmac_f32_e32 v194, 0x3377d1cf, v147
	v_fmac_f32_e32 v194, 0x3f317217, v147
	v_mov_b32_e32 v147, v194
	v_sub_f32_e32 v168, v168, v147
	v_mul_f32_e32 v147, 0x3fb8aa3b, v151
	v_exp_f32_e32 v147, v147
	s_nop 0
	v_fma_f32 v147, v177, v147, v135
	v_cmp_gt_f32_e64 s[40:41], s97, v147
	s_nop 1
	v_cndmask_b32_e64 v194, 0, 32, s[40:41]
	v_ldexp_f32 v147, v147, v194
	v_log_f32_e32 v147, v147
	s_nop 0
	v_mul_f32_e32 v194, 0x3f317217, v147
	v_fma_f32 v194, v147, s52, -v194
	v_fmac_f32_e32 v194, 0x3377d1cf, v147
	v_fmac_f32_e32 v194, 0x3f317217, v147
	v_mov_b32_e32 v147, v194
	v_cndmask_b32_e64 v194, 0, v216, s[40:41]
	v_sub_f32_e32 v147, v147, v194
	v_cndmask_b32_e64 v147, v151, v147, s[8:9]
	v_mul_f32_e32 v151, 0x3fb8aa3b, v168
	v_exp_f32_e32 v151, v151
	s_nop 0
	v_fma_f32 v151, v167, v151, v131
	v_cmp_gt_f32_e64 s[40:41], s97, v151
	s_nop 1
	v_cndmask_b32_e64 v194, 0, 32, s[40:41]
	v_ldexp_f32 v151, v151, v194
	v_log_f32_e32 v151, v151
	s_nop 0
	v_mul_f32_e32 v194, 0x3f317217, v151
	v_fma_f32 v194, v151, s52, -v194
	v_fmac_f32_e32 v194, 0x3377d1cf, v151
	v_fmac_f32_e32 v194, 0x3f317217, v151
	v_mov_b32_e32 v151, v194
	v_cndmask_b32_e64 v194, 0, v216, s[40:41]
	v_sub_f32_e32 v151, v151, v194
	v_cndmask_b32_e32 v151, v168, v151, vcc
	global_store_dwordx4 v[170:171], v[144:147], off offset:512
	global_store_dwordx4 v[170:171], v[148:151], off offset:528
	s_nop 1
	v_or_b32_e32 v148, 48, v166
	v_ashrrev_i32_e32 v149, 31, v148
	v_lshlrev_b64 v[144:145], 6, v[148:149]
	v_lshl_add_u64 v[144:145], v[160:161], 0, v[144:145]
	s_nop 0
	s_waitcnt lgkmcnt(0)
	s_nop 3
	s_nop 0
	s_nop 1
	s_waitcnt lgkmcnt(0)
	s_nop 1
	s_waitcnt lgkmcnt(0)
; __device__ __forceinline__ float silu_f(float x) { return x * __builtin_amdgcn_rcpf(1.f + __expf(-x)); }
; __device__ __forceinline__ v4u pack8(const f32x4 a, const f32x4 b) { v4u w; w.x = cvt_pk_bf16(a[0], a[1]); w.y = cvt_pk_bf16(a[2], a[3]); w.z = cvt_pk_bf16(b[0], b[1]); w.w = cvt_pk_bf16(b[2], b[3]); return w; }
;     __device__ __forceinline__ void operator()(const f32x4 (&acc)[2][2][4][2], const pg8::Unit& u, int wr, int wc, int fr, int fq) const {
;     ...
;         if (grp == 0) { WIN_LOOP( _Pragma("unroll") for (int i = 0; i < 4; ++i) { a[i] = silu_f(a[i]); b[i] = silu_f(b[i]); } *(v4u*)(QO + (size_t)row * DM + c) = pack8(a, b); ) }
;         else if (grp == 3) { WIN_LOOP( _Pragma("unroll") for (int i = 0; i < 4; ++i) { a[i] = silu_f(a[i]); b[i] = silu_f(b[i]); } *(v4u*)(GH + (size_t)row * 512 + c) = pack8(a, b); ) }
;         else if (grp == 1) {
;             f32x4 l0[2], l1[2];
; #pragma unroll
;             for (int bj = 0; bj < 2; ++bj) { l0[bj] = *(const f32x4*)(lb + cb + bj * 128); l1[bj] = *(const f32x4*)(lb + cb + bj * 128 + 4); }
;             WIN_LOOP( _Pragma("unroll") for (int i = 0; i < 4; ++i) { const float s0 = fminf(a[i], 0.f) - __logf(1.f + __expf(-fabsf(a[i]))), s1 = fminf(b[i], 0.f) - __logf(1.f + __expf(-fabsf(b[i]))); const float la = l0[bj][i], lbv = l1[bj][i];
;                     a[i] = la > 0.f ? __logf(la + (1.f - la) * __expf(s0)) : s0; b[i] = lbv > 0.f ? __logf(lbv + (1.f - lbv) * __expf(s1)) : s1; }
;                 *(f32x4*)(LF + (size_t)row * 512 + c) = a; *(f32x4*)(LF + (size_t)row * 512 + c + 4) = b; __builtin_amdgcn_sched_barrier(0); ) }
	s_nop 1
	v_mov_b32_e32 v168, v253
	v_lshlrev_b64 v[144:145], 11, v[148:149]
	v_lshl_add_u64 v[170:171], s[50:51], 0, v[144:145]
	v_lshl_add_u64 v[170:171], v[170:171], 0, v[192:193]
	v_pk_mul_f32 v[148:149], v[36:37], v[168:169] op_sel_hi:[1,0]
	v_pk_mul_f32 v[144:145], v[32:33], v[168:169] op_sel_hi:[1,0]
	v_min_f32_e32 v194, 0, v148
	v_mul_f32_e64 v148, |v148|, s57
	v_exp_f32_e32 v148, v148
	v_pk_mul_f32 v[150:151], v[38:39], v[168:169] op_sel_hi:[1,0]
	v_pk_mul_f32 v[146:147], v[34:35], v[168:169] op_sel_hi:[1,0]
	v_add_f32_e32 v148, 1.0, v148
	v_log_f32_e32 v148, v148
	s_nop 0
	v_mul_f32_e32 v195, 0x3f317217, v148
	v_fma_f32 v195, v148, s52, -v195
	v_fmac_f32_e32 v195, 0x3377d1cf, v148
	v_fmac_f32_e32 v195, 0x3f317217, v148
	v_mov_b32_e32 v148, v195
	v_sub_f32_e32 v148, v194, v148
	v_min_f32_e32 v194, 0, v144
	v_mul_f32_e64 v144, |v144|, s57
	v_exp_f32_e32 v144, v144
	s_nop 0
	v_add_f32_e32 v144, 1.0, v144
	v_log_f32_e32 v144, v144
	s_nop 0
	v_mul_f32_e32 v195, 0x3f317217, v144
	v_fma_f32 v195, v144, s52, -v195
	v_fmac_f32_e32 v195, 0x3377d1cf, v144
	v_fmac_f32_e32 v195, 0x3f317217, v144
	v_mov_b32_e32 v144, v195
	v_sub_f32_e32 v194, v194, v144
	v_mul_f32_e32 v144, 0x3fb8aa3b, v148
	v_exp_f32_e32 v144, v144
	s_nop 0
	v_fma_f32 v144, v190, v144, v140
	v_cmp_gt_f32_e64 s[40:41], s97, v144
	s_nop 1
	v_cndmask_b32_e64 v195, 0, 32, s[40:41]
	v_ldexp_f32 v144, v144, v195
	v_log_f32_e32 v144, v144
	s_nop 0
	v_mul_f32_e32 v195, 0x3f317217, v144
	v_fma_f32 v195, v144, s52, -v195
	v_fmac_f32_e32 v195, 0x3377d1cf, v144
	v_fmac_f32_e32 v195, 0x3f317217, v144
	v_mov_b32_e32 v144, v195
	v_cndmask_b32_e64 v195, 0, v216, s[40:41]
	v_sub_f32_e32 v144, v144, v195
	v_cndmask_b32_e64 v144, v148, v144, s[38:39]
	v_mul_f32_e32 v148, 0x3fb8aa3b, v194
	v_exp_f32_e32 v148, v148
	s_nop 0
	v_fma_f32 v148, v191, v148, v136
	v_cmp_gt_f32_e64 s[40:41], s97, v148
	s_nop 1
	v_cndmask_b32_e64 v195, 0, 32, s[40:41]
	v_ldexp_f32 v148, v148, v195
	v_log_f32_e32 v148, v148
	s_nop 0
	v_mul_f32_e32 v195, 0x3f317217, v148
	v_fma_f32 v195, v148, s52, -v195
	v_fmac_f32_e32 v195, 0x3377d1cf, v148
	v_fmac_f32_e32 v195, 0x3f317217, v148
	v_mov_b32_e32 v148, v195
	v_cndmask_b32_e64 v195, 0, v216, s[40:41]
	v_sub_f32_e32 v148, v148, v195
	v_cndmask_b32_e64 v148, v194, v148, s[36:37]
	v_min_f32_e32 v194, 0, v149
	v_mul_f32_e64 v149, |v149|, s57
	v_exp_f32_e32 v149, v149
	s_nop 0
	v_add_f32_e32 v149, 1.0, v149
	v_log_f32_e32 v149, v149
	s_nop 0
	v_mul_f32_e32 v195, 0x3f317217, v149
	v_fma_f32 v195, v149, s52, -v195
	v_fmac_f32_e32 v195, 0x3377d1cf, v149
	v_fmac_f32_e32 v195, 0x3f317217, v149
	v_mov_b32_e32 v149, v195
	v_sub_f32_e32 v149, v194, v149
	v_min_f32_e32 v194, 0, v145
	v_mul_f32_e64 v145, |v145|, s57
	v_exp_f32_e32 v145, v145
	s_nop 0
	v_add_f32_e32 v145, 1.0, v145
	v_log_f32_e32 v145, v145
	s_nop 0
	v_mul_f32_e32 v195, 0x3f317217, v145
	v_fma_f32 v195, v145, s52, -v195
	v_fmac_f32_e32 v195, 0x3377d1cf, v145
	v_fmac_f32_e32 v195, 0x3f317217, v145
	v_mov_b32_e32 v145, v195
	v_sub_f32_e32 v194, v194, v145
	v_mul_f32_e32 v145, 0x3fb8aa3b, v149
	v_exp_f32_e32 v145, v145
	s_nop 0
	v_fma_f32 v145, v188, v145, v141
	v_cmp_gt_f32_e64 s[40:41], s97, v145
	s_nop 1
	v_cndmask_b32_e64 v195, 0, 32, s[40:41]
	v_ldexp_f32 v145, v145, v195
	v_log_f32_e32 v145, v145
	s_nop 0
	v_mul_f32_e32 v195, 0x3f317217, v145
	v_fma_f32 v195, v145, s52, -v195
	v_fmac_f32_e32 v195, 0x3377d1cf, v145
	v_fmac_f32_e32 v195, 0x3f317217, v145
	v_mov_b32_e32 v145, v195
	v_cndmask_b32_e64 v195, 0, v216, s[40:41]
	v_sub_f32_e32 v145, v145, v195
	v_cndmask_b32_e64 v145, v149, v145, s[34:35]
	v_mul_f32_e32 v149, 0x3fb8aa3b, v194
	v_exp_f32_e32 v149, v149
	s_nop 0
	v_fma_f32 v149, v189, v149, v137
	v_cmp_gt_f32_e64 s[40:41], s97, v149
	s_nop 1
	v_cndmask_b32_e64 v195, 0, 32, s[40:41]
	v_ldexp_f32 v149, v149, v195
	v_log_f32_e32 v149, v149
	s_nop 0
	v_mul_f32_e32 v195, 0x3f317217, v149
	v_fma_f32 v195, v149, s52, -v195
	v_fmac_f32_e32 v195, 0x3377d1cf, v149
	v_fmac_f32_e32 v195, 0x3f317217, v149
	v_mov_b32_e32 v149, v195
	v_cndmask_b32_e64 v195, 0, v216, s[40:41]
	v_sub_f32_e32 v149, v149, v195
	v_cndmask_b32_e64 v149, v194, v149, s[30:31]
	v_min_f32_e32 v194, 0, v150
	v_mul_f32_e64 v150, |v150|, s57
	v_exp_f32_e32 v150, v150
	s_nop 0
	v_add_f32_e32 v150, 1.0, v150
	v_log_f32_e32 v150, v150
	s_nop 0
	v_mul_f32_e32 v195, 0x3f317217, v150
	v_fma_f32 v195, v150, s52, -v195
	v_fmac_f32_e32 v195, 0x3377d1cf, v150
	v_fmac_f32_e32 v195, 0x3f317217, v150
	v_mov_b32_e32 v150, v195
	v_sub_f32_e32 v150, v194, v150
	v_min_f32_e32 v194, 0, v146
	v_mul_f32_e64 v146, |v146|, s57
	v_exp_f32_e32 v146, v146
	s_nop 0
	v_add_f32_e32 v146, 1.0, v146
	v_log_f32_e32 v146, v146
	s_nop 0
	v_mul_f32_e32 v195, 0x3f317217, v146
	v_fma_f32 v195, v146, s52, -v195
	v_fmac_f32_e32 v195, 0x3377d1cf, v146
	v_fmac_f32_e32 v195, 0x3f317217, v146
	v_mov_b32_e32 v146, v195
	v_sub_f32_e32 v194, v194, v146
	v_mul_f32_e32 v146, 0x3fb8aa3b, v150
	v_exp_f32_e32 v146, v146
	s_nop 0
	v_fma_f32 v146, v187, v146, v142
	v_cmp_gt_f32_e64 s[40:41], s97, v146
	s_nop 1
	v_cndmask_b32_e64 v195, 0, 32, s[40:41]
	v_ldexp_f32 v146, v146, v195
	v_log_f32_e32 v146, v146
	s_nop 0
	v_mul_f32_e32 v195, 0x3f317217, v146
	v_fma_f32 v195, v146, s52, -v195
	v_fmac_f32_e32 v195, 0x3377d1cf, v146
	v_fmac_f32_e32 v195, 0x3f317217, v146
	v_mov_b32_e32 v146, v195
	v_cndmask_b32_e64 v195, 0, v216, s[40:41]
	v_sub_f32_e32 v146, v146, v195
	v_cndmask_b32_e64 v146, v150, v146, s[28:29]
	v_mul_f32_e32 v150, 0x3fb8aa3b, v194
	v_exp_f32_e32 v150, v150
	s_nop 0
	v_fma_f32 v150, v186, v150, v138
	v_cmp_gt_f32_e64 s[40:41], s97, v150
	s_nop 1
	v_cndmask_b32_e64 v195, 0, 32, s[40:41]
; __device__ __forceinline__ float silu_f(float x) { return x * __builtin_amdgcn_rcpf(1.f + __expf(-x)); }
; __device__ __forceinline__ v4u pack8(const f32x4 a, const f32x4 b) { v4u w; w.x = cvt_pk_bf16(a[0], a[1]); w.y = cvt_pk_bf16(a[2], a[3]); w.z = cvt_pk_bf16(b[0], b[1]); w.w = cvt_pk_bf16(b[2], b[3]); return w; }
;     __device__ __forceinline__ void operator()(const f32x4 (&acc)[2][2][4][2], const pg8::Unit& u, int wr, int wc, int fr, int fq) const {
;     ...
;         if (grp == 0) { WIN_LOOP( _Pragma("unroll") for (int i = 0; i < 4; ++i) { a[i] = silu_f(a[i]); b[i] = silu_f(b[i]); } *(v4u*)(QO + (size_t)row * DM + c) = pack8(a, b); ) }
;         else if (grp == 3) { WIN_LOOP( _Pragma("unroll") for (int i = 0; i < 4; ++i) { a[i] = silu_f(a[i]); b[i] = silu_f(b[i]); } *(v4u*)(GH + (size_t)row * 512 + c) = pack8(a, b); ) }
;         else if (grp == 1) {
;             f32x4 l0[2], l1[2];
; #pragma unroll
;             for (int bj = 0; bj < 2; ++bj) { l0[bj] = *(const f32x4*)(lb + cb + bj * 128); l1[bj] = *(const f32x4*)(lb + cb + bj * 128 + 4); }
;             WIN_LOOP( _Pragma("unroll") for (int i = 0; i < 4; ++i) { const float s0 = fminf(a[i], 0.f) - __logf(1.f + __expf(-fabsf(a[i]))), s1 = fminf(b[i], 0.f) - __logf(1.f + __expf(-fabsf(b[i]))); const float la = l0[bj][i], lbv = l1[bj][i];
;                     a[i] = la > 0.f ? __logf(la + (1.f - la) * __expf(s0)) : s0; b[i] = lbv > 0.f ? __logf(lbv + (1.f - lbv) * __expf(s1)) : s1; }
;                 *(f32x4*)(LF + (size_t)row * 512 + c) = a; *(f32x4*)(LF + (size_t)row * 512 + c + 4) = b; __builtin_amdgcn_sched_barrier(0); ) }
	v_ldexp_f32 v150, v150, v195
	v_log_f32_e32 v150, v150
	s_nop 0
	v_mul_f32_e32 v195, 0x3f317217, v150
	v_fma_f32 v195, v150, s52, -v195
	v_fmac_f32_e32 v195, 0x3377d1cf, v150
	v_fmac_f32_e32 v195, 0x3f317217, v150
	v_mov_b32_e32 v150, v195
	v_cndmask_b32_e64 v195, 0, v216, s[40:41]
	v_sub_f32_e32 v150, v150, v195
	v_cndmask_b32_e64 v150, v194, v150, s[26:27]
	v_min_f32_e32 v194, 0, v151
	v_mul_f32_e64 v151, |v151|, s57
	v_exp_f32_e32 v151, v151
	s_nop 0
	v_add_f32_e32 v151, 1.0, v151
	v_log_f32_e32 v151, v151
	s_nop 0
	v_mul_f32_e32 v195, 0x3f317217, v151
	v_fma_f32 v195, v151, s52, -v195
	v_fmac_f32_e32 v195, 0x3377d1cf, v151
	v_fmac_f32_e32 v195, 0x3f317217, v151
	v_mov_b32_e32 v151, v195
	v_sub_f32_e32 v151, v194, v151
	v_min_f32_e32 v194, 0, v147
	v_mul_f32_e64 v147, |v147|, s57
	v_exp_f32_e32 v147, v147
	s_nop 0
	v_add_f32_e32 v147, 1.0, v147
	v_log_f32_e32 v147, v147
	s_nop 0
	v_mul_f32_e32 v195, 0x3f317217, v147
	v_fma_f32 v195, v147, s52, -v195
	v_fmac_f32_e32 v195, 0x3377d1cf, v147
	v_fmac_f32_e32 v195, 0x3f317217, v147
	v_mov_b32_e32 v147, v195
	v_sub_f32_e32 v194, v194, v147
	v_mul_f32_e32 v147, 0x3fb8aa3b, v151
	v_exp_f32_e32 v147, v147
	s_nop 0
	v_fma_f32 v147, v185, v147, v143
	v_cmp_gt_f32_e64 s[40:41], s97, v147
	s_nop 1
	v_cndmask_b32_e64 v195, 0, 32, s[40:41]
	v_ldexp_f32 v147, v147, v195
	v_log_f32_e32 v147, v147
	s_nop 0
	v_mul_f32_e32 v195, 0x3f317217, v147
	v_fma_f32 v195, v147, s52, -v195
	v_fmac_f32_e32 v195, 0x3377d1cf, v147
	v_fmac_f32_e32 v195, 0x3f317217, v147
	v_mov_b32_e32 v147, v195
	v_cndmask_b32_e64 v195, 0, v216, s[40:41]
	v_sub_f32_e32 v147, v147, v195
	v_cndmask_b32_e64 v147, v151, v147, s[24:25]
	v_mul_f32_e32 v151, 0x3fb8aa3b, v194
	v_exp_f32_e32 v151, v151
	s_nop 0
	v_fma_f32 v151, v184, v151, v139
	v_cmp_gt_f32_e64 s[40:41], s97, v151
	s_nop 1
	v_cndmask_b32_e64 v195, 0, 32, s[40:41]
	v_ldexp_f32 v151, v151, v195
	v_log_f32_e32 v151, v151
	s_nop 0
	v_mul_f32_e32 v195, 0x3f317217, v151
	v_fma_f32 v195, v151, s52, -v195
	v_fmac_f32_e32 v195, 0x3377d1cf, v151
	v_fmac_f32_e32 v195, 0x3f317217, v151
	v_mov_b32_e32 v151, v195
	v_cndmask_b32_e64 v195, 0, v216, s[40:41]
	v_sub_f32_e32 v151, v151, v195
	v_cndmask_b32_e64 v151, v194, v151, s[22:23]
	global_store_dwordx4 v[170:171], v[144:147], off
	global_store_dwordx4 v[170:171], v[148:151], off offset:16
	s_nop 1
	v_pk_mul_f32 v[148:149], v[100:101], v[168:169] op_sel_hi:[1,0]
	v_pk_mul_f32 v[150:151], v[102:103], v[168:169] op_sel_hi:[1,0]
	v_pk_mul_f32 v[146:147], v[98:99], v[168:169] op_sel_hi:[1,0]
	v_pk_mul_f32 v[144:145], v[96:97], v[168:169] op_sel_hi:[1,0]
	v_min_f32_e32 v168, 0, v148
	v_mul_f32_e64 v148, |v148|, s57
	v_exp_f32_e32 v148, v148
	s_nop 0
	v_add_f32_e32 v148, 1.0, v148
	v_log_f32_e32 v148, v148
	s_nop 0
	v_mul_f32_e32 v194, 0x3f317217, v148
	v_fma_f32 v194, v148, s52, -v194
	v_fmac_f32_e32 v194, 0x3377d1cf, v148
	v_fmac_f32_e32 v194, 0x3f317217, v148
	v_mov_b32_e32 v148, v194
	v_sub_f32_e32 v148, v168, v148
	v_min_f32_e32 v168, 0, v144
	v_mul_f32_e64 v144, |v144|, s57
	v_exp_f32_e32 v144, v144
	s_nop 0
	v_add_f32_e32 v144, 1.0, v144
	v_log_f32_e32 v144, v144
	s_nop 0
	v_mul_f32_e32 v194, 0x3f317217, v144
	v_fma_f32 v194, v144, s52, -v194
	v_fmac_f32_e32 v194, 0x3377d1cf, v144
	v_fmac_f32_e32 v194, 0x3f317217, v144
	v_mov_b32_e32 v144, v194
	v_sub_f32_e32 v168, v168, v144
	v_mul_f32_e32 v144, 0x3fb8aa3b, v148
	v_exp_f32_e32 v144, v144
	s_nop 0
	v_fma_f32 v144, v183, v144, v132
	v_cmp_gt_f32_e64 s[40:41], s97, v144
	s_nop 1
	v_cndmask_b32_e64 v194, 0, 32, s[40:41]
	v_ldexp_f32 v144, v144, v194
	v_log_f32_e32 v144, v144
	s_nop 0
	v_mul_f32_e32 v194, 0x3f317217, v144
	v_fma_f32 v194, v144, s52, -v194
	v_fmac_f32_e32 v194, 0x3377d1cf, v144
	v_fmac_f32_e32 v194, 0x3f317217, v144
	v_mov_b32_e32 v144, v194
	v_cndmask_b32_e64 v194, 0, v216, s[40:41]
	v_sub_f32_e32 v144, v144, v194
	v_cndmask_b32_e64 v144, v148, v144, s[20:21]
	v_mul_f32_e32 v148, 0x3fb8aa3b, v168
	v_exp_f32_e32 v148, v148
	s_nop 0
	v_fma_f32 v148, v182, v148, v128
	v_cmp_gt_f32_e64 s[40:41], s97, v148
	s_nop 1
	v_cndmask_b32_e64 v194, 0, 32, s[40:41]
	v_ldexp_f32 v148, v148, v194
	v_log_f32_e32 v148, v148
	s_nop 0
	v_mul_f32_e32 v194, 0x3f317217, v148
	v_fma_f32 v194, v148, s52, -v194
	v_fmac_f32_e32 v194, 0x3377d1cf, v148
	v_fmac_f32_e32 v194, 0x3f317217, v148
	v_mov_b32_e32 v148, v194
	v_cndmask_b32_e64 v194, 0, v216, s[40:41]
	v_sub_f32_e32 v148, v148, v194
	v_cndmask_b32_e64 v148, v168, v148, s[18:19]
	v_min_f32_e32 v168, 0, v149
	v_mul_f32_e64 v149, |v149|, s57
	v_exp_f32_e32 v149, v149
	s_nop 0
	v_add_f32_e32 v149, 1.0, v149
	v_log_f32_e32 v149, v149
	s_nop 0
	v_mul_f32_e32 v194, 0x3f317217, v149
	v_fma_f32 v194, v149, s52, -v194
	v_fmac_f32_e32 v194, 0x3377d1cf, v149
	v_fmac_f32_e32 v194, 0x3f317217, v149
	v_mov_b32_e32 v149, v194
	v_sub_f32_e32 v149, v168, v149
	v_min_f32_e32 v168, 0, v145
	v_mul_f32_e64 v145, |v145|, s57
	v_exp_f32_e32 v145, v145
	s_nop 0
	v_add_f32_e32 v145, 1.0, v145
	v_log_f32_e32 v145, v145
	s_nop 0
	v_mul_f32_e32 v194, 0x3f317217, v145
	v_fma_f32 v194, v145, s52, -v194
	v_fmac_f32_e32 v194, 0x3377d1cf, v145
	v_fmac_f32_e32 v194, 0x3f317217, v145
	v_mov_b32_e32 v145, v194
	v_sub_f32_e32 v168, v168, v145
	v_mul_f32_e32 v145, 0x3fb8aa3b, v149
	v_exp_f32_e32 v145, v145
	s_nop 0
	v_fma_f32 v145, v181, v145, v133
	v_cmp_gt_f32_e64 s[40:41], s97, v145
	s_nop 1
	v_cndmask_b32_e64 v194, 0, 32, s[40:41]
	v_ldexp_f32 v145, v145, v194
	v_log_f32_e32 v145, v145
	s_nop 0
	v_mul_f32_e32 v194, 0x3f317217, v145
	v_fma_f32 v194, v145, s52, -v194
	v_fmac_f32_e32 v194, 0x3377d1cf, v145
	v_fmac_f32_e32 v194, 0x3f317217, v145
	v_mov_b32_e32 v145, v194
;     __device__ __forceinline__ void operator()(const f32x4 (&acc)[2][2][4][2], const pg8::Unit& u, int wr, int wc, int fr, int fq) const {
;     ...
;             WIN_LOOP( _Pragma("unroll") for (int i = 0; i < 4; ++i) { const float s0 = fminf(a[i], 0.f) - __logf(1.f + __expf(-fabsf(a[i]))), s1 = fminf(b[i], 0.f) - __logf(1.f + __expf(-fabsf(b[i]))); const float la = l0[bj][i], lbv = l1[bj][i];
;                     a[i] = la > 0.f ? __logf(la + (1.f - la) * __expf(s0)) : s0; b[i] = lbv > 0.f ? __logf(lbv + (1.f - lbv) * __expf(s1)) : s1; }
;                 *(f32x4*)(LF + (size_t)row * 512 + c) = a; *(f32x4*)(LF + (size_t)row * 512 + c + 4) = b; __builtin_amdgcn_sched_barrier(0); ) }
	v_cndmask_b32_e64 v194, 0, v216, s[40:41]
	v_sub_f32_e32 v145, v145, v194
	v_cndmask_b32_e64 v145, v149, v145, s[16:17]
	v_mul_f32_e32 v149, 0x3fb8aa3b, v168
	v_exp_f32_e32 v149, v149
	s_nop 0
	v_fma_f32 v149, v180, v149, v129
	v_cmp_gt_f32_e64 s[40:41], s97, v149
	s_nop 1
	v_cndmask_b32_e64 v194, 0, 32, s[40:41]
	v_ldexp_f32 v149, v149, v194
	v_log_f32_e32 v149, v149
	s_nop 0
	v_mul_f32_e32 v194, 0x3f317217, v149
	v_fma_f32 v194, v149, s52, -v194
	v_fmac_f32_e32 v194, 0x3377d1cf, v149
	v_fmac_f32_e32 v194, 0x3f317217, v149
	v_mov_b32_e32 v149, v194
	v_cndmask_b32_e64 v194, 0, v216, s[40:41]
	v_sub_f32_e32 v149, v149, v194
	v_cndmask_b32_e64 v149, v168, v149, s[14:15]
	v_min_f32_e32 v168, 0, v150
	v_mul_f32_e64 v150, |v150|, s57
	v_exp_f32_e32 v150, v150
	s_nop 0
	v_add_f32_e32 v150, 1.0, v150
	v_log_f32_e32 v150, v150
	s_nop 0
	v_mul_f32_e32 v194, 0x3f317217, v150
	v_fma_f32 v194, v150, s52, -v194
	v_fmac_f32_e32 v194, 0x3377d1cf, v150
	v_fmac_f32_e32 v194, 0x3f317217, v150
	v_mov_b32_e32 v150, v194
	v_sub_f32_e32 v150, v168, v150
	v_min_f32_e32 v168, 0, v146
	v_mul_f32_e64 v146, |v146|, s57
	v_exp_f32_e32 v146, v146
	s_nop 0
	v_add_f32_e32 v146, 1.0, v146
	v_log_f32_e32 v146, v146
	s_nop 0
	v_mul_f32_e32 v194, 0x3f317217, v146
	v_fma_f32 v194, v146, s52, -v194
	v_fmac_f32_e32 v194, 0x3377d1cf, v146
	v_fmac_f32_e32 v194, 0x3f317217, v146
	v_mov_b32_e32 v146, v194
	v_sub_f32_e32 v168, v168, v146
	v_mul_f32_e32 v146, 0x3fb8aa3b, v150
	v_exp_f32_e32 v146, v146
	s_nop 0
	v_fma_f32 v146, v179, v146, v134
	v_cmp_gt_f32_e64 s[40:41], s97, v146
	s_nop 1
	v_cndmask_b32_e64 v194, 0, 32, s[40:41]
	v_ldexp_f32 v146, v146, v194
	v_log_f32_e32 v146, v146
	s_nop 0
	v_mul_f32_e32 v194, 0x3f317217, v146
	v_fma_f32 v194, v146, s52, -v194
	v_fmac_f32_e32 v194, 0x3377d1cf, v146
	v_fmac_f32_e32 v194, 0x3f317217, v146
	v_mov_b32_e32 v146, v194
	v_cndmask_b32_e64 v194, 0, v216, s[40:41]
	v_sub_f32_e32 v146, v146, v194
	v_cndmask_b32_e64 v146, v150, v146, s[12:13]
	v_mul_f32_e32 v150, 0x3fb8aa3b, v168
	v_exp_f32_e32 v150, v150
	s_nop 0
	v_fma_f32 v150, v178, v150, v130
	v_cmp_gt_f32_e64 s[40:41], s97, v150
	s_nop 1
	v_cndmask_b32_e64 v194, 0, 32, s[40:41]
	v_ldexp_f32 v150, v150, v194
	v_log_f32_e32 v150, v150
	s_nop 0
	v_mul_f32_e32 v194, 0x3f317217, v150
	v_fma_f32 v194, v150, s52, -v194
	v_fmac_f32_e32 v194, 0x3377d1cf, v150
	v_fmac_f32_e32 v194, 0x3f317217, v150
	v_mov_b32_e32 v150, v194
	v_cndmask_b32_e64 v194, 0, v216, s[40:41]
	v_sub_f32_e32 v150, v150, v194
	v_cndmask_b32_e64 v150, v168, v150, s[10:11]
	v_min_f32_e32 v168, 0, v151
	v_mul_f32_e64 v151, |v151|, s57
	v_exp_f32_e32 v151, v151
	s_nop 0
	v_add_f32_e32 v151, 1.0, v151
	v_log_f32_e32 v151, v151
	s_nop 0
	v_mul_f32_e32 v194, 0x3f317217, v151
	v_fma_f32 v194, v151, s52, -v194
	v_fmac_f32_e32 v194, 0x3377d1cf, v151
	v_fmac_f32_e32 v194, 0x3f317217, v151
	v_mov_b32_e32 v151, v194
	v_sub_f32_e32 v151, v168, v151
	v_min_f32_e32 v168, 0, v147
	v_mul_f32_e64 v147, |v147|, s57
	v_exp_f32_e32 v147, v147
	s_nop 0
	v_add_f32_e32 v147, 1.0, v147
	v_log_f32_e32 v147, v147
	s_nop 0
	v_mul_f32_e32 v194, 0x3f317217, v147
	v_fma_f32 v194, v147, s52, -v194
	v_fmac_f32_e32 v194, 0x3377d1cf, v147
	v_fmac_f32_e32 v194, 0x3f317217, v147
	v_mov_b32_e32 v147, v194
	v_sub_f32_e32 v168, v168, v147
	v_mul_f32_e32 v147, 0x3fb8aa3b, v151
	v_exp_f32_e32 v147, v147
	s_nop 0
	v_fma_f32 v147, v177, v147, v135
	v_cmp_gt_f32_e64 s[40:41], s97, v147
	s_nop 1
	v_cndmask_b32_e64 v194, 0, 32, s[40:41]
	v_ldexp_f32 v147, v147, v194
	v_log_f32_e32 v147, v147
	s_nop 0
	v_mul_f32_e32 v194, 0x3f317217, v147
	v_fma_f32 v194, v147, s52, -v194
	v_fmac_f32_e32 v194, 0x3377d1cf, v147
	v_fmac_f32_e32 v194, 0x3f317217, v147
	v_mov_b32_e32 v147, v194
	v_cndmask_b32_e64 v194, 0, v216, s[40:41]
	v_sub_f32_e32 v147, v147, v194
	v_cndmask_b32_e64 v147, v151, v147, s[8:9]
	v_mul_f32_e32 v151, 0x3fb8aa3b, v168
	v_exp_f32_e32 v151, v151
	s_nop 0
	v_fma_f32 v151, v167, v151, v131
	v_cmp_gt_f32_e64 s[40:41], s97, v151
	s_nop 1
	v_cndmask_b32_e64 v194, 0, 32, s[40:41]
	v_ldexp_f32 v151, v151, v194
	v_log_f32_e32 v151, v151
	s_nop 0
	v_mul_f32_e32 v194, 0x3f317217, v151
	v_fma_f32 v194, v151, s52, -v194
	v_fmac_f32_e32 v194, 0x3377d1cf, v151
	v_fmac_f32_e32 v194, 0x3f317217, v151
	v_mov_b32_e32 v151, v194
	v_cndmask_b32_e64 v194, 0, v216, s[40:41]
	v_sub_f32_e32 v151, v151, v194
	v_cndmask_b32_e32 v151, v168, v151, vcc
	global_store_dwordx4 v[170:171], v[144:147], off offset:512
	global_store_dwordx4 v[170:171], v[148:151], off offset:528
	s_nop 1
	v_add_u32_e32 v148, 0x80, v166
	v_ashrrev_i32_e32 v149, 31, v148
	v_lshlrev_b64 v[144:145], 6, v[148:149]
	v_lshl_add_u64 v[144:145], v[160:161], 0, v[144:145]
	s_nop 0
	s_waitcnt lgkmcnt(0)
	s_nop 3
	s_nop 0
	s_nop 1
	s_waitcnt lgkmcnt(0)
	s_nop 1
	s_waitcnt lgkmcnt(0)
; __device__ __forceinline__ float silu_f(float x) { return x * __builtin_amdgcn_rcpf(1.f + __expf(-x)); }
; __device__ __forceinline__ v4u pack8(const f32x4 a, const f32x4 b) { v4u w; w.x = cvt_pk_bf16(a[0], a[1]); w.y = cvt_pk_bf16(a[2], a[3]); w.z = cvt_pk_bf16(b[0], b[1]); w.w = cvt_pk_bf16(b[2], b[3]); return w; }
;     __device__ __forceinline__ void operator()(const f32x4 (&acc)[2][2][4][2], const pg8::Unit& u, int wr, int wc, int fr, int fq) const {
;     ...
;         if (grp == 0) { WIN_LOOP( _Pragma("unroll") for (int i = 0; i < 4; ++i) { a[i] = silu_f(a[i]); b[i] = silu_f(b[i]); } *(v4u*)(QO + (size_t)row * DM + c) = pack8(a, b); ) }
;         else if (grp == 3) { WIN_LOOP( _Pragma("unroll") for (int i = 0; i < 4; ++i) { a[i] = silu_f(a[i]); b[i] = silu_f(b[i]); } *(v4u*)(GH + (size_t)row * 512 + c) = pack8(a, b); ) }
;         else if (grp == 1) {
;             f32x4 l0[2], l1[2];
; #pragma unroll
;             for (int bj = 0; bj < 2; ++bj) { l0[bj] = *(const f32x4*)(lb + cb + bj * 128); l1[bj] = *(const f32x4*)(lb + cb + bj * 128 + 4); }
;             WIN_LOOP( _Pragma("unroll") for (int i = 0; i < 4; ++i) { const float s0 = fminf(a[i], 0.f) - __logf(1.f + __expf(-fabsf(a[i]))), s1 = fminf(b[i], 0.f) - __logf(1.f + __expf(-fabsf(b[i]))); const float la = l0[bj][i], lbv = l1[bj][i];
;                     a[i] = la > 0.f ? __logf(la + (1.f - la) * __expf(s0)) : s0; b[i] = lbv > 0.f ? __logf(lbv + (1.f - lbv) * __expf(s1)) : s1; }
;                 *(f32x4*)(LF + (size_t)row * 512 + c) = a; *(f32x4*)(LF + (size_t)row * 512 + c + 4) = b; __builtin_amdgcn_sched_barrier(0); ) }
	s_nop 1
	v_mov_b32_e32 v168, v254
	v_lshlrev_b64 v[144:145], 11, v[148:149]
	v_lshl_add_u64 v[170:171], s[50:51], 0, v[144:145]
	v_lshl_add_u64 v[170:171], v[170:171], 0, v[192:193]
	v_pk_mul_f32 v[148:149], v[28:29], v[168:169] op_sel_hi:[1,0]
	v_pk_mul_f32 v[144:145], v[24:25], v[168:169] op_sel_hi:[1,0]
	v_min_f32_e32 v194, 0, v148
	v_mul_f32_e64 v148, |v148|, s57
	v_exp_f32_e32 v148, v148
	v_pk_mul_f32 v[150:151], v[30:31], v[168:169] op_sel_hi:[1,0]
	v_pk_mul_f32 v[146:147], v[26:27], v[168:169] op_sel_hi:[1,0]
	v_add_f32_e32 v148, 1.0, v148
	v_log_f32_e32 v148, v148
	s_nop 0
	v_mul_f32_e32 v195, 0x3f317217, v148
	v_fma_f32 v195, v148, s52, -v195
	v_fmac_f32_e32 v195, 0x3377d1cf, v148
	v_fmac_f32_e32 v195, 0x3f317217, v148
	v_mov_b32_e32 v148, v195
	v_sub_f32_e32 v148, v194, v148
	v_min_f32_e32 v194, 0, v144
	v_mul_f32_e64 v144, |v144|, s57
	v_exp_f32_e32 v144, v144
	s_nop 0
	v_add_f32_e32 v144, 1.0, v144
	v_log_f32_e32 v144, v144
	s_nop 0
	v_mul_f32_e32 v195, 0x3f317217, v144
	v_fma_f32 v195, v144, s52, -v195
	v_fmac_f32_e32 v195, 0x3377d1cf, v144
	v_fmac_f32_e32 v195, 0x3f317217, v144
	v_mov_b32_e32 v144, v195
	v_sub_f32_e32 v194, v194, v144
	v_mul_f32_e32 v144, 0x3fb8aa3b, v148
	v_exp_f32_e32 v144, v144
	s_nop 0
	v_fma_f32 v144, v190, v144, v140
	v_cmp_gt_f32_e64 s[40:41], s97, v144
	s_nop 1
	v_cndmask_b32_e64 v195, 0, 32, s[40:41]
	v_ldexp_f32 v144, v144, v195
	v_log_f32_e32 v144, v144
	s_nop 0
	v_mul_f32_e32 v195, 0x3f317217, v144
	v_fma_f32 v195, v144, s52, -v195
	v_fmac_f32_e32 v195, 0x3377d1cf, v144
	v_fmac_f32_e32 v195, 0x3f317217, v144
	v_mov_b32_e32 v144, v195
	v_cndmask_b32_e64 v195, 0, v216, s[40:41]
	v_sub_f32_e32 v144, v144, v195
	v_cndmask_b32_e64 v144, v148, v144, s[38:39]
	v_mul_f32_e32 v148, 0x3fb8aa3b, v194
	v_exp_f32_e32 v148, v148
	s_nop 0
	v_fma_f32 v148, v191, v148, v136
	v_cmp_gt_f32_e64 s[40:41], s97, v148
	s_nop 1
	v_cndmask_b32_e64 v195, 0, 32, s[40:41]
	v_ldexp_f32 v148, v148, v195
	v_log_f32_e32 v148, v148
	s_nop 0
	v_mul_f32_e32 v195, 0x3f317217, v148
	v_fma_f32 v195, v148, s52, -v195
	v_fmac_f32_e32 v195, 0x3377d1cf, v148
	v_fmac_f32_e32 v195, 0x3f317217, v148
	v_mov_b32_e32 v148, v195
	v_cndmask_b32_e64 v195, 0, v216, s[40:41]
	v_sub_f32_e32 v148, v148, v195
	v_cndmask_b32_e64 v148, v194, v148, s[36:37]
	v_min_f32_e32 v194, 0, v149
	v_mul_f32_e64 v149, |v149|, s57
	v_exp_f32_e32 v149, v149
	s_nop 0
	v_add_f32_e32 v149, 1.0, v149
	v_log_f32_e32 v149, v149
	s_nop 0
	v_mul_f32_e32 v195, 0x3f317217, v149
	v_fma_f32 v195, v149, s52, -v195
	v_fmac_f32_e32 v195, 0x3377d1cf, v149
	v_fmac_f32_e32 v195, 0x3f317217, v149
	v_mov_b32_e32 v149, v195
	v_sub_f32_e32 v149, v194, v149
	v_min_f32_e32 v194, 0, v145
	v_mul_f32_e64 v145, |v145|, s57
	v_exp_f32_e32 v145, v145
	s_nop 0
	v_add_f32_e32 v145, 1.0, v145
	v_log_f32_e32 v145, v145
	s_nop 0
	v_mul_f32_e32 v195, 0x3f317217, v145
	v_fma_f32 v195, v145, s52, -v195
	v_fmac_f32_e32 v195, 0x3377d1cf, v145
	v_fmac_f32_e32 v195, 0x3f317217, v145
	v_mov_b32_e32 v145, v195
	v_sub_f32_e32 v194, v194, v145
	v_mul_f32_e32 v145, 0x3fb8aa3b, v149
	v_exp_f32_e32 v145, v145
	s_nop 0
	v_fma_f32 v145, v188, v145, v141
	v_cmp_gt_f32_e64 s[40:41], s97, v145
	s_nop 1
	v_cndmask_b32_e64 v195, 0, 32, s[40:41]
	v_ldexp_f32 v145, v145, v195
	v_log_f32_e32 v145, v145
	s_nop 0
	v_mul_f32_e32 v195, 0x3f317217, v145
	v_fma_f32 v195, v145, s52, -v195
	v_fmac_f32_e32 v195, 0x3377d1cf, v145
	v_fmac_f32_e32 v195, 0x3f317217, v145
	v_mov_b32_e32 v145, v195
	v_cndmask_b32_e64 v195, 0, v216, s[40:41]
	v_sub_f32_e32 v145, v145, v195
	v_cndmask_b32_e64 v145, v149, v145, s[34:35]
	v_mul_f32_e32 v149, 0x3fb8aa3b, v194
	v_exp_f32_e32 v149, v149
	s_nop 0
	v_fma_f32 v149, v189, v149, v137
	v_cmp_gt_f32_e64 s[40:41], s97, v149
	s_nop 1
	v_cndmask_b32_e64 v195, 0, 32, s[40:41]
	v_ldexp_f32 v149, v149, v195
	v_log_f32_e32 v149, v149
	s_nop 0
	v_mul_f32_e32 v195, 0x3f317217, v149
	v_fma_f32 v195, v149, s52, -v195
	v_fmac_f32_e32 v195, 0x3377d1cf, v149
	v_fmac_f32_e32 v195, 0x3f317217, v149
	v_mov_b32_e32 v149, v195
	v_cndmask_b32_e64 v195, 0, v216, s[40:41]
	v_sub_f32_e32 v149, v149, v195
	v_cndmask_b32_e64 v149, v194, v149, s[30:31]
	v_min_f32_e32 v194, 0, v150
	v_mul_f32_e64 v150, |v150|, s57
	v_exp_f32_e32 v150, v150
	s_nop 0
	v_add_f32_e32 v150, 1.0, v150
	v_log_f32_e32 v150, v150
	s_nop 0
	v_mul_f32_e32 v195, 0x3f317217, v150
	v_fma_f32 v195, v150, s52, -v195
	v_fmac_f32_e32 v195, 0x3377d1cf, v150
	v_fmac_f32_e32 v195, 0x3f317217, v150
	v_mov_b32_e32 v150, v195
	v_sub_f32_e32 v150, v194, v150
	v_min_f32_e32 v194, 0, v146
	v_mul_f32_e64 v146, |v146|, s57
	v_exp_f32_e32 v146, v146
	s_nop 0
	v_add_f32_e32 v146, 1.0, v146
	v_log_f32_e32 v146, v146
	s_nop 0
	v_mul_f32_e32 v195, 0x3f317217, v146
	v_fma_f32 v195, v146, s52, -v195
	v_fmac_f32_e32 v195, 0x3377d1cf, v146
	v_fmac_f32_e32 v195, 0x3f317217, v146
	v_mov_b32_e32 v146, v195
	v_sub_f32_e32 v194, v194, v146
	v_mul_f32_e32 v146, 0x3fb8aa3b, v150
	v_exp_f32_e32 v146, v146
	s_nop 0
	v_fma_f32 v146, v187, v146, v142
	v_cmp_gt_f32_e64 s[40:41], s97, v146
	s_nop 1
	v_cndmask_b32_e64 v195, 0, 32, s[40:41]
	v_ldexp_f32 v146, v146, v195
	v_log_f32_e32 v146, v146
	s_nop 0
	v_mul_f32_e32 v195, 0x3f317217, v146
	v_fma_f32 v195, v146, s52, -v195
	v_fmac_f32_e32 v195, 0x3377d1cf, v146
	v_fmac_f32_e32 v195, 0x3f317217, v146
	v_mov_b32_e32 v146, v195
	v_cndmask_b32_e64 v195, 0, v216, s[40:41]
	v_sub_f32_e32 v146, v146, v195
	v_cndmask_b32_e64 v146, v150, v146, s[28:29]
	v_mul_f32_e32 v150, 0x3fb8aa3b, v194
	v_exp_f32_e32 v150, v150
	s_nop 0
	v_fma_f32 v150, v186, v150, v138
	v_cmp_gt_f32_e64 s[40:41], s97, v150
	s_nop 1
	v_cndmask_b32_e64 v195, 0, 32, s[40:41]
; __device__ __forceinline__ float silu_f(float x) { return x * __builtin_amdgcn_rcpf(1.f + __expf(-x)); }
; __device__ __forceinline__ v4u pack8(const f32x4 a, const f32x4 b) { v4u w; w.x = cvt_pk_bf16(a[0], a[1]); w.y = cvt_pk_bf16(a[2], a[3]); w.z = cvt_pk_bf16(b[0], b[1]); w.w = cvt_pk_bf16(b[2], b[3]); return w; }
;     __device__ __forceinline__ void operator()(const f32x4 (&acc)[2][2][4][2], const pg8::Unit& u, int wr, int wc, int fr, int fq) const {
;     ...
;         if (grp == 0) { WIN_LOOP( _Pragma("unroll") for (int i = 0; i < 4; ++i) { a[i] = silu_f(a[i]); b[i] = silu_f(b[i]); } *(v4u*)(QO + (size_t)row * DM + c) = pack8(a, b); ) }
;         else if (grp == 3) { WIN_LOOP( _Pragma("unroll") for (int i = 0; i < 4; ++i) { a[i] = silu_f(a[i]); b[i] = silu_f(b[i]); } *(v4u*)(GH + (size_t)row * 512 + c) = pack8(a, b); ) }
;         else if (grp == 1) {
;             f32x4 l0[2], l1[2];
; #pragma unroll
;             for (int bj = 0; bj < 2; ++bj) { l0[bj] = *(const f32x4*)(lb + cb + bj * 128); l1[bj] = *(const f32x4*)(lb + cb + bj * 128 + 4); }
;             WIN_LOOP( _Pragma("unroll") for (int i = 0; i < 4; ++i) { const float s0 = fminf(a[i], 0.f) - __logf(1.f + __expf(-fabsf(a[i]))), s1 = fminf(b[i], 0.f) - __logf(1.f + __expf(-fabsf(b[i]))); const float la = l0[bj][i], lbv = l1[bj][i];
;                     a[i] = la > 0.f ? __logf(la + (1.f - la) * __expf(s0)) : s0; b[i] = lbv > 0.f ? __logf(lbv + (1.f - lbv) * __expf(s1)) : s1; }
;                 *(f32x4*)(LF + (size_t)row * 512 + c) = a; *(f32x4*)(LF + (size_t)row * 512 + c + 4) = b; __builtin_amdgcn_sched_barrier(0); ) }
	v_ldexp_f32 v150, v150, v195
	v_log_f32_e32 v150, v150
	s_nop 0
	v_mul_f32_e32 v195, 0x3f317217, v150
	v_fma_f32 v195, v150, s52, -v195
	v_fmac_f32_e32 v195, 0x3377d1cf, v150
	v_fmac_f32_e32 v195, 0x3f317217, v150
	v_mov_b32_e32 v150, v195
	v_cndmask_b32_e64 v195, 0, v216, s[40:41]
	v_sub_f32_e32 v150, v150, v195
	v_cndmask_b32_e64 v150, v194, v150, s[26:27]
	v_min_f32_e32 v194, 0, v151
	v_mul_f32_e64 v151, |v151|, s57
	v_exp_f32_e32 v151, v151
	s_nop 0
	v_add_f32_e32 v151, 1.0, v151
	v_log_f32_e32 v151, v151
	s_nop 0
	v_mul_f32_e32 v195, 0x3f317217, v151
	v_fma_f32 v195, v151, s52, -v195
	v_fmac_f32_e32 v195, 0x3377d1cf, v151
	v_fmac_f32_e32 v195, 0x3f317217, v151
	v_mov_b32_e32 v151, v195
	v_sub_f32_e32 v151, v194, v151
	v_min_f32_e32 v194, 0, v147
	v_mul_f32_e64 v147, |v147|, s57
	v_exp_f32_e32 v147, v147
	s_nop 0
	v_add_f32_e32 v147, 1.0, v147
	v_log_f32_e32 v147, v147
	s_nop 0
	v_mul_f32_e32 v195, 0x3f317217, v147
	v_fma_f32 v195, v147, s52, -v195
	v_fmac_f32_e32 v195, 0x3377d1cf, v147
	v_fmac_f32_e32 v195, 0x3f317217, v147
	v_mov_b32_e32 v147, v195
	v_sub_f32_e32 v194, v194, v147
	v_mul_f32_e32 v147, 0x3fb8aa3b, v151
	v_exp_f32_e32 v147, v147
	s_nop 0
	v_fma_f32 v147, v185, v147, v143
	v_cmp_gt_f32_e64 s[40:41], s97, v147
	s_nop 1
	v_cndmask_b32_e64 v195, 0, 32, s[40:41]
	v_ldexp_f32 v147, v147, v195
	v_log_f32_e32 v147, v147
	s_nop 0
	v_mul_f32_e32 v195, 0x3f317217, v147
	v_fma_f32 v195, v147, s52, -v195
	v_fmac_f32_e32 v195, 0x3377d1cf, v147
	v_fmac_f32_e32 v195, 0x3f317217, v147
	v_mov_b32_e32 v147, v195
	v_cndmask_b32_e64 v195, 0, v216, s[40:41]
	v_sub_f32_e32 v147, v147, v195
	v_cndmask_b32_e64 v147, v151, v147, s[24:25]
	v_mul_f32_e32 v151, 0x3fb8aa3b, v194
	v_exp_f32_e32 v151, v151
	s_nop 0
	v_fma_f32 v151, v184, v151, v139
	v_cmp_gt_f32_e64 s[40:41], s97, v151
	s_nop 1
	v_cndmask_b32_e64 v195, 0, 32, s[40:41]
	v_ldexp_f32 v151, v151, v195
	v_log_f32_e32 v151, v151
	s_nop 0
	v_mul_f32_e32 v195, 0x3f317217, v151
	v_fma_f32 v195, v151, s52, -v195
	v_fmac_f32_e32 v195, 0x3377d1cf, v151
	v_fmac_f32_e32 v195, 0x3f317217, v151
	v_mov_b32_e32 v151, v195
	v_cndmask_b32_e64 v195, 0, v216, s[40:41]
	v_sub_f32_e32 v151, v151, v195
	v_cndmask_b32_e64 v151, v194, v151, s[22:23]
	global_store_dwordx4 v[170:171], v[144:147], off
	global_store_dwordx4 v[170:171], v[148:151], off offset:16
	s_nop 1
	v_pk_mul_f32 v[148:149], v[92:93], v[168:169] op_sel_hi:[1,0]
	v_pk_mul_f32 v[150:151], v[94:95], v[168:169] op_sel_hi:[1,0]
	v_pk_mul_f32 v[146:147], v[90:91], v[168:169] op_sel_hi:[1,0]
	v_pk_mul_f32 v[144:145], v[88:89], v[168:169] op_sel_hi:[1,0]
	v_min_f32_e32 v168, 0, v148
	v_mul_f32_e64 v148, |v148|, s57
	v_exp_f32_e32 v148, v148
	s_nop 0
	v_add_f32_e32 v148, 1.0, v148
	v_log_f32_e32 v148, v148
	s_nop 0
	v_mul_f32_e32 v194, 0x3f317217, v148
	v_fma_f32 v194, v148, s52, -v194
	v_fmac_f32_e32 v194, 0x3377d1cf, v148
	v_fmac_f32_e32 v194, 0x3f317217, v148
	v_mov_b32_e32 v148, v194
	v_sub_f32_e32 v148, v168, v148
	v_min_f32_e32 v168, 0, v144
	v_mul_f32_e64 v144, |v144|, s57
	v_exp_f32_e32 v144, v144
	s_nop 0
	v_add_f32_e32 v144, 1.0, v144
	v_log_f32_e32 v144, v144
	s_nop 0
	v_mul_f32_e32 v194, 0x3f317217, v144
	v_fma_f32 v194, v144, s52, -v194
	v_fmac_f32_e32 v194, 0x3377d1cf, v144
	v_fmac_f32_e32 v194, 0x3f317217, v144
	v_mov_b32_e32 v144, v194
	v_sub_f32_e32 v168, v168, v144
	v_mul_f32_e32 v144, 0x3fb8aa3b, v148
	v_exp_f32_e32 v144, v144
	s_nop 0
	v_fma_f32 v144, v183, v144, v132
	v_cmp_gt_f32_e64 s[40:41], s97, v144
	s_nop 1
	v_cndmask_b32_e64 v194, 0, 32, s[40:41]
	v_ldexp_f32 v144, v144, v194
	v_log_f32_e32 v144, v144
	s_nop 0
	v_mul_f32_e32 v194, 0x3f317217, v144
	v_fma_f32 v194, v144, s52, -v194
	v_fmac_f32_e32 v194, 0x3377d1cf, v144
	v_fmac_f32_e32 v194, 0x3f317217, v144
	v_mov_b32_e32 v144, v194
	v_cndmask_b32_e64 v194, 0, v216, s[40:41]
	v_sub_f32_e32 v144, v144, v194
	v_cndmask_b32_e64 v144, v148, v144, s[20:21]
	v_mul_f32_e32 v148, 0x3fb8aa3b, v168
	v_exp_f32_e32 v148, v148
	s_nop 0
	v_fma_f32 v148, v182, v148, v128
	v_cmp_gt_f32_e64 s[40:41], s97, v148
	s_nop 1
	v_cndmask_b32_e64 v194, 0, 32, s[40:41]
	v_ldexp_f32 v148, v148, v194
	v_log_f32_e32 v148, v148
	s_nop 0
	v_mul_f32_e32 v194, 0x3f317217, v148
	v_fma_f32 v194, v148, s52, -v194
	v_fmac_f32_e32 v194, 0x3377d1cf, v148
	v_fmac_f32_e32 v194, 0x3f317217, v148
	v_mov_b32_e32 v148, v194
	v_cndmask_b32_e64 v194, 0, v216, s[40:41]
	v_sub_f32_e32 v148, v148, v194
	v_cndmask_b32_e64 v148, v168, v148, s[18:19]
	v_min_f32_e32 v168, 0, v149
	v_mul_f32_e64 v149, |v149|, s57
	v_exp_f32_e32 v149, v149
	s_nop 0
	v_add_f32_e32 v149, 1.0, v149
	v_log_f32_e32 v149, v149
	s_nop 0
	v_mul_f32_e32 v194, 0x3f317217, v149
	v_fma_f32 v194, v149, s52, -v194
	v_fmac_f32_e32 v194, 0x3377d1cf, v149
	v_fmac_f32_e32 v194, 0x3f317217, v149
	v_mov_b32_e32 v149, v194
	v_sub_f32_e32 v149, v168, v149
	v_min_f32_e32 v168, 0, v145
	v_mul_f32_e64 v145, |v145|, s57
	v_exp_f32_e32 v145, v145
	s_nop 0
	v_add_f32_e32 v145, 1.0, v145
	v_log_f32_e32 v145, v145
	s_nop 0
	v_mul_f32_e32 v194, 0x3f317217, v145
	v_fma_f32 v194, v145, s52, -v194
	v_fmac_f32_e32 v194, 0x3377d1cf, v145
	v_fmac_f32_e32 v194, 0x3f317217, v145
	v_mov_b32_e32 v145, v194
	v_sub_f32_e32 v168, v168, v145
	v_mul_f32_e32 v145, 0x3fb8aa3b, v149
	v_exp_f32_e32 v145, v145
	s_nop 0
	v_fma_f32 v145, v181, v145, v133
	v_cmp_gt_f32_e64 s[40:41], s97, v145
	s_nop 1
	v_cndmask_b32_e64 v194, 0, 32, s[40:41]
	v_ldexp_f32 v145, v145, v194
	v_log_f32_e32 v145, v145
	s_nop 0
	v_mul_f32_e32 v194, 0x3f317217, v145
	v_fma_f32 v194, v145, s52, -v194
	v_fmac_f32_e32 v194, 0x3377d1cf, v145
	v_fmac_f32_e32 v194, 0x3f317217, v145
	v_mov_b32_e32 v145, v194
;     __device__ __forceinline__ void operator()(const f32x4 (&acc)[2][2][4][2], const pg8::Unit& u, int wr, int wc, int fr, int fq) const {
;     ...
;             WIN_LOOP( _Pragma("unroll") for (int i = 0; i < 4; ++i) { const float s0 = fminf(a[i], 0.f) - __logf(1.f + __expf(-fabsf(a[i]))), s1 = fminf(b[i], 0.f) - __logf(1.f + __expf(-fabsf(b[i]))); const float la = l0[bj][i], lbv = l1[bj][i];
;                     a[i] = la > 0.f ? __logf(la + (1.f - la) * __expf(s0)) : s0; b[i] = lbv > 0.f ? __logf(lbv + (1.f - lbv) * __expf(s1)) : s1; }
;                 *(f32x4*)(LF + (size_t)row * 512 + c) = a; *(f32x4*)(LF + (size_t)row * 512 + c + 4) = b; __builtin_amdgcn_sched_barrier(0); ) }
	v_cndmask_b32_e64 v194, 0, v216, s[40:41]
	v_sub_f32_e32 v145, v145, v194
	v_cndmask_b32_e64 v145, v149, v145, s[16:17]
	v_mul_f32_e32 v149, 0x3fb8aa3b, v168
	v_exp_f32_e32 v149, v149
	s_nop 0
	v_fma_f32 v149, v180, v149, v129
	v_cmp_gt_f32_e64 s[40:41], s97, v149
	s_nop 1
	v_cndmask_b32_e64 v194, 0, 32, s[40:41]
	v_ldexp_f32 v149, v149, v194
	v_log_f32_e32 v149, v149
	s_nop 0
	v_mul_f32_e32 v194, 0x3f317217, v149
	v_fma_f32 v194, v149, s52, -v194
	v_fmac_f32_e32 v194, 0x3377d1cf, v149
	v_fmac_f32_e32 v194, 0x3f317217, v149
	v_mov_b32_e32 v149, v194
	v_cndmask_b32_e64 v194, 0, v216, s[40:41]
	v_sub_f32_e32 v149, v149, v194
	v_cndmask_b32_e64 v149, v168, v149, s[14:15]
	v_min_f32_e32 v168, 0, v150
	v_mul_f32_e64 v150, |v150|, s57
	v_exp_f32_e32 v150, v150
	s_nop 0
	v_add_f32_e32 v150, 1.0, v150
	v_log_f32_e32 v150, v150
	s_nop 0
	v_mul_f32_e32 v194, 0x3f317217, v150
	v_fma_f32 v194, v150, s52, -v194
	v_fmac_f32_e32 v194, 0x3377d1cf, v150
	v_fmac_f32_e32 v194, 0x3f317217, v150
	v_mov_b32_e32 v150, v194
	v_sub_f32_e32 v150, v168, v150
	v_min_f32_e32 v168, 0, v146
	v_mul_f32_e64 v146, |v146|, s57
	v_exp_f32_e32 v146, v146
	s_nop 0
	v_add_f32_e32 v146, 1.0, v146
	v_log_f32_e32 v146, v146
	s_nop 0
	v_mul_f32_e32 v194, 0x3f317217, v146
	v_fma_f32 v194, v146, s52, -v194
	v_fmac_f32_e32 v194, 0x3377d1cf, v146
	v_fmac_f32_e32 v194, 0x3f317217, v146
	v_mov_b32_e32 v146, v194
	v_sub_f32_e32 v168, v168, v146
	v_mul_f32_e32 v146, 0x3fb8aa3b, v150
	v_exp_f32_e32 v146, v146
	s_nop 0
	v_fma_f32 v146, v179, v146, v134
	v_cmp_gt_f32_e64 s[40:41], s97, v146
	s_nop 1
	v_cndmask_b32_e64 v194, 0, 32, s[40:41]
	v_ldexp_f32 v146, v146, v194
	v_log_f32_e32 v146, v146
	s_nop 0
	v_mul_f32_e32 v194, 0x3f317217, v146
	v_fma_f32 v194, v146, s52, -v194
	v_fmac_f32_e32 v194, 0x3377d1cf, v146
	v_fmac_f32_e32 v194, 0x3f317217, v146
	v_mov_b32_e32 v146, v194
	v_cndmask_b32_e64 v194, 0, v216, s[40:41]
	v_sub_f32_e32 v146, v146, v194
	v_cndmask_b32_e64 v146, v150, v146, s[12:13]
	v_mul_f32_e32 v150, 0x3fb8aa3b, v168
	v_exp_f32_e32 v150, v150
	s_nop 0
	v_fma_f32 v150, v178, v150, v130
	v_cmp_gt_f32_e64 s[40:41], s97, v150
	s_nop 1
	v_cndmask_b32_e64 v194, 0, 32, s[40:41]
	v_ldexp_f32 v150, v150, v194
	v_log_f32_e32 v150, v150
	s_nop 0
	v_mul_f32_e32 v194, 0x3f317217, v150
	v_fma_f32 v194, v150, s52, -v194
	v_fmac_f32_e32 v194, 0x3377d1cf, v150
	v_fmac_f32_e32 v194, 0x3f317217, v150
	v_mov_b32_e32 v150, v194
	v_cndmask_b32_e64 v194, 0, v216, s[40:41]
	v_sub_f32_e32 v150, v150, v194
	v_cndmask_b32_e64 v150, v168, v150, s[10:11]
	v_min_f32_e32 v168, 0, v151
	v_mul_f32_e64 v151, |v151|, s57
	v_exp_f32_e32 v151, v151
	s_nop 0
	v_add_f32_e32 v151, 1.0, v151
	v_log_f32_e32 v151, v151
	s_nop 0
	v_mul_f32_e32 v194, 0x3f317217, v151
	v_fma_f32 v194, v151, s52, -v194
	v_fmac_f32_e32 v194, 0x3377d1cf, v151
	v_fmac_f32_e32 v194, 0x3f317217, v151
	v_mov_b32_e32 v151, v194
	v_sub_f32_e32 v151, v168, v151
	v_min_f32_e32 v168, 0, v147
	v_mul_f32_e64 v147, |v147|, s57
	v_exp_f32_e32 v147, v147
	s_nop 0
	v_add_f32_e32 v147, 1.0, v147
	v_log_f32_e32 v147, v147
	s_nop 0
	v_mul_f32_e32 v194, 0x3f317217, v147
	v_fma_f32 v194, v147, s52, -v194
	v_fmac_f32_e32 v194, 0x3377d1cf, v147
	v_fmac_f32_e32 v194, 0x3f317217, v147
	v_mov_b32_e32 v147, v194
	v_sub_f32_e32 v168, v168, v147
	v_mul_f32_e32 v147, 0x3fb8aa3b, v151
	v_exp_f32_e32 v147, v147
	s_nop 0
	v_fma_f32 v147, v177, v147, v135
	v_cmp_gt_f32_e64 s[40:41], s97, v147
	s_nop 1
	v_cndmask_b32_e64 v194, 0, 32, s[40:41]
	v_ldexp_f32 v147, v147, v194
	v_log_f32_e32 v147, v147
	s_nop 0
	v_mul_f32_e32 v194, 0x3f317217, v147
	v_fma_f32 v194, v147, s52, -v194
	v_fmac_f32_e32 v194, 0x3377d1cf, v147
	v_fmac_f32_e32 v194, 0x3f317217, v147
	v_mov_b32_e32 v147, v194
	v_cndmask_b32_e64 v194, 0, v216, s[40:41]
	v_sub_f32_e32 v147, v147, v194
	v_cndmask_b32_e64 v147, v151, v147, s[8:9]
	v_mul_f32_e32 v151, 0x3fb8aa3b, v168
	v_exp_f32_e32 v151, v151
	s_nop 0
	v_fma_f32 v151, v167, v151, v131
	v_cmp_gt_f32_e64 s[40:41], s97, v151
	s_nop 1
	v_cndmask_b32_e64 v194, 0, 32, s[40:41]
	v_ldexp_f32 v151, v151, v194
	v_log_f32_e32 v151, v151
	s_nop 0
	v_mul_f32_e32 v194, 0x3f317217, v151
	v_fma_f32 v194, v151, s52, -v194
	v_fmac_f32_e32 v194, 0x3377d1cf, v151
	v_fmac_f32_e32 v194, 0x3f317217, v151
	v_mov_b32_e32 v151, v194
	v_cndmask_b32_e64 v194, 0, v216, s[40:41]
	v_sub_f32_e32 v151, v151, v194
	v_cndmask_b32_e32 v151, v168, v151, vcc
	global_store_dwordx4 v[170:171], v[144:147], off offset:512
	global_store_dwordx4 v[170:171], v[148:151], off offset:528
	s_nop 1
	v_add_u32_e32 v148, 0x90, v166
	v_ashrrev_i32_e32 v149, 31, v148
	v_lshlrev_b64 v[144:145], 6, v[148:149]
	v_lshl_add_u64 v[144:145], v[160:161], 0, v[144:145]
	s_nop 0
	s_waitcnt lgkmcnt(0)
	s_nop 3
	s_nop 0
	s_nop 1
	s_waitcnt lgkmcnt(0)
	s_nop 1
	s_waitcnt lgkmcnt(0)
; __device__ __forceinline__ float silu_f(float x) { return x * __builtin_amdgcn_rcpf(1.f + __expf(-x)); }
; __device__ __forceinline__ v4u pack8(const f32x4 a, const f32x4 b) { v4u w; w.x = cvt_pk_bf16(a[0], a[1]); w.y = cvt_pk_bf16(a[2], a[3]); w.z = cvt_pk_bf16(b[0], b[1]); w.w = cvt_pk_bf16(b[2], b[3]); return w; }
;     __device__ __forceinline__ void operator()(const f32x4 (&acc)[2][2][4][2], const pg8::Unit& u, int wr, int wc, int fr, int fq) const {
;     ...
;         if (grp == 0) { WIN_LOOP( _Pragma("unroll") for (int i = 0; i < 4; ++i) { a[i] = silu_f(a[i]); b[i] = silu_f(b[i]); } *(v4u*)(QO + (size_t)row * DM + c) = pack8(a, b); ) }
;         else if (grp == 3) { WIN_LOOP( _Pragma("unroll") for (int i = 0; i < 4; ++i) { a[i] = silu_f(a[i]); b[i] = silu_f(b[i]); } *(v4u*)(GH + (size_t)row * 512 + c) = pack8(a, b); ) }
;         else if (grp == 1) {
;             f32x4 l0[2], l1[2];
; #pragma unroll
;             for (int bj = 0; bj < 2; ++bj) { l0[bj] = *(const f32x4*)(lb + cb + bj * 128); l1[bj] = *(const f32x4*)(lb + cb + bj * 128 + 4); }
;             WIN_LOOP( _Pragma("unroll") for (int i = 0; i < 4; ++i) { const float s0 = fminf(a[i], 0.f) - __logf(1.f + __expf(-fabsf(a[i]))), s1 = fminf(b[i], 0.f) - __logf(1.f + __expf(-fabsf(b[i]))); const float la = l0[bj][i], lbv = l1[bj][i];
;                     a[i] = la > 0.f ? __logf(la + (1.f - la) * __expf(s0)) : s0; b[i] = lbv > 0.f ? __logf(lbv + (1.f - lbv) * __expf(s1)) : s1; }
;                 *(f32x4*)(LF + (size_t)row * 512 + c) = a; *(f32x4*)(LF + (size_t)row * 512 + c + 4) = b; __builtin_amdgcn_sched_barrier(0); ) }
	s_nop 1
	v_mov_b32_e32 v168, v240
	v_lshlrev_b64 v[144:145], 11, v[148:149]
	v_lshl_add_u64 v[170:171], s[50:51], 0, v[144:145]
	v_lshl_add_u64 v[170:171], v[170:171], 0, v[192:193]
	v_pk_mul_f32 v[148:149], v[20:21], v[168:169] op_sel_hi:[1,0]
	v_pk_mul_f32 v[144:145], v[16:17], v[168:169] op_sel_hi:[1,0]
	v_min_f32_e32 v194, 0, v148
	v_mul_f32_e64 v148, |v148|, s57
	v_exp_f32_e32 v148, v148
	v_pk_mul_f32 v[150:151], v[22:23], v[168:169] op_sel_hi:[1,0]
	v_pk_mul_f32 v[146:147], v[18:19], v[168:169] op_sel_hi:[1,0]
	v_add_f32_e32 v148, 1.0, v148
	v_log_f32_e32 v148, v148
	s_nop 0
	v_mul_f32_e32 v195, 0x3f317217, v148
	v_fma_f32 v195, v148, s52, -v195
	v_fmac_f32_e32 v195, 0x3377d1cf, v148
	v_fmac_f32_e32 v195, 0x3f317217, v148
	v_mov_b32_e32 v148, v195
	v_sub_f32_e32 v148, v194, v148
	v_min_f32_e32 v194, 0, v144
	v_mul_f32_e64 v144, |v144|, s57
	v_exp_f32_e32 v144, v144
	s_nop 0
	v_add_f32_e32 v144, 1.0, v144
	v_log_f32_e32 v144, v144
	s_nop 0
	v_mul_f32_e32 v195, 0x3f317217, v144
	v_fma_f32 v195, v144, s52, -v195
	v_fmac_f32_e32 v195, 0x3377d1cf, v144
	v_fmac_f32_e32 v195, 0x3f317217, v144
	v_mov_b32_e32 v144, v195
	v_sub_f32_e32 v194, v194, v144
	v_mul_f32_e32 v144, 0x3fb8aa3b, v148
	v_exp_f32_e32 v144, v144
	s_nop 0
	v_fma_f32 v144, v190, v144, v140
	v_cmp_gt_f32_e64 s[40:41], s97, v144
	s_nop 1
	v_cndmask_b32_e64 v195, 0, 32, s[40:41]
	v_ldexp_f32 v144, v144, v195
	v_log_f32_e32 v144, v144
	s_nop 0
	v_mul_f32_e32 v195, 0x3f317217, v144
	v_fma_f32 v195, v144, s52, -v195
	v_fmac_f32_e32 v195, 0x3377d1cf, v144
	v_fmac_f32_e32 v195, 0x3f317217, v144
	v_mov_b32_e32 v144, v195
	v_cndmask_b32_e64 v195, 0, v216, s[40:41]
	v_sub_f32_e32 v144, v144, v195
	v_cndmask_b32_e64 v144, v148, v144, s[38:39]
	v_mul_f32_e32 v148, 0x3fb8aa3b, v194
	v_exp_f32_e32 v148, v148
	s_nop 0
	v_fma_f32 v148, v191, v148, v136
	v_cmp_gt_f32_e64 s[40:41], s97, v148
	s_nop 1
	v_cndmask_b32_e64 v195, 0, 32, s[40:41]
	v_ldexp_f32 v148, v148, v195
	v_log_f32_e32 v148, v148
	s_nop 0
	v_mul_f32_e32 v195, 0x3f317217, v148
	v_fma_f32 v195, v148, s52, -v195
	v_fmac_f32_e32 v195, 0x3377d1cf, v148
	v_fmac_f32_e32 v195, 0x3f317217, v148
	v_mov_b32_e32 v148, v195
	v_cndmask_b32_e64 v195, 0, v216, s[40:41]
	v_sub_f32_e32 v148, v148, v195
	v_cndmask_b32_e64 v148, v194, v148, s[36:37]
	v_min_f32_e32 v194, 0, v149
	v_mul_f32_e64 v149, |v149|, s57
	v_exp_f32_e32 v149, v149
	s_nop 0
	v_add_f32_e32 v149, 1.0, v149
	v_log_f32_e32 v149, v149
	s_nop 0
	v_mul_f32_e32 v195, 0x3f317217, v149
	v_fma_f32 v195, v149, s52, -v195
	v_fmac_f32_e32 v195, 0x3377d1cf, v149
	v_fmac_f32_e32 v195, 0x3f317217, v149
	v_mov_b32_e32 v149, v195
	v_sub_f32_e32 v149, v194, v149
	v_min_f32_e32 v194, 0, v145
	v_mul_f32_e64 v145, |v145|, s57
	v_exp_f32_e32 v145, v145
	s_nop 0
	v_add_f32_e32 v145, 1.0, v145
	v_log_f32_e32 v145, v145
	s_nop 0
	v_mul_f32_e32 v195, 0x3f317217, v145
	v_fma_f32 v195, v145, s52, -v195
	v_fmac_f32_e32 v195, 0x3377d1cf, v145
	v_fmac_f32_e32 v195, 0x3f317217, v145
	v_mov_b32_e32 v145, v195
	v_sub_f32_e32 v194, v194, v145
	v_mul_f32_e32 v145, 0x3fb8aa3b, v149
	v_exp_f32_e32 v145, v145
	s_nop 0
	v_fma_f32 v145, v188, v145, v141
	v_cmp_gt_f32_e64 s[40:41], s97, v145
	s_nop 1
	v_cndmask_b32_e64 v195, 0, 32, s[40:41]
	v_ldexp_f32 v145, v145, v195
	v_log_f32_e32 v145, v145
	s_nop 0
	v_mul_f32_e32 v195, 0x3f317217, v145
	v_fma_f32 v195, v145, s52, -v195
	v_fmac_f32_e32 v195, 0x3377d1cf, v145
	v_fmac_f32_e32 v195, 0x3f317217, v145
	v_mov_b32_e32 v145, v195
	v_cndmask_b32_e64 v195, 0, v216, s[40:41]
	v_sub_f32_e32 v145, v145, v195
	v_cndmask_b32_e64 v145, v149, v145, s[34:35]
	v_mul_f32_e32 v149, 0x3fb8aa3b, v194
	v_exp_f32_e32 v149, v149
	s_nop 0
	v_fma_f32 v149, v189, v149, v137
	v_cmp_gt_f32_e64 s[40:41], s97, v149
	s_nop 1
	v_cndmask_b32_e64 v195, 0, 32, s[40:41]
	v_ldexp_f32 v149, v149, v195
	v_log_f32_e32 v149, v149
	s_nop 0
	v_mul_f32_e32 v195, 0x3f317217, v149
	v_fma_f32 v195, v149, s52, -v195
	v_fmac_f32_e32 v195, 0x3377d1cf, v149
	v_fmac_f32_e32 v195, 0x3f317217, v149
	v_mov_b32_e32 v149, v195
	v_cndmask_b32_e64 v195, 0, v216, s[40:41]
	v_sub_f32_e32 v149, v149, v195
	v_cndmask_b32_e64 v149, v194, v149, s[30:31]
	v_min_f32_e32 v194, 0, v150
	v_mul_f32_e64 v150, |v150|, s57
	v_exp_f32_e32 v150, v150
	s_nop 0
	v_add_f32_e32 v150, 1.0, v150
	v_log_f32_e32 v150, v150
	s_nop 0
	v_mul_f32_e32 v195, 0x3f317217, v150
	v_fma_f32 v195, v150, s52, -v195
	v_fmac_f32_e32 v195, 0x3377d1cf, v150
	v_fmac_f32_e32 v195, 0x3f317217, v150
	v_mov_b32_e32 v150, v195
	v_sub_f32_e32 v150, v194, v150
	v_min_f32_e32 v194, 0, v146
	v_mul_f32_e64 v146, |v146|, s57
	v_exp_f32_e32 v146, v146
	s_nop 0
	v_add_f32_e32 v146, 1.0, v146
	v_log_f32_e32 v146, v146
	s_nop 0
	v_mul_f32_e32 v195, 0x3f317217, v146
	v_fma_f32 v195, v146, s52, -v195
	v_fmac_f32_e32 v195, 0x3377d1cf, v146
	v_fmac_f32_e32 v195, 0x3f317217, v146
	v_mov_b32_e32 v146, v195
	v_sub_f32_e32 v194, v194, v146
	v_mul_f32_e32 v146, 0x3fb8aa3b, v150
	v_exp_f32_e32 v146, v146
	s_nop 0
	v_fma_f32 v146, v187, v146, v142
	v_cmp_gt_f32_e64 s[40:41], s97, v146
	s_nop 1
	v_cndmask_b32_e64 v195, 0, 32, s[40:41]
	v_ldexp_f32 v146, v146, v195
	v_log_f32_e32 v146, v146
	s_nop 0
	v_mul_f32_e32 v195, 0x3f317217, v146
	v_fma_f32 v195, v146, s52, -v195
	v_fmac_f32_e32 v195, 0x3377d1cf, v146
	v_fmac_f32_e32 v195, 0x3f317217, v146
	v_mov_b32_e32 v146, v195
	v_cndmask_b32_e64 v195, 0, v216, s[40:41]
	v_sub_f32_e32 v146, v146, v195
	v_cndmask_b32_e64 v146, v150, v146, s[28:29]
	v_mul_f32_e32 v150, 0x3fb8aa3b, v194
	v_exp_f32_e32 v150, v150
	s_nop 0
	v_fma_f32 v150, v186, v150, v138
	v_cmp_gt_f32_e64 s[40:41], s97, v150
	s_nop 1
	v_cndmask_b32_e64 v195, 0, 32, s[40:41]
; __device__ __forceinline__ float silu_f(float x) { return x * __builtin_amdgcn_rcpf(1.f + __expf(-x)); }
; __device__ __forceinline__ v4u pack8(const f32x4 a, const f32x4 b) { v4u w; w.x = cvt_pk_bf16(a[0], a[1]); w.y = cvt_pk_bf16(a[2], a[3]); w.z = cvt_pk_bf16(b[0], b[1]); w.w = cvt_pk_bf16(b[2], b[3]); return w; }
;     __device__ __forceinline__ void operator()(const f32x4 (&acc)[2][2][4][2], const pg8::Unit& u, int wr, int wc, int fr, int fq) const {
;     ...
;         if (grp == 0) { WIN_LOOP( _Pragma("unroll") for (int i = 0; i < 4; ++i) { a[i] = silu_f(a[i]); b[i] = silu_f(b[i]); } *(v4u*)(QO + (size_t)row * DM + c) = pack8(a, b); ) }
;         else if (grp == 3) { WIN_LOOP( _Pragma("unroll") for (int i = 0; i < 4; ++i) { a[i] = silu_f(a[i]); b[i] = silu_f(b[i]); } *(v4u*)(GH + (size_t)row * 512 + c) = pack8(a, b); ) }
;         else if (grp == 1) {
;             f32x4 l0[2], l1[2];
; #pragma unroll
;             for (int bj = 0; bj < 2; ++bj) { l0[bj] = *(const f32x4*)(lb + cb + bj * 128); l1[bj] = *(const f32x4*)(lb + cb + bj * 128 + 4); }
;             WIN_LOOP( _Pragma("unroll") for (int i = 0; i < 4; ++i) { const float s0 = fminf(a[i], 0.f) - __logf(1.f + __expf(-fabsf(a[i]))), s1 = fminf(b[i], 0.f) - __logf(1.f + __expf(-fabsf(b[i]))); const float la = l0[bj][i], lbv = l1[bj][i];
;                     a[i] = la > 0.f ? __logf(la + (1.f - la) * __expf(s0)) : s0; b[i] = lbv > 0.f ? __logf(lbv + (1.f - lbv) * __expf(s1)) : s1; }
;                 *(f32x4*)(LF + (size_t)row * 512 + c) = a; *(f32x4*)(LF + (size_t)row * 512 + c + 4) = b; __builtin_amdgcn_sched_barrier(0); ) }
	v_ldexp_f32 v150, v150, v195
	v_log_f32_e32 v150, v150
	s_nop 0
	v_mul_f32_e32 v195, 0x3f317217, v150
	v_fma_f32 v195, v150, s52, -v195
	v_fmac_f32_e32 v195, 0x3377d1cf, v150
	v_fmac_f32_e32 v195, 0x3f317217, v150
	v_mov_b32_e32 v150, v195
	v_cndmask_b32_e64 v195, 0, v216, s[40:41]
	v_sub_f32_e32 v150, v150, v195
	v_cndmask_b32_e64 v150, v194, v150, s[26:27]
	v_min_f32_e32 v194, 0, v151
	v_mul_f32_e64 v151, |v151|, s57
	v_exp_f32_e32 v151, v151
	s_nop 0
	v_add_f32_e32 v151, 1.0, v151
	v_log_f32_e32 v151, v151
	s_nop 0
	v_mul_f32_e32 v195, 0x3f317217, v151
	v_fma_f32 v195, v151, s52, -v195
	v_fmac_f32_e32 v195, 0x3377d1cf, v151
	v_fmac_f32_e32 v195, 0x3f317217, v151
	v_mov_b32_e32 v151, v195
	v_sub_f32_e32 v151, v194, v151
	v_min_f32_e32 v194, 0, v147
	v_mul_f32_e64 v147, |v147|, s57
	v_exp_f32_e32 v147, v147
	s_nop 0
	v_add_f32_e32 v147, 1.0, v147
	v_log_f32_e32 v147, v147
	s_nop 0
	v_mul_f32_e32 v195, 0x3f317217, v147
	v_fma_f32 v195, v147, s52, -v195
	v_fmac_f32_e32 v195, 0x3377d1cf, v147
	v_fmac_f32_e32 v195, 0x3f317217, v147
	v_mov_b32_e32 v147, v195
	v_sub_f32_e32 v194, v194, v147
	v_mul_f32_e32 v147, 0x3fb8aa3b, v151
	v_exp_f32_e32 v147, v147
	s_nop 0
	v_fma_f32 v147, v185, v147, v143
	v_cmp_gt_f32_e64 s[40:41], s97, v147
	s_nop 1
	v_cndmask_b32_e64 v195, 0, 32, s[40:41]
	v_ldexp_f32 v147, v147, v195
	v_log_f32_e32 v147, v147
	s_nop 0
	v_mul_f32_e32 v195, 0x3f317217, v147
	v_fma_f32 v195, v147, s52, -v195
	v_fmac_f32_e32 v195, 0x3377d1cf, v147
	v_fmac_f32_e32 v195, 0x3f317217, v147
	v_mov_b32_e32 v147, v195
	v_cndmask_b32_e64 v195, 0, v216, s[40:41]
	v_sub_f32_e32 v147, v147, v195
	v_cndmask_b32_e64 v147, v151, v147, s[24:25]
	v_mul_f32_e32 v151, 0x3fb8aa3b, v194
	v_exp_f32_e32 v151, v151
	s_nop 0
	v_fma_f32 v151, v184, v151, v139
	v_cmp_gt_f32_e64 s[40:41], s97, v151
	s_nop 1
	v_cndmask_b32_e64 v195, 0, 32, s[40:41]
	v_ldexp_f32 v151, v151, v195
	v_log_f32_e32 v151, v151
	s_nop 0
	v_mul_f32_e32 v195, 0x3f317217, v151
	v_fma_f32 v195, v151, s52, -v195
	v_fmac_f32_e32 v195, 0x3377d1cf, v151
	v_fmac_f32_e32 v195, 0x3f317217, v151
	v_mov_b32_e32 v151, v195
	v_cndmask_b32_e64 v195, 0, v216, s[40:41]
	v_sub_f32_e32 v151, v151, v195
	v_cndmask_b32_e64 v151, v194, v151, s[22:23]
	global_store_dwordx4 v[170:171], v[144:147], off
	global_store_dwordx4 v[170:171], v[148:151], off offset:16
	s_nop 1
	v_pk_mul_f32 v[148:149], v[84:85], v[168:169] op_sel_hi:[1,0]
	v_pk_mul_f32 v[150:151], v[86:87], v[168:169] op_sel_hi:[1,0]
	v_pk_mul_f32 v[146:147], v[82:83], v[168:169] op_sel_hi:[1,0]
	v_pk_mul_f32 v[144:145], v[80:81], v[168:169] op_sel_hi:[1,0]
	v_min_f32_e32 v168, 0, v148
	v_mul_f32_e64 v148, |v148|, s57
	v_exp_f32_e32 v148, v148
	s_nop 0
	v_add_f32_e32 v148, 1.0, v148
	v_log_f32_e32 v148, v148
	s_nop 0
	v_mul_f32_e32 v194, 0x3f317217, v148
	v_fma_f32 v194, v148, s52, -v194
	v_fmac_f32_e32 v194, 0x3377d1cf, v148
	v_fmac_f32_e32 v194, 0x3f317217, v148
	v_mov_b32_e32 v148, v194
	v_sub_f32_e32 v148, v168, v148
	v_min_f32_e32 v168, 0, v144
	v_mul_f32_e64 v144, |v144|, s57
	v_exp_f32_e32 v144, v144
	s_nop 0
	v_add_f32_e32 v144, 1.0, v144
	v_log_f32_e32 v144, v144
	s_nop 0
	v_mul_f32_e32 v194, 0x3f317217, v144
	v_fma_f32 v194, v144, s52, -v194
	v_fmac_f32_e32 v194, 0x3377d1cf, v144
	v_fmac_f32_e32 v194, 0x3f317217, v144
	v_mov_b32_e32 v144, v194
	v_sub_f32_e32 v168, v168, v144
	v_mul_f32_e32 v144, 0x3fb8aa3b, v148
	v_exp_f32_e32 v144, v144
	s_nop 0
	v_fma_f32 v144, v183, v144, v132
	v_cmp_gt_f32_e64 s[40:41], s97, v144
	s_nop 1
	v_cndmask_b32_e64 v194, 0, 32, s[40:41]
	v_ldexp_f32 v144, v144, v194
	v_log_f32_e32 v144, v144
	s_nop 0
	v_mul_f32_e32 v194, 0x3f317217, v144
	v_fma_f32 v194, v144, s52, -v194
	v_fmac_f32_e32 v194, 0x3377d1cf, v144
	v_fmac_f32_e32 v194, 0x3f317217, v144
	v_mov_b32_e32 v144, v194
	v_cndmask_b32_e64 v194, 0, v216, s[40:41]
	v_sub_f32_e32 v144, v144, v194
	v_cndmask_b32_e64 v144, v148, v144, s[20:21]
	v_mul_f32_e32 v148, 0x3fb8aa3b, v168
	v_exp_f32_e32 v148, v148
	s_nop 0
	v_fma_f32 v148, v182, v148, v128
	v_cmp_gt_f32_e64 s[40:41], s97, v148
	s_nop 1
	v_cndmask_b32_e64 v194, 0, 32, s[40:41]
	v_ldexp_f32 v148, v148, v194
	v_log_f32_e32 v148, v148
	s_nop 0
	v_mul_f32_e32 v194, 0x3f317217, v148
	v_fma_f32 v194, v148, s52, -v194
	v_fmac_f32_e32 v194, 0x3377d1cf, v148
	v_fmac_f32_e32 v194, 0x3f317217, v148
	v_mov_b32_e32 v148, v194
	v_cndmask_b32_e64 v194, 0, v216, s[40:41]
	v_sub_f32_e32 v148, v148, v194
	v_cndmask_b32_e64 v148, v168, v148, s[18:19]
	v_min_f32_e32 v168, 0, v149
	v_mul_f32_e64 v149, |v149|, s57
	v_exp_f32_e32 v149, v149
	s_nop 0
	v_add_f32_e32 v149, 1.0, v149
	v_log_f32_e32 v149, v149
	s_nop 0
	v_mul_f32_e32 v194, 0x3f317217, v149
	v_fma_f32 v194, v149, s52, -v194
	v_fmac_f32_e32 v194, 0x3377d1cf, v149
	v_fmac_f32_e32 v194, 0x3f317217, v149
	v_mov_b32_e32 v149, v194
	v_sub_f32_e32 v149, v168, v149
	v_min_f32_e32 v168, 0, v145
	v_mul_f32_e64 v145, |v145|, s57
	v_exp_f32_e32 v145, v145
	s_nop 0
	v_add_f32_e32 v145, 1.0, v145
	v_log_f32_e32 v145, v145
	s_nop 0
	v_mul_f32_e32 v194, 0x3f317217, v145
	v_fma_f32 v194, v145, s52, -v194
	v_fmac_f32_e32 v194, 0x3377d1cf, v145
	v_fmac_f32_e32 v194, 0x3f317217, v145
	v_mov_b32_e32 v145, v194
	v_sub_f32_e32 v168, v168, v145
	v_mul_f32_e32 v145, 0x3fb8aa3b, v149
	v_exp_f32_e32 v145, v145
	s_nop 0
	v_fma_f32 v145, v181, v145, v133
	v_cmp_gt_f32_e64 s[40:41], s97, v145
	s_nop 1
	v_cndmask_b32_e64 v194, 0, 32, s[40:41]
	v_ldexp_f32 v145, v145, v194
	v_log_f32_e32 v145, v145
	s_nop 0
	v_mul_f32_e32 v194, 0x3f317217, v145
	v_fma_f32 v194, v145, s52, -v194
	v_fmac_f32_e32 v194, 0x3377d1cf, v145
	v_fmac_f32_e32 v194, 0x3f317217, v145
	v_mov_b32_e32 v145, v194
;     __device__ __forceinline__ void operator()(const f32x4 (&acc)[2][2][4][2], const pg8::Unit& u, int wr, int wc, int fr, int fq) const {
;     ...
;             WIN_LOOP( _Pragma("unroll") for (int i = 0; i < 4; ++i) { const float s0 = fminf(a[i], 0.f) - __logf(1.f + __expf(-fabsf(a[i]))), s1 = fminf(b[i], 0.f) - __logf(1.f + __expf(-fabsf(b[i]))); const float la = l0[bj][i], lbv = l1[bj][i];
;                     a[i] = la > 0.f ? __logf(la + (1.f - la) * __expf(s0)) : s0; b[i] = lbv > 0.f ? __logf(lbv + (1.f - lbv) * __expf(s1)) : s1; }
;                 *(f32x4*)(LF + (size_t)row * 512 + c) = a; *(f32x4*)(LF + (size_t)row * 512 + c + 4) = b; __builtin_amdgcn_sched_barrier(0); ) }
	v_cndmask_b32_e64 v194, 0, v216, s[40:41]
	v_sub_f32_e32 v145, v145, v194
	v_cndmask_b32_e64 v145, v149, v145, s[16:17]
	v_mul_f32_e32 v149, 0x3fb8aa3b, v168
	v_exp_f32_e32 v149, v149
	s_nop 0
	v_fma_f32 v149, v180, v149, v129
	v_cmp_gt_f32_e64 s[40:41], s97, v149
	s_nop 1
	v_cndmask_b32_e64 v194, 0, 32, s[40:41]
	v_ldexp_f32 v149, v149, v194
	v_log_f32_e32 v149, v149
	s_nop 0
	v_mul_f32_e32 v194, 0x3f317217, v149
	v_fma_f32 v194, v149, s52, -v194
	v_fmac_f32_e32 v194, 0x3377d1cf, v149
	v_fmac_f32_e32 v194, 0x3f317217, v149
	v_mov_b32_e32 v149, v194
	v_cndmask_b32_e64 v194, 0, v216, s[40:41]
	v_sub_f32_e32 v149, v149, v194
	v_cndmask_b32_e64 v149, v168, v149, s[14:15]
	v_min_f32_e32 v168, 0, v150
	v_mul_f32_e64 v150, |v150|, s57
	v_exp_f32_e32 v150, v150
	s_nop 0
	v_add_f32_e32 v150, 1.0, v150
	v_log_f32_e32 v150, v150
	s_nop 0
	v_mul_f32_e32 v194, 0x3f317217, v150
	v_fma_f32 v194, v150, s52, -v194
	v_fmac_f32_e32 v194, 0x3377d1cf, v150
	v_fmac_f32_e32 v194, 0x3f317217, v150
	v_mov_b32_e32 v150, v194
	v_sub_f32_e32 v150, v168, v150
	v_min_f32_e32 v168, 0, v146
	v_mul_f32_e64 v146, |v146|, s57
	v_exp_f32_e32 v146, v146
	s_nop 0
	v_add_f32_e32 v146, 1.0, v146
	v_log_f32_e32 v146, v146
	s_nop 0
	v_mul_f32_e32 v194, 0x3f317217, v146
	v_fma_f32 v194, v146, s52, -v194
	v_fmac_f32_e32 v194, 0x3377d1cf, v146
	v_fmac_f32_e32 v194, 0x3f317217, v146
	v_mov_b32_e32 v146, v194
	v_sub_f32_e32 v168, v168, v146
	v_mul_f32_e32 v146, 0x3fb8aa3b, v150
	v_exp_f32_e32 v146, v146
	s_nop 0
	v_fma_f32 v146, v179, v146, v134
	v_cmp_gt_f32_e64 s[40:41], s97, v146
	s_nop 1
	v_cndmask_b32_e64 v194, 0, 32, s[40:41]
	v_ldexp_f32 v146, v146, v194
	v_log_f32_e32 v146, v146
	s_nop 0
	v_mul_f32_e32 v194, 0x3f317217, v146
	v_fma_f32 v194, v146, s52, -v194
	v_fmac_f32_e32 v194, 0x3377d1cf, v146
	v_fmac_f32_e32 v194, 0x3f317217, v146
	v_mov_b32_e32 v146, v194
	v_cndmask_b32_e64 v194, 0, v216, s[40:41]
	v_sub_f32_e32 v146, v146, v194
	v_cndmask_b32_e64 v146, v150, v146, s[12:13]
	v_mul_f32_e32 v150, 0x3fb8aa3b, v168
	v_exp_f32_e32 v150, v150
	s_nop 0
	v_fma_f32 v150, v178, v150, v130
	v_cmp_gt_f32_e64 s[40:41], s97, v150
	s_nop 1
	v_cndmask_b32_e64 v194, 0, 32, s[40:41]
	v_ldexp_f32 v150, v150, v194
	v_log_f32_e32 v150, v150
	s_nop 0
	v_mul_f32_e32 v194, 0x3f317217, v150
	v_fma_f32 v194, v150, s52, -v194
	v_fmac_f32_e32 v194, 0x3377d1cf, v150
	v_fmac_f32_e32 v194, 0x3f317217, v150
	v_mov_b32_e32 v150, v194
	v_cndmask_b32_e64 v194, 0, v216, s[40:41]
	v_sub_f32_e32 v150, v150, v194
	v_cndmask_b32_e64 v150, v168, v150, s[10:11]
	v_min_f32_e32 v168, 0, v151
	v_mul_f32_e64 v151, |v151|, s57
	v_exp_f32_e32 v151, v151
	s_nop 0
	v_add_f32_e32 v151, 1.0, v151
	v_log_f32_e32 v151, v151
	s_nop 0
	v_mul_f32_e32 v194, 0x3f317217, v151
	v_fma_f32 v194, v151, s52, -v194
	v_fmac_f32_e32 v194, 0x3377d1cf, v151
	v_fmac_f32_e32 v194, 0x3f317217, v151
	v_mov_b32_e32 v151, v194
	v_sub_f32_e32 v151, v168, v151
	v_min_f32_e32 v168, 0, v147
	v_mul_f32_e64 v147, |v147|, s57
	v_exp_f32_e32 v147, v147
	s_nop 0
	v_add_f32_e32 v147, 1.0, v147
	v_log_f32_e32 v147, v147
	s_nop 0
	v_mul_f32_e32 v194, 0x3f317217, v147
	v_fma_f32 v194, v147, s52, -v194
	v_fmac_f32_e32 v194, 0x3377d1cf, v147
	v_fmac_f32_e32 v194, 0x3f317217, v147
	v_mov_b32_e32 v147, v194
	v_sub_f32_e32 v168, v168, v147
	v_mul_f32_e32 v147, 0x3fb8aa3b, v151
	v_exp_f32_e32 v147, v147
	s_nop 0
	v_fma_f32 v147, v177, v147, v135
	v_cmp_gt_f32_e64 s[40:41], s97, v147
	s_nop 1
	v_cndmask_b32_e64 v194, 0, 32, s[40:41]
	v_ldexp_f32 v147, v147, v194
	v_log_f32_e32 v147, v147
	s_nop 0
	v_mul_f32_e32 v194, 0x3f317217, v147
	v_fma_f32 v194, v147, s52, -v194
	v_fmac_f32_e32 v194, 0x3377d1cf, v147
	v_fmac_f32_e32 v194, 0x3f317217, v147
	v_mov_b32_e32 v147, v194
	v_cndmask_b32_e64 v194, 0, v216, s[40:41]
	v_sub_f32_e32 v147, v147, v194
	v_cndmask_b32_e64 v147, v151, v147, s[8:9]
	v_mul_f32_e32 v151, 0x3fb8aa3b, v168
	v_exp_f32_e32 v151, v151
	s_nop 0
	v_fma_f32 v151, v167, v151, v131
	v_cmp_gt_f32_e64 s[40:41], s97, v151
	s_nop 1
	v_cndmask_b32_e64 v194, 0, 32, s[40:41]
	v_ldexp_f32 v151, v151, v194
	v_log_f32_e32 v151, v151
	s_nop 0
	v_mul_f32_e32 v194, 0x3f317217, v151
	v_fma_f32 v194, v151, s52, -v194
	v_fmac_f32_e32 v194, 0x3377d1cf, v151
	v_fmac_f32_e32 v194, 0x3f317217, v151
	v_mov_b32_e32 v151, v194
	v_cndmask_b32_e64 v194, 0, v216, s[40:41]
	v_sub_f32_e32 v151, v151, v194
	v_cndmask_b32_e32 v151, v168, v151, vcc
	global_store_dwordx4 v[170:171], v[144:147], off offset:512
	global_store_dwordx4 v[170:171], v[148:151], off offset:528
	s_nop 1
	v_add_u32_e32 v148, 0xa0, v166
	v_ashrrev_i32_e32 v149, 31, v148
	v_lshlrev_b64 v[144:145], 6, v[148:149]
	v_lshl_add_u64 v[144:145], v[160:161], 0, v[144:145]
	s_nop 0
	s_waitcnt lgkmcnt(0)
	s_nop 3
	s_nop 0
	s_nop 1
	s_waitcnt lgkmcnt(0)
	s_nop 1
	s_waitcnt lgkmcnt(0)
; __device__ __forceinline__ float silu_f(float x) { return x * __builtin_amdgcn_rcpf(1.f + __expf(-x)); }
; __device__ __forceinline__ v4u pack8(const f32x4 a, const f32x4 b) { v4u w; w.x = cvt_pk_bf16(a[0], a[1]); w.y = cvt_pk_bf16(a[2], a[3]); w.z = cvt_pk_bf16(b[0], b[1]); w.w = cvt_pk_bf16(b[2], b[3]); return w; }
;     __device__ __forceinline__ void operator()(const f32x4 (&acc)[2][2][4][2], const pg8::Unit& u, int wr, int wc, int fr, int fq) const {
;     ...
;         if (grp == 0) { WIN_LOOP( _Pragma("unroll") for (int i = 0; i < 4; ++i) { a[i] = silu_f(a[i]); b[i] = silu_f(b[i]); } *(v4u*)(QO + (size_t)row * DM + c) = pack8(a, b); ) }
;         else if (grp == 3) { WIN_LOOP( _Pragma("unroll") for (int i = 0; i < 4; ++i) { a[i] = silu_f(a[i]); b[i] = silu_f(b[i]); } *(v4u*)(GH + (size_t)row * 512 + c) = pack8(a, b); ) }
;         else if (grp == 1) {
;             f32x4 l0[2], l1[2];
; #pragma unroll
;             for (int bj = 0; bj < 2; ++bj) { l0[bj] = *(const f32x4*)(lb + cb + bj * 128); l1[bj] = *(const f32x4*)(lb + cb + bj * 128 + 4); }
;             WIN_LOOP( _Pragma("unroll") for (int i = 0; i < 4; ++i) { const float s0 = fminf(a[i], 0.f) - __logf(1.f + __expf(-fabsf(a[i]))), s1 = fminf(b[i], 0.f) - __logf(1.f + __expf(-fabsf(b[i]))); const float la = l0[bj][i], lbv = l1[bj][i];
;                     a[i] = la > 0.f ? __logf(la + (1.f - la) * __expf(s0)) : s0; b[i] = lbv > 0.f ? __logf(lbv + (1.f - lbv) * __expf(s1)) : s1; }
;                 *(f32x4*)(LF + (size_t)row * 512 + c) = a; *(f32x4*)(LF + (size_t)row * 512 + c + 4) = b; __builtin_amdgcn_sched_barrier(0); ) }
	s_nop 1
	v_mov_b32_e32 v168, v241
	v_lshlrev_b64 v[144:145], 11, v[148:149]
	v_lshl_add_u64 v[170:171], s[50:51], 0, v[144:145]
	v_lshl_add_u64 v[170:171], v[170:171], 0, v[192:193]
	v_pk_mul_f32 v[148:149], v[12:13], v[168:169] op_sel_hi:[1,0]
	v_pk_mul_f32 v[144:145], v[8:9], v[168:169] op_sel_hi:[1,0]
	v_min_f32_e32 v194, 0, v148
	v_mul_f32_e64 v148, |v148|, s57
	v_exp_f32_e32 v148, v148
	v_pk_mul_f32 v[150:151], v[14:15], v[168:169] op_sel_hi:[1,0]
	v_pk_mul_f32 v[146:147], v[10:11], v[168:169] op_sel_hi:[1,0]
	v_add_f32_e32 v148, 1.0, v148
	v_log_f32_e32 v148, v148
	s_nop 0
	v_mul_f32_e32 v195, 0x3f317217, v148
	v_fma_f32 v195, v148, s52, -v195
	v_fmac_f32_e32 v195, 0x3377d1cf, v148
	v_fmac_f32_e32 v195, 0x3f317217, v148
	v_mov_b32_e32 v148, v195
	v_sub_f32_e32 v148, v194, v148
	v_min_f32_e32 v194, 0, v144
	v_mul_f32_e64 v144, |v144|, s57
	v_exp_f32_e32 v144, v144
	s_nop 0
	v_add_f32_e32 v144, 1.0, v144
	v_log_f32_e32 v144, v144
	s_nop 0
	v_mul_f32_e32 v195, 0x3f317217, v144
	v_fma_f32 v195, v144, s52, -v195
	v_fmac_f32_e32 v195, 0x3377d1cf, v144
	v_fmac_f32_e32 v195, 0x3f317217, v144
	v_mov_b32_e32 v144, v195
	v_sub_f32_e32 v194, v194, v144
	v_mul_f32_e32 v144, 0x3fb8aa3b, v148
	v_exp_f32_e32 v144, v144
	s_nop 0
	v_fma_f32 v144, v190, v144, v140
	v_cmp_gt_f32_e64 s[40:41], s97, v144
	s_nop 1
	v_cndmask_b32_e64 v195, 0, 32, s[40:41]
	v_ldexp_f32 v144, v144, v195
	v_log_f32_e32 v144, v144
	s_nop 0
	v_mul_f32_e32 v195, 0x3f317217, v144
	v_fma_f32 v195, v144, s52, -v195
	v_fmac_f32_e32 v195, 0x3377d1cf, v144
	v_fmac_f32_e32 v195, 0x3f317217, v144
	v_mov_b32_e32 v144, v195
	v_cndmask_b32_e64 v195, 0, v216, s[40:41]
	v_sub_f32_e32 v144, v144, v195
	v_cndmask_b32_e64 v144, v148, v144, s[38:39]
	v_mul_f32_e32 v148, 0x3fb8aa3b, v194
	v_exp_f32_e32 v148, v148
	s_nop 0
	v_fma_f32 v148, v191, v148, v136
	v_cmp_gt_f32_e64 s[40:41], s97, v148
	s_nop 1
	v_cndmask_b32_e64 v195, 0, 32, s[40:41]
	v_ldexp_f32 v148, v148, v195
	v_log_f32_e32 v148, v148
	s_nop 0
	v_mul_f32_e32 v195, 0x3f317217, v148
	v_fma_f32 v195, v148, s52, -v195
	v_fmac_f32_e32 v195, 0x3377d1cf, v148
	v_fmac_f32_e32 v195, 0x3f317217, v148
	v_mov_b32_e32 v148, v195
	v_cndmask_b32_e64 v195, 0, v216, s[40:41]
	v_sub_f32_e32 v148, v148, v195
	v_cndmask_b32_e64 v148, v194, v148, s[36:37]
	v_min_f32_e32 v194, 0, v149
	v_mul_f32_e64 v149, |v149|, s57
	v_exp_f32_e32 v149, v149
	s_nop 0
	v_add_f32_e32 v149, 1.0, v149
	v_log_f32_e32 v149, v149
	s_nop 0
	v_mul_f32_e32 v195, 0x3f317217, v149
	v_fma_f32 v195, v149, s52, -v195
	v_fmac_f32_e32 v195, 0x3377d1cf, v149
	v_fmac_f32_e32 v195, 0x3f317217, v149
	v_mov_b32_e32 v149, v195
	v_sub_f32_e32 v149, v194, v149
	v_min_f32_e32 v194, 0, v145
	v_mul_f32_e64 v145, |v145|, s57
	v_exp_f32_e32 v145, v145
	s_nop 0
	v_add_f32_e32 v145, 1.0, v145
	v_log_f32_e32 v145, v145
	s_nop 0
	v_mul_f32_e32 v195, 0x3f317217, v145
	v_fma_f32 v195, v145, s52, -v195
	v_fmac_f32_e32 v195, 0x3377d1cf, v145
	v_fmac_f32_e32 v195, 0x3f317217, v145
	v_mov_b32_e32 v145, v195
	v_sub_f32_e32 v194, v194, v145
	v_mul_f32_e32 v145, 0x3fb8aa3b, v149
	v_exp_f32_e32 v145, v145
	s_nop 0
	v_fma_f32 v145, v188, v145, v141
	v_cmp_gt_f32_e64 s[40:41], s97, v145
	s_nop 1
	v_cndmask_b32_e64 v195, 0, 32, s[40:41]
	v_ldexp_f32 v145, v145, v195
	v_log_f32_e32 v145, v145
	s_nop 0
	v_mul_f32_e32 v195, 0x3f317217, v145
	v_fma_f32 v195, v145, s52, -v195
	v_fmac_f32_e32 v195, 0x3377d1cf, v145
	v_fmac_f32_e32 v195, 0x3f317217, v145
	v_mov_b32_e32 v145, v195
	v_cndmask_b32_e64 v195, 0, v216, s[40:41]
	v_sub_f32_e32 v145, v145, v195
	v_cndmask_b32_e64 v145, v149, v145, s[34:35]
	v_mul_f32_e32 v149, 0x3fb8aa3b, v194
	v_exp_f32_e32 v149, v149
	s_nop 0
	v_fma_f32 v149, v189, v149, v137
	v_cmp_gt_f32_e64 s[40:41], s97, v149
	s_nop 1
	v_cndmask_b32_e64 v195, 0, 32, s[40:41]
	v_ldexp_f32 v149, v149, v195
	v_log_f32_e32 v149, v149
	s_nop 0
	v_mul_f32_e32 v195, 0x3f317217, v149
	v_fma_f32 v195, v149, s52, -v195
	v_fmac_f32_e32 v195, 0x3377d1cf, v149
	v_fmac_f32_e32 v195, 0x3f317217, v149
	v_mov_b32_e32 v149, v195
	v_cndmask_b32_e64 v195, 0, v216, s[40:41]
	v_sub_f32_e32 v149, v149, v195
	v_cndmask_b32_e64 v149, v194, v149, s[30:31]
	v_min_f32_e32 v194, 0, v150
	v_mul_f32_e64 v150, |v150|, s57
	v_exp_f32_e32 v150, v150
	s_nop 0
	v_add_f32_e32 v150, 1.0, v150
	v_log_f32_e32 v150, v150
	s_nop 0
	v_mul_f32_e32 v195, 0x3f317217, v150
	v_fma_f32 v195, v150, s52, -v195
	v_fmac_f32_e32 v195, 0x3377d1cf, v150
	v_fmac_f32_e32 v195, 0x3f317217, v150
	v_mov_b32_e32 v150, v195
	v_sub_f32_e32 v150, v194, v150
	v_min_f32_e32 v194, 0, v146
	v_mul_f32_e64 v146, |v146|, s57
	v_exp_f32_e32 v146, v146
	s_nop 0
	v_add_f32_e32 v146, 1.0, v146
	v_log_f32_e32 v146, v146
	s_nop 0
	v_mul_f32_e32 v195, 0x3f317217, v146
	v_fma_f32 v195, v146, s52, -v195
	v_fmac_f32_e32 v195, 0x3377d1cf, v146
	v_fmac_f32_e32 v195, 0x3f317217, v146
	v_mov_b32_e32 v146, v195
	v_sub_f32_e32 v194, v194, v146
	v_mul_f32_e32 v146, 0x3fb8aa3b, v150
	v_exp_f32_e32 v146, v146
	s_nop 0
	v_fma_f32 v146, v187, v146, v142
	v_cmp_gt_f32_e64 s[40:41], s97, v146
	s_nop 1
	v_cndmask_b32_e64 v195, 0, 32, s[40:41]
	v_ldexp_f32 v146, v146, v195
	v_log_f32_e32 v146, v146
	s_nop 0
	v_mul_f32_e32 v195, 0x3f317217, v146
	v_fma_f32 v195, v146, s52, -v195
	v_fmac_f32_e32 v195, 0x3377d1cf, v146
	v_fmac_f32_e32 v195, 0x3f317217, v146
	v_mov_b32_e32 v146, v195
	v_cndmask_b32_e64 v195, 0, v216, s[40:41]
	v_sub_f32_e32 v146, v146, v195
	v_cndmask_b32_e64 v146, v150, v146, s[28:29]
	v_mul_f32_e32 v150, 0x3fb8aa3b, v194
	v_exp_f32_e32 v150, v150
	s_nop 0
	v_fma_f32 v150, v186, v150, v138
	v_cmp_gt_f32_e64 s[40:41], s97, v150
	s_nop 1
	v_cndmask_b32_e64 v195, 0, 32, s[40:41]
; __device__ __forceinline__ float silu_f(float x) { return x * __builtin_amdgcn_rcpf(1.f + __expf(-x)); }
; __device__ __forceinline__ v4u pack8(const f32x4 a, const f32x4 b) { v4u w; w.x = cvt_pk_bf16(a[0], a[1]); w.y = cvt_pk_bf16(a[2], a[3]); w.z = cvt_pk_bf16(b[0], b[1]); w.w = cvt_pk_bf16(b[2], b[3]); return w; }
;     __device__ __forceinline__ void operator()(const f32x4 (&acc)[2][2][4][2], const pg8::Unit& u, int wr, int wc, int fr, int fq) const {
;     ...
;         if (grp == 0) { WIN_LOOP( _Pragma("unroll") for (int i = 0; i < 4; ++i) { a[i] = silu_f(a[i]); b[i] = silu_f(b[i]); } *(v4u*)(QO + (size_t)row * DM + c) = pack8(a, b); ) }
;         else if (grp == 3) { WIN_LOOP( _Pragma("unroll") for (int i = 0; i < 4; ++i) { a[i] = silu_f(a[i]); b[i] = silu_f(b[i]); } *(v4u*)(GH + (size_t)row * 512 + c) = pack8(a, b); ) }
;         else if (grp == 1) {
;             f32x4 l0[2], l1[2];
; #pragma unroll
;             for (int bj = 0; bj < 2; ++bj) { l0[bj] = *(const f32x4*)(lb + cb + bj * 128); l1[bj] = *(const f32x4*)(lb + cb + bj * 128 + 4); }
;             WIN_LOOP( _Pragma("unroll") for (int i = 0; i < 4; ++i) { const float s0 = fminf(a[i], 0.f) - __logf(1.f + __expf(-fabsf(a[i]))), s1 = fminf(b[i], 0.f) - __logf(1.f + __expf(-fabsf(b[i]))); const float la = l0[bj][i], lbv = l1[bj][i];
;                     a[i] = la > 0.f ? __logf(la + (1.f - la) * __expf(s0)) : s0; b[i] = lbv > 0.f ? __logf(lbv + (1.f - lbv) * __expf(s1)) : s1; }
;                 *(f32x4*)(LF + (size_t)row * 512 + c) = a; *(f32x4*)(LF + (size_t)row * 512 + c + 4) = b; __builtin_amdgcn_sched_barrier(0); ) }
	v_ldexp_f32 v150, v150, v195
	v_log_f32_e32 v150, v150
	s_nop 0
	v_mul_f32_e32 v195, 0x3f317217, v150
	v_fma_f32 v195, v150, s52, -v195
	v_fmac_f32_e32 v195, 0x3377d1cf, v150
	v_fmac_f32_e32 v195, 0x3f317217, v150
	v_mov_b32_e32 v150, v195
	v_cndmask_b32_e64 v195, 0, v216, s[40:41]
	v_sub_f32_e32 v150, v150, v195
	v_cndmask_b32_e64 v150, v194, v150, s[26:27]
	v_min_f32_e32 v194, 0, v151
	v_mul_f32_e64 v151, |v151|, s57
	v_exp_f32_e32 v151, v151
	s_nop 0
	v_add_f32_e32 v151, 1.0, v151
	v_log_f32_e32 v151, v151
	s_nop 0
	v_mul_f32_e32 v195, 0x3f317217, v151
	v_fma_f32 v195, v151, s52, -v195
	v_fmac_f32_e32 v195, 0x3377d1cf, v151
	v_fmac_f32_e32 v195, 0x3f317217, v151
	v_mov_b32_e32 v151, v195
	v_sub_f32_e32 v151, v194, v151
	v_min_f32_e32 v194, 0, v147
	v_mul_f32_e64 v147, |v147|, s57
	v_exp_f32_e32 v147, v147
	s_nop 0
	v_add_f32_e32 v147, 1.0, v147
	v_log_f32_e32 v147, v147
	s_nop 0
	v_mul_f32_e32 v195, 0x3f317217, v147
	v_fma_f32 v195, v147, s52, -v195
	v_fmac_f32_e32 v195, 0x3377d1cf, v147
	v_fmac_f32_e32 v195, 0x3f317217, v147
	v_mov_b32_e32 v147, v195
	v_sub_f32_e32 v194, v194, v147
	v_mul_f32_e32 v147, 0x3fb8aa3b, v151
	v_exp_f32_e32 v147, v147
	s_nop 0
	v_fma_f32 v147, v185, v147, v143
	v_cmp_gt_f32_e64 s[40:41], s97, v147
	s_nop 1
	v_cndmask_b32_e64 v195, 0, 32, s[40:41]
	v_ldexp_f32 v147, v147, v195
	v_log_f32_e32 v147, v147
	s_nop 0
	v_mul_f32_e32 v195, 0x3f317217, v147
	v_fma_f32 v195, v147, s52, -v195
	v_fmac_f32_e32 v195, 0x3377d1cf, v147
	v_fmac_f32_e32 v195, 0x3f317217, v147
	v_mov_b32_e32 v147, v195
	v_cndmask_b32_e64 v195, 0, v216, s[40:41]
	v_sub_f32_e32 v147, v147, v195
	v_cndmask_b32_e64 v147, v151, v147, s[24:25]
	v_mul_f32_e32 v151, 0x3fb8aa3b, v194
	v_exp_f32_e32 v151, v151
	s_nop 0
	v_fma_f32 v151, v184, v151, v139
	v_cmp_gt_f32_e64 s[40:41], s97, v151
	s_nop 1
	v_cndmask_b32_e64 v195, 0, 32, s[40:41]
	v_ldexp_f32 v151, v151, v195
	v_log_f32_e32 v151, v151
	s_nop 0
	v_mul_f32_e32 v195, 0x3f317217, v151
	v_fma_f32 v195, v151, s52, -v195
	v_fmac_f32_e32 v195, 0x3377d1cf, v151
	v_fmac_f32_e32 v195, 0x3f317217, v151
	v_mov_b32_e32 v151, v195
	v_cndmask_b32_e64 v195, 0, v216, s[40:41]
	v_sub_f32_e32 v151, v151, v195
	v_cndmask_b32_e64 v151, v194, v151, s[22:23]
	global_store_dwordx4 v[170:171], v[144:147], off
	global_store_dwordx4 v[170:171], v[148:151], off offset:16
	s_nop 1
	v_pk_mul_f32 v[148:149], v[76:77], v[168:169] op_sel_hi:[1,0]
	v_pk_mul_f32 v[150:151], v[78:79], v[168:169] op_sel_hi:[1,0]
	v_pk_mul_f32 v[146:147], v[74:75], v[168:169] op_sel_hi:[1,0]
	v_pk_mul_f32 v[144:145], v[72:73], v[168:169] op_sel_hi:[1,0]
	v_min_f32_e32 v168, 0, v148
	v_mul_f32_e64 v148, |v148|, s57
	v_exp_f32_e32 v148, v148
	s_nop 0
	v_add_f32_e32 v148, 1.0, v148
	v_log_f32_e32 v148, v148
	s_nop 0
	v_mul_f32_e32 v194, 0x3f317217, v148
	v_fma_f32 v194, v148, s52, -v194
	v_fmac_f32_e32 v194, 0x3377d1cf, v148
	v_fmac_f32_e32 v194, 0x3f317217, v148
	v_mov_b32_e32 v148, v194
	v_sub_f32_e32 v148, v168, v148
	v_min_f32_e32 v168, 0, v144
	v_mul_f32_e64 v144, |v144|, s57
	v_exp_f32_e32 v144, v144
	s_nop 0
	v_add_f32_e32 v144, 1.0, v144
	v_log_f32_e32 v144, v144
	s_nop 0
	v_mul_f32_e32 v194, 0x3f317217, v144
	v_fma_f32 v194, v144, s52, -v194
	v_fmac_f32_e32 v194, 0x3377d1cf, v144
	v_fmac_f32_e32 v194, 0x3f317217, v144
	v_mov_b32_e32 v144, v194
	v_sub_f32_e32 v168, v168, v144
	v_mul_f32_e32 v144, 0x3fb8aa3b, v148
	v_exp_f32_e32 v144, v144
	s_nop 0
	v_fma_f32 v144, v183, v144, v132
	v_cmp_gt_f32_e64 s[40:41], s97, v144
	s_nop 1
	v_cndmask_b32_e64 v194, 0, 32, s[40:41]
	v_ldexp_f32 v144, v144, v194
	v_log_f32_e32 v144, v144
	s_nop 0
	v_mul_f32_e32 v194, 0x3f317217, v144
	v_fma_f32 v194, v144, s52, -v194
	v_fmac_f32_e32 v194, 0x3377d1cf, v144
	v_fmac_f32_e32 v194, 0x3f317217, v144
	v_mov_b32_e32 v144, v194
	v_cndmask_b32_e64 v194, 0, v216, s[40:41]
	v_sub_f32_e32 v144, v144, v194
	v_cndmask_b32_e64 v144, v148, v144, s[20:21]
	v_mul_f32_e32 v148, 0x3fb8aa3b, v168
	v_exp_f32_e32 v148, v148
	s_nop 0
	v_fma_f32 v148, v182, v148, v128
	v_cmp_gt_f32_e64 s[40:41], s97, v148
	s_nop 1
	v_cndmask_b32_e64 v194, 0, 32, s[40:41]
	v_ldexp_f32 v148, v148, v194
	v_log_f32_e32 v148, v148
	s_nop 0
	v_mul_f32_e32 v194, 0x3f317217, v148
	v_fma_f32 v194, v148, s52, -v194
	v_fmac_f32_e32 v194, 0x3377d1cf, v148
	v_fmac_f32_e32 v194, 0x3f317217, v148
	v_mov_b32_e32 v148, v194
	v_cndmask_b32_e64 v194, 0, v216, s[40:41]
	v_sub_f32_e32 v148, v148, v194
	v_cndmask_b32_e64 v148, v168, v148, s[18:19]
	v_min_f32_e32 v168, 0, v149
	v_mul_f32_e64 v149, |v149|, s57
	v_exp_f32_e32 v149, v149
	s_nop 0
	v_add_f32_e32 v149, 1.0, v149
	v_log_f32_e32 v149, v149
	s_nop 0
	v_mul_f32_e32 v194, 0x3f317217, v149
	v_fma_f32 v194, v149, s52, -v194
	v_fmac_f32_e32 v194, 0x3377d1cf, v149
	v_fmac_f32_e32 v194, 0x3f317217, v149
	v_mov_b32_e32 v149, v194
	v_sub_f32_e32 v149, v168, v149
	v_min_f32_e32 v168, 0, v145
	v_mul_f32_e64 v145, |v145|, s57
	v_exp_f32_e32 v145, v145
	s_nop 0
	v_add_f32_e32 v145, 1.0, v145
	v_log_f32_e32 v145, v145
	s_nop 0
	v_mul_f32_e32 v194, 0x3f317217, v145
	v_fma_f32 v194, v145, s52, -v194
	v_fmac_f32_e32 v194, 0x3377d1cf, v145
	v_fmac_f32_e32 v194, 0x3f317217, v145
	v_mov_b32_e32 v145, v194
	v_sub_f32_e32 v168, v168, v145
	v_mul_f32_e32 v145, 0x3fb8aa3b, v149
	v_exp_f32_e32 v145, v145
	s_nop 0
	v_fma_f32 v145, v181, v145, v133
	v_cmp_gt_f32_e64 s[40:41], s97, v145
	s_nop 1
	v_cndmask_b32_e64 v194, 0, 32, s[40:41]
	v_ldexp_f32 v145, v145, v194
	v_log_f32_e32 v145, v145
	s_nop 0
	v_mul_f32_e32 v194, 0x3f317217, v145
	v_fma_f32 v194, v145, s52, -v194
	v_fmac_f32_e32 v194, 0x3377d1cf, v145
	v_fmac_f32_e32 v194, 0x3f317217, v145
	v_mov_b32_e32 v145, v194
;     __device__ __forceinline__ void operator()(const f32x4 (&acc)[2][2][4][2], const pg8::Unit& u, int wr, int wc, int fr, int fq) const {
;     ...
;             WIN_LOOP( _Pragma("unroll") for (int i = 0; i < 4; ++i) { const float s0 = fminf(a[i], 0.f) - __logf(1.f + __expf(-fabsf(a[i]))), s1 = fminf(b[i], 0.f) - __logf(1.f + __expf(-fabsf(b[i]))); const float la = l0[bj][i], lbv = l1[bj][i];
;                     a[i] = la > 0.f ? __logf(la + (1.f - la) * __expf(s0)) : s0; b[i] = lbv > 0.f ? __logf(lbv + (1.f - lbv) * __expf(s1)) : s1; }
;                 *(f32x4*)(LF + (size_t)row * 512 + c) = a; *(f32x4*)(LF + (size_t)row * 512 + c + 4) = b; __builtin_amdgcn_sched_barrier(0); ) }
	v_cndmask_b32_e64 v194, 0, v216, s[40:41]
	v_sub_f32_e32 v145, v145, v194
	v_cndmask_b32_e64 v145, v149, v145, s[16:17]
	v_mul_f32_e32 v149, 0x3fb8aa3b, v168
	v_exp_f32_e32 v149, v149
	s_nop 0
	v_fma_f32 v149, v180, v149, v129
	v_cmp_gt_f32_e64 s[40:41], s97, v149
	s_nop 1
	v_cndmask_b32_e64 v194, 0, 32, s[40:41]
	v_ldexp_f32 v149, v149, v194
	v_log_f32_e32 v149, v149
	s_nop 0
	v_mul_f32_e32 v194, 0x3f317217, v149
	v_fma_f32 v194, v149, s52, -v194
	v_fmac_f32_e32 v194, 0x3377d1cf, v149
	v_fmac_f32_e32 v194, 0x3f317217, v149
	v_mov_b32_e32 v149, v194
	v_cndmask_b32_e64 v194, 0, v216, s[40:41]
	v_sub_f32_e32 v149, v149, v194
	v_cndmask_b32_e64 v149, v168, v149, s[14:15]
	v_min_f32_e32 v168, 0, v150
	v_mul_f32_e64 v150, |v150|, s57
	v_exp_f32_e32 v150, v150
	s_nop 0
	v_add_f32_e32 v150, 1.0, v150
	v_log_f32_e32 v150, v150
	s_nop 0
	v_mul_f32_e32 v194, 0x3f317217, v150
	v_fma_f32 v194, v150, s52, -v194
	v_fmac_f32_e32 v194, 0x3377d1cf, v150
	v_fmac_f32_e32 v194, 0x3f317217, v150
	v_mov_b32_e32 v150, v194
	v_sub_f32_e32 v150, v168, v150
	v_min_f32_e32 v168, 0, v146
	v_mul_f32_e64 v146, |v146|, s57
	v_exp_f32_e32 v146, v146
	s_nop 0
	v_add_f32_e32 v146, 1.0, v146
	v_log_f32_e32 v146, v146
	s_nop 0
	v_mul_f32_e32 v194, 0x3f317217, v146
	v_fma_f32 v194, v146, s52, -v194
	v_fmac_f32_e32 v194, 0x3377d1cf, v146
	v_fmac_f32_e32 v194, 0x3f317217, v146
	v_mov_b32_e32 v146, v194
	v_sub_f32_e32 v168, v168, v146
	v_mul_f32_e32 v146, 0x3fb8aa3b, v150
	v_exp_f32_e32 v146, v146
	s_nop 0
	v_fma_f32 v146, v179, v146, v134
	v_cmp_gt_f32_e64 s[40:41], s97, v146
	s_nop 1
	v_cndmask_b32_e64 v194, 0, 32, s[40:41]
	v_ldexp_f32 v146, v146, v194
	v_log_f32_e32 v146, v146
	s_nop 0
	v_mul_f32_e32 v194, 0x3f317217, v146
	v_fma_f32 v194, v146, s52, -v194
	v_fmac_f32_e32 v194, 0x3377d1cf, v146
	v_fmac_f32_e32 v194, 0x3f317217, v146
	v_mov_b32_e32 v146, v194
	v_cndmask_b32_e64 v194, 0, v216, s[40:41]
	v_sub_f32_e32 v146, v146, v194
	v_cndmask_b32_e64 v146, v150, v146, s[12:13]
	v_mul_f32_e32 v150, 0x3fb8aa3b, v168
	v_exp_f32_e32 v150, v150
	s_nop 0
	v_fma_f32 v150, v178, v150, v130
	v_cmp_gt_f32_e64 s[40:41], s97, v150
	s_nop 1
	v_cndmask_b32_e64 v194, 0, 32, s[40:41]
	v_ldexp_f32 v150, v150, v194
	v_log_f32_e32 v150, v150
	s_nop 0
	v_mul_f32_e32 v194, 0x3f317217, v150
	v_fma_f32 v194, v150, s52, -v194
	v_fmac_f32_e32 v194, 0x3377d1cf, v150
	v_fmac_f32_e32 v194, 0x3f317217, v150
	v_mov_b32_e32 v150, v194
	v_cndmask_b32_e64 v194, 0, v216, s[40:41]
	v_sub_f32_e32 v150, v150, v194
	v_cndmask_b32_e64 v150, v168, v150, s[10:11]
	v_min_f32_e32 v168, 0, v151
	v_mul_f32_e64 v151, |v151|, s57
	v_exp_f32_e32 v151, v151
	s_nop 0
	v_add_f32_e32 v151, 1.0, v151
	v_log_f32_e32 v151, v151
	s_nop 0
	v_mul_f32_e32 v194, 0x3f317217, v151
	v_fma_f32 v194, v151, s52, -v194
	v_fmac_f32_e32 v194, 0x3377d1cf, v151
	v_fmac_f32_e32 v194, 0x3f317217, v151
	v_mov_b32_e32 v151, v194
	v_sub_f32_e32 v151, v168, v151
	v_min_f32_e32 v168, 0, v147
	v_mul_f32_e64 v147, |v147|, s57
	v_exp_f32_e32 v147, v147
	s_nop 0
	v_add_f32_e32 v147, 1.0, v147
	v_log_f32_e32 v147, v147
	s_nop 0
	v_mul_f32_e32 v194, 0x3f317217, v147
	v_fma_f32 v194, v147, s52, -v194
	v_fmac_f32_e32 v194, 0x3377d1cf, v147
	v_fmac_f32_e32 v194, 0x3f317217, v147
	v_mov_b32_e32 v147, v194
	v_sub_f32_e32 v168, v168, v147
	v_mul_f32_e32 v147, 0x3fb8aa3b, v151
	v_exp_f32_e32 v147, v147
	s_nop 0
	v_fma_f32 v147, v177, v147, v135
	v_cmp_gt_f32_e64 s[40:41], s97, v147
	s_nop 1
	v_cndmask_b32_e64 v194, 0, 32, s[40:41]
	v_ldexp_f32 v147, v147, v194
	v_log_f32_e32 v147, v147
	s_nop 0
	v_mul_f32_e32 v194, 0x3f317217, v147
	v_fma_f32 v194, v147, s52, -v194
	v_fmac_f32_e32 v194, 0x3377d1cf, v147
	v_fmac_f32_e32 v194, 0x3f317217, v147
	v_mov_b32_e32 v147, v194
	v_cndmask_b32_e64 v194, 0, v216, s[40:41]
	v_sub_f32_e32 v147, v147, v194
	v_cndmask_b32_e64 v147, v151, v147, s[8:9]
	v_mul_f32_e32 v151, 0x3fb8aa3b, v168
	v_exp_f32_e32 v151, v151
	s_nop 0
	v_fma_f32 v151, v167, v151, v131
	v_cmp_gt_f32_e64 s[40:41], s97, v151
	s_nop 1
	v_cndmask_b32_e64 v194, 0, 32, s[40:41]
	v_ldexp_f32 v151, v151, v194
	v_log_f32_e32 v151, v151
	s_nop 0
	v_mul_f32_e32 v194, 0x3f317217, v151
	v_fma_f32 v194, v151, s52, -v194
	v_fmac_f32_e32 v194, 0x3377d1cf, v151
	v_fmac_f32_e32 v194, 0x3f317217, v151
	v_mov_b32_e32 v151, v194
	v_cndmask_b32_e64 v194, 0, v216, s[40:41]
	v_sub_f32_e32 v151, v151, v194
	v_cndmask_b32_e32 v151, v168, v151, vcc
	global_store_dwordx4 v[170:171], v[144:147], off offset:512
	global_store_dwordx4 v[170:171], v[148:151], off offset:528
	s_nop 1
	v_add_u32_e32 v148, 0xb0, v166
	v_ashrrev_i32_e32 v149, 31, v148
	v_lshlrev_b64 v[144:145], 6, v[148:149]
	v_lshl_add_u64 v[144:145], v[160:161], 0, v[144:145]
	s_nop 0
	s_waitcnt lgkmcnt(0)
	s_nop 3
	v_lshlrev_b64 v[146:147], 11, v[148:149]
	s_nop 1
	v_lshl_add_u64 v[146:147], s[50:51], 0, v[146:147]
	v_lshl_add_u64 v[146:147], v[146:147], 0, v[192:193]
	s_waitcnt lgkmcnt(0)
	s_nop 1
	s_waitcnt lgkmcnt(0)
; __device__ __forceinline__ float silu_f(float x) { return x * __builtin_amdgcn_rcpf(1.f + __expf(-x)); }
; __device__ __forceinline__ v4u pack8(const f32x4 a, const f32x4 b) { v4u w; w.x = cvt_pk_bf16(a[0], a[1]); w.y = cvt_pk_bf16(a[2], a[3]); w.z = cvt_pk_bf16(b[0], b[1]); w.w = cvt_pk_bf16(b[2], b[3]); return w; }
;     __device__ __forceinline__ void operator()(const f32x4 (&acc)[2][2][4][2], const pg8::Unit& u, int wr, int wc, int fr, int fq) const {
;     ...
;         if (grp == 0) { WIN_LOOP( _Pragma("unroll") for (int i = 0; i < 4; ++i) { a[i] = silu_f(a[i]); b[i] = silu_f(b[i]); } *(v4u*)(QO + (size_t)row * DM + c) = pack8(a, b); ) }
;         else if (grp == 3) { WIN_LOOP( _Pragma("unroll") for (int i = 0; i < 4; ++i) { a[i] = silu_f(a[i]); b[i] = silu_f(b[i]); } *(v4u*)(GH + (size_t)row * 512 + c) = pack8(a, b); ) }
;         else if (grp == 1) {
;             f32x4 l0[2], l1[2];
; #pragma unroll
;             for (int bj = 0; bj < 2; ++bj) { l0[bj] = *(const f32x4*)(lb + cb + bj * 128); l1[bj] = *(const f32x4*)(lb + cb + bj * 128 + 4); }
;             WIN_LOOP( _Pragma("unroll") for (int i = 0; i < 4; ++i) { const float s0 = fminf(a[i], 0.f) - __logf(1.f + __expf(-fabsf(a[i]))), s1 = fminf(b[i], 0.f) - __logf(1.f + __expf(-fabsf(b[i]))); const float la = l0[bj][i], lbv = l1[bj][i];
;                     a[i] = la > 0.f ? __logf(la + (1.f - la) * __expf(s0)) : s0; b[i] = lbv > 0.f ? __logf(lbv + (1.f - lbv) * __expf(s1)) : s1; }
;                 *(f32x4*)(LF + (size_t)row * 512 + c) = a; *(f32x4*)(LF + (size_t)row * 512 + c + 4) = b; __builtin_amdgcn_sched_barrier(0); ) }
	s_nop 1
	v_mov_b32_e32 v144, v245
	s_nop 0
	v_pk_mul_f32 v[170:171], v[4:5], v[144:145] op_sel_hi:[1,0]
	v_pk_mul_f32 v[150:151], v[6:7], v[144:145] op_sel_hi:[1,0]
	v_pk_mul_f32 v[148:149], v[2:3], v[144:145] op_sel_hi:[1,0]
	v_pk_mul_f32 v[168:169], v[0:1], v[144:145] op_sel_hi:[1,0]
	v_min_f32_e32 v145, 0, v170
	v_mul_f32_e64 v170, |v170|, s57
	v_exp_f32_e32 v170, v170
	s_nop 0
	v_add_f32_e32 v170, 1.0, v170
	v_log_f32_e32 v170, v170
	s_nop 0
	v_mul_f32_e32 v194, 0x3f317217, v170
	v_fma_f32 v194, v170, s52, -v194
	v_fmac_f32_e32 v194, 0x3377d1cf, v170
	v_fmac_f32_e32 v194, 0x3f317217, v170
	v_mov_b32_e32 v170, v194
	v_sub_f32_e32 v145, v145, v170
	v_min_f32_e32 v170, 0, v168
	v_mul_f32_e64 v168, |v168|, s57
	v_exp_f32_e32 v168, v168
	s_nop 0
	v_add_f32_e32 v168, 1.0, v168
	v_log_f32_e32 v168, v168
	s_nop 0
	v_mul_f32_e32 v194, 0x3f317217, v168
	v_fma_f32 v194, v168, s52, -v194
	v_fmac_f32_e32 v194, 0x3377d1cf, v168
	v_fmac_f32_e32 v194, 0x3f317217, v168
	v_mov_b32_e32 v168, v194
	v_sub_f32_e32 v168, v170, v168
	v_mul_f32_e32 v170, 0x3fb8aa3b, v145
	v_exp_f32_e32 v170, v170
	s_nop 0
	v_fma_f32 v140, v190, v170, v140
	v_cmp_gt_f32_e64 s[40:41], s97, v140
	s_nop 1
	v_cndmask_b32_e64 v170, 0, 32, s[40:41]
	v_ldexp_f32 v140, v140, v170
	v_log_f32_e32 v140, v140
	s_nop 0
	v_mul_f32_e32 v170, 0x3f317217, v140
	v_fma_f32 v170, v140, s52, -v170
	v_fmac_f32_e32 v170, 0x3377d1cf, v140
	v_fmac_f32_e32 v170, 0x3f317217, v140
	v_mov_b32_e32 v140, v170
	v_cndmask_b32_e64 v170, 0, v216, s[40:41]
	v_sub_f32_e32 v140, v140, v170
	v_cndmask_b32_e64 v140, v145, v140, s[38:39]
	v_mul_f32_e32 v145, 0x3fb8aa3b, v168
	v_exp_f32_e32 v145, v145
	v_readlane_b32 s42, v255, 57
	v_readlane_b32 s43, v255, 58
	v_fma_f32 v136, v191, v145, v136
	v_cmp_gt_f32_e64 s[38:39], s97, v136
	s_nop 1
	v_cndmask_b32_e64 v145, 0, 32, s[38:39]
	v_ldexp_f32 v136, v136, v145
	v_log_f32_e32 v136, v136
	s_nop 0
	v_mul_f32_e32 v145, 0x3f317217, v136
	v_fma_f32 v145, v136, s52, -v145
	v_fmac_f32_e32 v145, 0x3377d1cf, v136
	v_fmac_f32_e32 v145, 0x3f317217, v136
	v_mov_b32_e32 v136, v145
	v_cndmask_b32_e64 v145, 0, v216, s[38:39]
	v_sub_f32_e32 v136, v136, v145
	v_cndmask_b32_e64 v136, v168, v136, s[36:37]
	v_mul_f32_e64 v168, |v171|, s57
	v_exp_f32_e32 v168, v168
	v_min_f32_e32 v145, 0, v171
	s_mov_b32 s40, s2
	v_add_f32_e32 v168, 1.0, v168
	v_log_f32_e32 v168, v168
	s_nop 0
	v_mul_f32_e32 v170, 0x3f317217, v168
	v_fma_f32 v170, v168, s52, -v170
	v_fmac_f32_e32 v170, 0x3377d1cf, v168
	v_fmac_f32_e32 v170, 0x3f317217, v168
	v_mov_b32_e32 v168, v170
	v_sub_f32_e32 v145, v145, v168
	v_min_f32_e32 v168, 0, v169
	v_mul_f32_e64 v169, |v169|, s57
	v_exp_f32_e32 v169, v169
	s_nop 0
	v_add_f32_e32 v169, 1.0, v169
	v_log_f32_e32 v169, v169
	s_nop 0
	v_mul_f32_e32 v170, 0x3f317217, v169
	v_fma_f32 v170, v169, s52, -v170
	v_fmac_f32_e32 v170, 0x3377d1cf, v169
	v_fmac_f32_e32 v170, 0x3f317217, v169
	v_mov_b32_e32 v169, v170
	v_sub_f32_e32 v168, v168, v169
	v_mul_f32_e32 v169, 0x3fb8aa3b, v145
	v_exp_f32_e32 v169, v169
	s_nop 0
	v_fma_f32 v141, v188, v169, v141
	v_cmp_gt_f32_e64 s[36:37], s97, v141
	s_nop 1
	v_cndmask_b32_e64 v169, 0, 32, s[36:37]
	v_ldexp_f32 v141, v141, v169
	v_log_f32_e32 v141, v141
	s_nop 0
	v_mul_f32_e32 v169, 0x3f317217, v141
	v_fma_f32 v169, v141, s52, -v169
	v_fmac_f32_e32 v169, 0x3377d1cf, v141
	v_fmac_f32_e32 v169, 0x3f317217, v141
	v_mov_b32_e32 v141, v169
	v_cndmask_b32_e64 v169, 0, v216, s[36:37]
	v_sub_f32_e32 v141, v141, v169
	v_cndmask_b32_e64 v141, v145, v141, s[34:35]
	v_mul_f32_e32 v145, 0x3fb8aa3b, v168
	v_exp_f32_e32 v145, v145
	v_readlane_b32 s38, v255, 53
	v_readlane_b32 s39, v255, 54
	v_fma_f32 v137, v189, v145, v137
	v_cmp_gt_f32_e64 s[34:35], s97, v137
	s_nop 1
	v_cndmask_b32_e64 v145, 0, 32, s[34:35]
	v_ldexp_f32 v137, v137, v145
	v_log_f32_e32 v137, v137
	s_nop 0
	v_mul_f32_e32 v145, 0x3f317217, v137
	v_fma_f32 v145, v137, s52, -v145
	v_fmac_f32_e32 v145, 0x3377d1cf, v137
	v_fmac_f32_e32 v145, 0x3f317217, v137
	v_mov_b32_e32 v137, v145
	v_cndmask_b32_e64 v145, 0, v216, s[34:35]
	v_sub_f32_e32 v137, v137, v145
	v_min_f32_e32 v145, 0, v150
	v_mul_f32_e64 v150, |v150|, s57
	v_exp_f32_e32 v150, v150
	v_cndmask_b32_e64 v137, v168, v137, s[30:31]
	v_readlane_b32 s36, v255, 51
	v_readlane_b32 s37, v255, 52
	v_add_f32_e32 v150, 1.0, v150
	v_log_f32_e32 v150, v150
	s_nop 0
	v_mul_f32_e32 v168, 0x3f317217, v150
	v_fma_f32 v168, v150, s52, -v168
	v_fmac_f32_e32 v168, 0x3377d1cf, v150
	v_fmac_f32_e32 v168, 0x3f317217, v150
	v_mov_b32_e32 v150, v168
	v_sub_f32_e32 v145, v145, v150
	v_min_f32_e32 v150, 0, v148
	v_mul_f32_e64 v148, |v148|, s57
	v_exp_f32_e32 v148, v148
	s_nop 0
	v_add_f32_e32 v148, 1.0, v148
	v_log_f32_e32 v148, v148
	s_nop 0
	v_mul_f32_e32 v168, 0x3f317217, v148
	v_fma_f32 v168, v148, s52, -v168
	v_fmac_f32_e32 v168, 0x3377d1cf, v148
	v_fmac_f32_e32 v168, 0x3f317217, v148
	v_mov_b32_e32 v148, v168
	v_sub_f32_e32 v148, v150, v148
	v_mul_f32_e32 v150, 0x3fb8aa3b, v145
	v_exp_f32_e32 v150, v150
	s_nop 0
	v_fma_f32 v142, v187, v150, v142
	v_cmp_gt_f32_e64 s[30:31], s97, v142
	s_nop 1
	v_cndmask_b32_e64 v150, 0, 32, s[30:31]
	v_ldexp_f32 v142, v142, v150
	v_log_f32_e32 v142, v142
	s_nop 0
	v_mul_f32_e32 v150, 0x3f317217, v142
	v_fma_f32 v150, v142, s52, -v150
	v_fmac_f32_e32 v150, 0x3377d1cf, v142
	v_fmac_f32_e32 v150, 0x3f317217, v142
	v_mov_b32_e32 v142, v150
	v_cndmask_b32_e64 v150, 0, v216, s[30:31]
	v_sub_f32_e32 v142, v142, v150
	v_cndmask_b32_e64 v142, v145, v142, s[28:29]
	v_mul_f32_e32 v145, 0x3fb8aa3b, v148
	v_exp_f32_e32 v145, v145
	v_readlane_b32 s34, v255, 49
	v_readlane_b32 s35, v255, 50
	v_fma_f32 v138, v186, v145, v138
	v_cmp_gt_f32_e64 s[28:29], s97, v138
; __device__ __forceinline__ float silu_f(float x) { return x * __builtin_amdgcn_rcpf(1.f + __expf(-x)); }
; __device__ __forceinline__ v4u pack8(const f32x4 a, const f32x4 b) { v4u w; w.x = cvt_pk_bf16(a[0], a[1]); w.y = cvt_pk_bf16(a[2], a[3]); w.z = cvt_pk_bf16(b[0], b[1]); w.w = cvt_pk_bf16(b[2], b[3]); return w; }
;     __device__ __forceinline__ void operator()(const f32x4 (&acc)[2][2][4][2], const pg8::Unit& u, int wr, int wc, int fr, int fq) const {
;     ...
;         if (grp == 0) { WIN_LOOP( _Pragma("unroll") for (int i = 0; i < 4; ++i) { a[i] = silu_f(a[i]); b[i] = silu_f(b[i]); } *(v4u*)(QO + (size_t)row * DM + c) = pack8(a, b); ) }
;         else if (grp == 3) { WIN_LOOP( _Pragma("unroll") for (int i = 0; i < 4; ++i) { a[i] = silu_f(a[i]); b[i] = silu_f(b[i]); } *(v4u*)(GH + (size_t)row * 512 + c) = pack8(a, b); ) }
;         else if (grp == 1) {
;             f32x4 l0[2], l1[2];
; #pragma unroll
;             for (int bj = 0; bj < 2; ++bj) { l0[bj] = *(const f32x4*)(lb + cb + bj * 128); l1[bj] = *(const f32x4*)(lb + cb + bj * 128 + 4); }
;             WIN_LOOP( _Pragma("unroll") for (int i = 0; i < 4; ++i) { const float s0 = fminf(a[i], 0.f) - __logf(1.f + __expf(-fabsf(a[i]))), s1 = fminf(b[i], 0.f) - __logf(1.f + __expf(-fabsf(b[i]))); const float la = l0[bj][i], lbv = l1[bj][i];
;                     a[i] = la > 0.f ? __logf(la + (1.f - la) * __expf(s0)) : s0; b[i] = lbv > 0.f ? __logf(lbv + (1.f - lbv) * __expf(s1)) : s1; }
;                 *(f32x4*)(LF + (size_t)row * 512 + c) = a; *(f32x4*)(LF + (size_t)row * 512 + c + 4) = b; __builtin_amdgcn_sched_barrier(0); ) }
	s_nop 1
	v_cndmask_b32_e64 v145, 0, 32, s[28:29]
	v_ldexp_f32 v138, v138, v145
	v_log_f32_e32 v138, v138
	s_nop 0
	v_mul_f32_e32 v145, 0x3f317217, v138
	v_fma_f32 v145, v138, s52, -v145
	v_fmac_f32_e32 v145, 0x3377d1cf, v138
	v_fmac_f32_e32 v145, 0x3f317217, v138
	v_mov_b32_e32 v138, v145
	v_cndmask_b32_e64 v145, 0, v216, s[28:29]
	v_sub_f32_e32 v138, v138, v145
	v_cndmask_b32_e64 v138, v148, v138, s[26:27]
	v_mul_f32_e64 v148, |v151|, s57
	v_exp_f32_e32 v148, v148
	v_min_f32_e32 v145, 0, v151
	v_readlane_b32 s30, v255, 47
	v_readlane_b32 s31, v255, 48
	v_add_f32_e32 v148, 1.0, v148
	v_log_f32_e32 v148, v148
	s_nop 0
	v_mul_f32_e32 v150, 0x3f317217, v148
	v_fma_f32 v150, v148, s52, -v150
	v_fmac_f32_e32 v150, 0x3377d1cf, v148
	v_fmac_f32_e32 v150, 0x3f317217, v148
	v_mov_b32_e32 v148, v150
	v_sub_f32_e32 v145, v145, v148
	v_min_f32_e32 v148, 0, v149
	v_mul_f32_e64 v149, |v149|, s57
	v_exp_f32_e32 v149, v149
	s_nop 0
	v_add_f32_e32 v149, 1.0, v149
	v_log_f32_e32 v149, v149
	s_nop 0
	v_mul_f32_e32 v150, 0x3f317217, v149
	v_fma_f32 v150, v149, s52, -v150
	v_fmac_f32_e32 v150, 0x3377d1cf, v149
	v_fmac_f32_e32 v150, 0x3f317217, v149
	v_mov_b32_e32 v149, v150
	v_sub_f32_e32 v148, v148, v149
	v_mul_f32_e32 v149, 0x3fb8aa3b, v145
	v_exp_f32_e32 v149, v149
	s_nop 0
	v_fmac_f32_e32 v143, v185, v149
	v_cmp_gt_f32_e64 s[26:27], s97, v143
	s_nop 1
	v_cndmask_b32_e64 v149, 0, 32, s[26:27]
	v_ldexp_f32 v143, v143, v149
	v_log_f32_e32 v143, v143
	s_nop 0
	v_mul_f32_e32 v149, 0x3f317217, v143
	v_fma_f32 v149, v143, s52, -v149
	v_fmac_f32_e32 v149, 0x3377d1cf, v143
	v_fmac_f32_e32 v149, 0x3f317217, v143
	v_cmp_lt_f32_e64 s[28:29], |v143|, s53
	s_nop 1
	v_cndmask_b32_e64 v143, v143, v149, s[28:29]
	v_cndmask_b32_e64 v149, 0, v216, s[26:27]
	v_sub_f32_e32 v143, v143, v149
	v_cndmask_b32_e64 v143, v145, v143, s[24:25]
	v_mul_f32_e32 v145, 0x3fb8aa3b, v148
	v_exp_f32_e32 v145, v145
	s_mov_b32 s29, s91
	s_mov_b32 s28, s95
	v_fmac_f32_e32 v139, v184, v145
	v_cmp_gt_f32_e64 s[24:25], s97, v139
	s_nop 1
	v_cndmask_b32_e64 v145, 0, 32, s[24:25]
	v_ldexp_f32 v139, v139, v145
	v_log_f32_e32 v139, v139
	s_nop 0
	v_mul_f32_e32 v145, 0x3f317217, v139
	v_fma_f32 v145, v139, s52, -v145
	v_fmac_f32_e32 v145, 0x3377d1cf, v139
	v_fmac_f32_e32 v145, 0x3f317217, v139
	v_cmp_lt_f32_e64 s[26:27], |v139|, s53
	s_nop 1
	v_cndmask_b32_e64 v139, v139, v145, s[26:27]
	v_cndmask_b32_e64 v145, 0, v216, s[24:25]
	v_readlane_b32 s27, v255, 56
	v_readlane_b32 s26, v255, 31
	v_sub_f32_e32 v139, v139, v145
	v_cndmask_b32_e64 v139, v148, v139, s[22:23]
	global_store_dwordx4 v[146:147], v[140:143], off
	global_store_dwordx4 v[146:147], v[136:139], off offset:16
	s_nop 0
	v_pk_mul_f32 v[142:143], v[68:69], v[144:145] op_sel_hi:[1,0]
	v_pk_mul_f32 v[138:139], v[70:71], v[144:145] op_sel_hi:[1,0]
	v_pk_mul_f32 v[136:137], v[66:67], v[144:145] op_sel_hi:[1,0]
	v_pk_mul_f32 v[140:141], v[64:65], v[144:145] op_sel_hi:[1,0]
	v_min_f32_e32 v144, 0, v142
	v_mul_f32_e64 v142, |v142|, s57
	v_exp_f32_e32 v142, v142
	s_nop 0
	v_add_f32_e32 v142, 1.0, v142
	v_log_f32_e32 v142, v142
	s_nop 0
	v_mul_f32_e32 v145, 0x3f317217, v142
	v_fma_f32 v145, v142, s52, -v145
	v_fmac_f32_e32 v145, 0x3377d1cf, v142
	v_fmac_f32_e32 v145, 0x3f317217, v142
	v_mov_b32_e32 v142, v145
	v_sub_f32_e32 v142, v144, v142
	v_min_f32_e32 v144, 0, v140
	v_mul_f32_e64 v140, |v140|, s57
	v_exp_f32_e32 v140, v140
	s_nop 0
	v_add_f32_e32 v140, 1.0, v140
	v_log_f32_e32 v140, v140
	s_nop 0
	v_mul_f32_e32 v145, 0x3f317217, v140
	v_fma_f32 v145, v140, s52, -v145
	v_fmac_f32_e32 v145, 0x3377d1cf, v140
	v_fmac_f32_e32 v145, 0x3f317217, v140
	v_mov_b32_e32 v140, v145
	v_sub_f32_e32 v140, v144, v140
	v_mul_f32_e32 v144, 0x3fb8aa3b, v142
	v_exp_f32_e32 v144, v144
	s_nop 0
	v_fma_f32 v132, v183, v144, v132
	v_cmp_gt_f32_e64 s[22:23], s97, v132
	s_nop 1
	v_cndmask_b32_e64 v144, 0, 32, s[22:23]
	v_ldexp_f32 v132, v132, v144
	v_log_f32_e32 v132, v132
	s_nop 0
	v_mul_f32_e32 v144, 0x3f317217, v132
	v_fma_f32 v144, v132, s52, -v144
	v_fmac_f32_e32 v144, 0x3377d1cf, v132
	v_fmac_f32_e32 v144, 0x3f317217, v132
	v_mov_b32_e32 v132, v144
	v_cndmask_b32_e64 v144, 0, v216, s[22:23]
	v_sub_f32_e32 v132, v132, v144
	v_cndmask_b32_e64 v132, v142, v132, s[20:21]
	v_mul_f32_e32 v142, 0x3fb8aa3b, v140
	v_exp_f32_e32 v142, v142
	s_nop 0
	v_fma_f32 v128, v182, v142, v128
	v_cmp_gt_f32_e64 s[20:21], s97, v128
	s_nop 1
	v_cndmask_b32_e64 v142, 0, 32, s[20:21]
	v_ldexp_f32 v128, v128, v142
	v_log_f32_e32 v128, v128
	s_nop 0
	v_mul_f32_e32 v142, 0x3f317217, v128
	v_fma_f32 v142, v128, s52, -v142
	v_fmac_f32_e32 v142, 0x3377d1cf, v128
	v_fmac_f32_e32 v142, 0x3f317217, v128
	v_mov_b32_e32 v128, v142
	v_cndmask_b32_e64 v142, 0, v216, s[20:21]
	v_sub_f32_e32 v128, v128, v142
	v_mul_f32_e64 v142, |v143|, s57
	v_exp_f32_e32 v142, v142
	v_cndmask_b32_e64 v128, v140, v128, s[18:19]
	v_min_f32_e32 v140, 0, v143
	v_readlane_b32 s23, v255, 55
	v_add_f32_e32 v142, 1.0, v142
	v_log_f32_e32 v142, v142
	s_nop 0
	v_mul_f32_e32 v143, 0x3f317217, v142
	v_fma_f32 v143, v142, s52, -v143
	v_fmac_f32_e32 v143, 0x3377d1cf, v142
	v_fmac_f32_e32 v143, 0x3f317217, v142
	v_mov_b32_e32 v142, v143
	v_sub_f32_e32 v140, v140, v142
	v_min_f32_e32 v142, 0, v141
	v_mul_f32_e64 v141, |v141|, s57
	v_exp_f32_e32 v141, v141
	s_nop 0
	v_add_f32_e32 v141, 1.0, v141
; __device__ __forceinline__ float silu_f(float x) { return x * __builtin_amdgcn_rcpf(1.f + __expf(-x)); }
; __device__ __forceinline__ v4u pack8(const f32x4 a, const f32x4 b) { v4u w; w.x = cvt_pk_bf16(a[0], a[1]); w.y = cvt_pk_bf16(a[2], a[3]); w.z = cvt_pk_bf16(b[0], b[1]); w.w = cvt_pk_bf16(b[2], b[3]); return w; }
;     __device__ __forceinline__ void operator()(const f32x4 (&acc)[2][2][4][2], const pg8::Unit& u, int wr, int wc, int fr, int fq) const {
;     ...
;         if (grp == 0) { WIN_LOOP( _Pragma("unroll") for (int i = 0; i < 4; ++i) { a[i] = silu_f(a[i]); b[i] = silu_f(b[i]); } *(v4u*)(QO + (size_t)row * DM + c) = pack8(a, b); ) }
;         else if (grp == 3) { WIN_LOOP( _Pragma("unroll") for (int i = 0; i < 4; ++i) { a[i] = silu_f(a[i]); b[i] = silu_f(b[i]); } *(v4u*)(GH + (size_t)row * 512 + c) = pack8(a, b); ) }
;         else if (grp == 1) {
;             f32x4 l0[2], l1[2];
; #pragma unroll
;             for (int bj = 0; bj < 2; ++bj) { l0[bj] = *(const f32x4*)(lb + cb + bj * 128); l1[bj] = *(const f32x4*)(lb + cb + bj * 128 + 4); }
;             WIN_LOOP( _Pragma("unroll") for (int i = 0; i < 4; ++i) { const float s0 = fminf(a[i], 0.f) - __logf(1.f + __expf(-fabsf(a[i]))), s1 = fminf(b[i], 0.f) - __logf(1.f + __expf(-fabsf(b[i]))); const float la = l0[bj][i], lbv = l1[bj][i];
;                     a[i] = la > 0.f ? __logf(la + (1.f - la) * __expf(s0)) : s0; b[i] = lbv > 0.f ? __logf(lbv + (1.f - lbv) * __expf(s1)) : s1; }
;                 *(f32x4*)(LF + (size_t)row * 512 + c) = a; *(f32x4*)(LF + (size_t)row * 512 + c + 4) = b; __builtin_amdgcn_sched_barrier(0); ) }
	v_log_f32_e32 v141, v141
	s_nop 0
	v_mul_f32_e32 v143, 0x3f317217, v141
	v_fma_f32 v143, v141, s52, -v143
	v_fmac_f32_e32 v143, 0x3377d1cf, v141
	v_fmac_f32_e32 v143, 0x3f317217, v141
	v_mov_b32_e32 v141, v143
	v_sub_f32_e32 v141, v142, v141
	v_mul_f32_e32 v142, 0x3fb8aa3b, v140
	v_exp_f32_e32 v142, v142
	s_nop 0
	v_fma_f32 v133, v181, v142, v133
	v_cmp_gt_f32_e64 s[18:19], s97, v133
	s_nop 1
	v_cndmask_b32_e64 v142, 0, 32, s[18:19]
	v_ldexp_f32 v133, v133, v142
	v_log_f32_e32 v133, v133
	s_nop 0
	v_mul_f32_e32 v142, 0x3f317217, v133
	v_fma_f32 v142, v133, s52, -v142
	v_fmac_f32_e32 v142, 0x3377d1cf, v133
	v_fmac_f32_e32 v142, 0x3f317217, v133
	v_mov_b32_e32 v133, v142
	v_cndmask_b32_e64 v142, 0, v216, s[18:19]
	v_sub_f32_e32 v133, v133, v142
	v_cndmask_b32_e64 v133, v140, v133, s[16:17]
	v_mul_f32_e32 v140, 0x3fb8aa3b, v141
	v_exp_f32_e32 v140, v140
	s_nop 0
	v_fma_f32 v129, v180, v140, v129
	v_cmp_gt_f32_e64 s[16:17], s97, v129
	s_nop 1
	v_cndmask_b32_e64 v140, 0, 32, s[16:17]
	v_ldexp_f32 v129, v129, v140
	v_log_f32_e32 v129, v129
	s_nop 0
	v_mul_f32_e32 v140, 0x3f317217, v129
	v_fma_f32 v140, v129, s52, -v140
	v_fmac_f32_e32 v140, 0x3377d1cf, v129
	v_fmac_f32_e32 v140, 0x3f317217, v129
	v_mov_b32_e32 v129, v140
	v_cndmask_b32_e64 v140, 0, v216, s[16:17]
	v_sub_f32_e32 v129, v129, v140
	v_min_f32_e32 v140, 0, v138
	v_mul_f32_e64 v138, |v138|, s57
	v_exp_f32_e32 v138, v138
	v_cndmask_b32_e64 v129, v141, v129, s[14:15]
	v_add_f32_e32 v138, 1.0, v138
	v_log_f32_e32 v138, v138
	s_nop 0
	v_mul_f32_e32 v141, 0x3f317217, v138
	v_fma_f32 v141, v138, s52, -v141
	v_fmac_f32_e32 v141, 0x3377d1cf, v138
	v_fmac_f32_e32 v141, 0x3f317217, v138
	v_mov_b32_e32 v138, v141
	v_sub_f32_e32 v138, v140, v138
	v_min_f32_e32 v140, 0, v136
	v_mul_f32_e64 v136, |v136|, s57
	v_exp_f32_e32 v136, v136
	s_nop 0
	v_add_f32_e32 v136, 1.0, v136
	v_log_f32_e32 v136, v136
	s_nop 0
	v_mul_f32_e32 v141, 0x3f317217, v136
	v_fma_f32 v141, v136, s52, -v141
	v_fmac_f32_e32 v141, 0x3377d1cf, v136
	v_fmac_f32_e32 v141, 0x3f317217, v136
	v_mov_b32_e32 v136, v141
	v_sub_f32_e32 v136, v140, v136
	v_mul_f32_e32 v140, 0x3fb8aa3b, v138
	v_exp_f32_e32 v140, v140
	s_nop 0
	v_fma_f32 v134, v179, v140, v134
	v_cmp_gt_f32_e64 s[14:15], s97, v134
	s_nop 1
	v_cndmask_b32_e64 v140, 0, 32, s[14:15]
	v_ldexp_f32 v134, v134, v140
	v_log_f32_e32 v134, v134
	s_nop 0
	v_mul_f32_e32 v140, 0x3f317217, v134
	v_fma_f32 v140, v134, s52, -v140
	v_fmac_f32_e32 v140, 0x3377d1cf, v134
	v_fmac_f32_e32 v140, 0x3f317217, v134
	v_mov_b32_e32 v134, v140
	v_cndmask_b32_e64 v140, 0, v216, s[14:15]
	v_sub_f32_e32 v134, v134, v140
	v_cndmask_b32_e64 v134, v138, v134, s[12:13]
	v_mul_f32_e32 v138, 0x3fb8aa3b, v136
	v_exp_f32_e32 v138, v138
	s_nop 0
	v_fma_f32 v130, v178, v138, v130
	v_cmp_gt_f32_e64 s[12:13], s97, v130
	s_nop 1
	v_cndmask_b32_e64 v138, 0, 32, s[12:13]
	v_ldexp_f32 v130, v130, v138
	v_log_f32_e32 v130, v130
	s_nop 0
	v_mul_f32_e32 v138, 0x3f317217, v130
	v_fma_f32 v138, v130, s52, -v138
	v_fmac_f32_e32 v138, 0x3377d1cf, v130
	v_fmac_f32_e32 v138, 0x3f317217, v130
	v_mov_b32_e32 v130, v138
	v_cndmask_b32_e64 v138, 0, v216, s[12:13]
	v_sub_f32_e32 v130, v130, v138
	v_mul_f32_e64 v138, |v139|, s57
	v_exp_f32_e32 v138, v138
	v_cndmask_b32_e64 v130, v136, v130, s[10:11]
	v_min_f32_e32 v136, 0, v139
	v_add_f32_e32 v138, 1.0, v138
	v_log_f32_e32 v138, v138
	s_nop 0
	v_mul_f32_e32 v139, 0x3f317217, v138
	v_fma_f32 v139, v138, s52, -v139
	v_fmac_f32_e32 v139, 0x3377d1cf, v138
	v_fmac_f32_e32 v139, 0x3f317217, v138
	v_mov_b32_e32 v138, v139
	v_sub_f32_e32 v136, v136, v138
	v_min_f32_e32 v138, 0, v137
	v_mul_f32_e64 v137, |v137|, s57
	v_exp_f32_e32 v137, v137
	s_nop 0
	v_add_f32_e32 v137, 1.0, v137
	v_log_f32_e32 v137, v137
	s_nop 0
	v_mul_f32_e32 v139, 0x3f317217, v137
	v_fma_f32 v139, v137, s52, -v139
	v_fmac_f32_e32 v139, 0x3377d1cf, v137
	v_fmac_f32_e32 v139, 0x3f317217, v137
	v_mov_b32_e32 v137, v139
	v_sub_f32_e32 v137, v138, v137
	v_mul_f32_e32 v138, 0x3fb8aa3b, v136
	v_exp_f32_e32 v138, v138
	s_nop 0
	v_fmac_f32_e32 v135, v177, v138
	v_cmp_gt_f32_e64 s[10:11], s97, v135
	s_nop 1
	v_cndmask_b32_e64 v138, 0, 32, s[10:11]
	v_ldexp_f32 v135, v135, v138
	v_log_f32_e32 v135, v135
	s_nop 0
	v_mul_f32_e32 v138, 0x3f317217, v135
	v_fma_f32 v138, v135, s52, -v138
	v_fmac_f32_e32 v138, 0x3377d1cf, v135
	v_fmac_f32_e32 v138, 0x3f317217, v135
	v_cmp_lt_f32_e64 s[12:13], |v135|, s53
	s_nop 1
	v_cndmask_b32_e64 v135, v135, v138, s[12:13]
	v_cndmask_b32_e64 v138, 0, v216, s[10:11]
	v_sub_f32_e32 v135, v135, v138
	v_cndmask_b32_e64 v135, v136, v135, s[8:9]
	v_mul_f32_e32 v136, 0x3fb8aa3b, v137
	v_exp_f32_e32 v136, v136
	s_nop 0
	v_fmac_f32_e32 v131, v167, v136
	v_cmp_gt_f32_e64 s[8:9], s97, v131
	s_nop 1
	v_cndmask_b32_e64 v136, 0, 32, s[8:9]
	v_ldexp_f32 v131, v131, v136
	v_log_f32_e32 v131, v131
	s_nop 0
	v_mul_f32_e32 v136, 0x3f317217, v131
	v_fma_f32 v136, v131, s52, -v136
	v_fmac_f32_e32 v136, 0x3377d1cf, v131
	v_fmac_f32_e32 v136, 0x3f317217, v131
	v_cmp_lt_f32_e64 s[10:11], |v131|, s53
	s_nop 1
	v_cndmask_b32_e64 v131, v131, v136, s[10:11]
	v_cndmask_b32_e64 v136, 0, v216, s[8:9]
	v_sub_f32_e32 v131, v131, v136
	v_cndmask_b32_e32 v131, v137, v131, vcc
	global_store_dwordx4 v[146:147], v[132:135], off offset:512
	global_store_dwordx4 v[146:147], v[128:131], off offset:528
